# stack: count loop + attn bfe nops + writelane mask build + indexer tile steps MFMA interleaved with previous tile epilogue
# baseline (speedup 1.0000x reference)
.LBB0_1141:
	ds_read_b128 v[0:3], v131 offset:0
	ds_read_b128 v[4:7], v131 offset:32
	ds_read_b128 v[10:13], v131 offset:64
	ds_read_b128 v[80:83], v131 offset:0x60
	s_cmp_lt_u32 s95, 2
	s_waitcnt lgkmcnt(0)
	ds_read_b128 v[108:111], v131 offset:0x1200
	ds_read_b128 v[104:107], v131 offset:0x1220
	ds_read_b128 v[100:103], v131 offset:0x1240
	ds_read_b128 v[96:99], v131 offset:0x1260
	s_cselect_b64 s[48:49], -1, 0
	v_mfma_f32_32x32x16_bf16 v[16:31], v[32:35], v[0:3], 0
	s_cmp_gt_u32 s95, 1
	v_mov_b32_e32 v0, 0
	v_mov_b32_e32 v1, 0
	v_mov_b32_e32 v2, 0
	v_mov_b32_e32 v3, 0
	v_mov_b32_e32 v8, 0
	v_mov_b32_e32 v9, 0
	v_mfma_f32_32x32x16_bf16 v[16:31], v[36:39], v[4:7], v[16:31]
	v_mov_b32_e32 v4, 0
	v_mov_b32_e32 v5, 0
	v_mov_b32_e32 v6, 0
	v_mov_b32_e32 v7, 0
	s_cselect_b64 s[50:51], -1, 0
	s_and_b64 vcc, exec, s[48:49]
	v_mov_b32_e32 v14, 0
	v_mfma_f32_32x32x16_bf16 v[16:31], v[40:43], v[10:13], v[16:31]
	v_mov_b32_e32 v10, 0
	v_mov_b32_e32 v11, 0
	v_mov_b32_e32 v12, 0
	v_mov_b32_e32 v13, 0
	v_mov_b32_e32 v15, 0
	v_mfma_f32_32x32x16_bf16 v[16:31], v[44:47], v[80:83], v[16:31]
	s_waitcnt lgkmcnt(0)
	ds_read_b128 v[92:95], v131 offset:0x2400
	ds_read_b128 v[88:91], v131 offset:0x2420
	ds_read_b128 v[84:87], v131 offset:0x2440
	ds_read_b128 v[80:83], v131 offset:0x2460
	s_cbranch_vccnz .LBB0_1143
	v_mfma_f32_32x32x16_bf16 v[0:15], v[32:35], v[108:111], 0
	s_nop 5
	v_max_i32_e32 v109, 0, v16
	v_fma_f32 v110, v48, v109, 0
	v_max_i32_e32 v109, 0, v17
	v_fmac_f32_e32 v110, v49, v109
	v_max_i32_e32 v109, 0, v18
	v_fmac_f32_e32 v110, v50, v109
	v_max_i32_e32 v109, 0, v19
	v_fmac_f32_e32 v110, v51, v109
	v_max_i32_e32 v109, 0, v20
	v_fmac_f32_e32 v110, v52, v109
	v_mfma_f32_32x32x16_bf16 v[0:15], v[36:39], v[104:107], v[0:15]
	v_max_i32_e32 v109, 0, v21
	v_fmac_f32_e32 v110, v53, v109
	v_max_i32_e32 v109, 0, v22
	v_fmac_f32_e32 v110, v54, v109
	v_max_i32_e32 v109, 0, v23
	v_fmac_f32_e32 v110, v55, v109
	v_max_i32_e32 v109, 0, v24
	v_fmac_f32_e32 v110, v56, v109
	v_max_i32_e32 v109, 0, v25
	v_fmac_f32_e32 v110, v57, v109
	v_mfma_f32_32x32x16_bf16 v[0:15], v[40:43], v[100:103], v[0:15]
	v_max_i32_e32 v109, 0, v26
	s_ashr_i32 s58, s58, 5
	v_fmac_f32_e32 v110, v58, v109
	v_max_i32_e32 v109, 0, v27
	s_lshl_b32 s64, s95, 4
	s_and_b32 s96, s58, -2
	v_fmac_f32_e32 v110, v59, v109
	v_max_i32_e32 v109, 0, v28
	s_add_i32 s96, s96, s64
	v_fmac_f32_e32 v110, v60, v109
	v_max_i32_e32 v109, 0, v29
	v_or_b32_e32 v203, s96, v129
	v_fmac_f32_e32 v110, v61, v109
	v_mfma_f32_32x32x16_bf16 v[0:15], v[44:47], v[96:99], v[0:15]
	v_max_i32_e32 v109, 0, v30
	v_fmac_f32_e32 v110, v62, v109
	v_max_i32_e32 v109, 0, v31
	v_cmp_gt_i32_e32 vcc, v130, v203
	v_fmac_f32_e32 v110, v63, v109
	s_and_b64 vcc, s[48:49], vcc
	v_cndmask_b32_e32 v200, v110, v197, vcc
	s_branch .Lixj112

.Lixj112:
	s_waitcnt lgkmcnt(0)
	ds_read_b128 v[104:107], v131 offset:0x3600
	ds_read_b128 v[100:103], v131 offset:0x3620
	ds_read_b128 v[96:99], v131 offset:0x3640
	ds_read_b128 v[108:111], v131 offset:0x3660
	s_cmp_gt_u32 s95, 3
	s_cselect_b64 s[64:65], -1, 0
	s_cmp_lt_u32 s95, 4
	s_cbranch_scc1 .LBB0_1145
	v_mfma_f32_32x32x16_bf16 v[16:31], v[32:35], v[92:95], 0
	s_lshr_b32 s58, s95, 1
	v_cndmask_b32_e64 v93, 0, 1, s[50:51]
	s_add_i32 s58, s58, 1
	v_cmp_ne_u32_e64 s[48:49], 1, v93
	s_andn2_b64 vcc, exec, s[50:51]
	v_max_i32_e32 v93, 0, v0
	v_fma_f32 v94, v48, v93, 0
	v_max_i32_e32 v93, 0, v1
	v_fmac_f32_e32 v94, v49, v93
	v_max_i32_e32 v93, 0, v2
	v_fmac_f32_e32 v94, v50, v93
	v_max_i32_e32 v93, 0, v3
	v_fmac_f32_e32 v94, v51, v93
	v_max_i32_e32 v93, 0, v4
	v_fmac_f32_e32 v94, v52, v93
	v_mfma_f32_32x32x16_bf16 v[16:31], v[36:39], v[88:91], v[16:31]
	v_max_i32_e32 v93, 0, v5
	v_fmac_f32_e32 v94, v53, v93
	v_max_i32_e32 v93, 0, v6
	v_fmac_f32_e32 v94, v54, v93
	v_max_i32_e32 v93, 0, v7
	v_fmac_f32_e32 v94, v55, v93
	v_max_i32_e32 v93, 0, v8
	v_fmac_f32_e32 v94, v56, v93
	v_max_i32_e32 v93, 0, v9
	v_fmac_f32_e32 v94, v57, v93
	v_mfma_f32_32x32x16_bf16 v[16:31], v[40:43], v[84:87], v[16:31]
	v_max_i32_e32 v93, 0, v10
	v_fmac_f32_e32 v94, v58, v93
	v_max_i32_e32 v93, 0, v11
	v_fmac_f32_e32 v94, v59, v93
	v_max_i32_e32 v93, 0, v12
	v_fmac_f32_e32 v94, v60, v93
	v_max_i32_e32 v93, 0, v13
	v_fmac_f32_e32 v94, v61, v93
	v_mfma_f32_32x32x16_bf16 v[16:31], v[44:47], v[80:83], v[16:31]
	v_max_i32_e32 v93, 0, v14
	v_fmac_f32_e32 v94, v62, v93
	v_max_i32_e32 v93, 0, v15
	v_fmac_f32_e32 v94, v63, v93
	s_cmp_eq_u32 s58, 2
	v_or_b32_e32 v93, 32, v130
	s_cselect_b64 s[50:51], -1, 0
	v_cmp_gt_i32_e32 vcc, v93, v203
	s_and_b64 vcc, s[50:51], vcc
	s_nop 0
	v_cndmask_b32_e32 v201, v94, v197, vcc
	s_branch .LBB0_1147

.LBB0_1149:
	s_waitcnt lgkmcnt(0)
	ds_read_b128 v[112:115], v131 offset:0x4800
	ds_read_b128 v[88:91], v131 offset:0x4820
	ds_read_b128 v[80:83], v131 offset:0x4840
	ds_read_b128 v[116:119], v131 offset:0x4860
	s_cmp_gt_u32 s95, 5
	s_cselect_b64 s[66:67], -1, 0
	s_cmp_lt_u32 s95, 6
	s_cbranch_scc1 .LBB0_1151
	v_mfma_f32_32x32x16_bf16 v[0:15], v[32:35], v[104:107], 0
	v_cndmask_b32_e64 v105, 0, 1, s[64:65]
	v_cmp_ne_u32_e64 s[50:51], 1, v105
	s_andn2_b64 vcc, exec, s[64:65]
	v_max_i32_e32 v105, 0, v16
	v_fma_f32 v106, v48, v105, 0
	v_max_i32_e32 v105, 0, v17
	v_fmac_f32_e32 v106, v49, v105
	v_max_i32_e32 v105, 0, v18
	v_fmac_f32_e32 v106, v50, v105
	v_max_i32_e32 v105, 0, v19
	v_fmac_f32_e32 v106, v51, v105
	v_max_i32_e32 v105, 0, v20
	v_fmac_f32_e32 v106, v52, v105
	v_mfma_f32_32x32x16_bf16 v[0:15], v[36:39], v[100:103], v[0:15]
	v_max_i32_e32 v105, 0, v21
	v_fmac_f32_e32 v106, v53, v105
	v_max_i32_e32 v105, 0, v22
	v_fmac_f32_e32 v106, v54, v105
	v_max_i32_e32 v105, 0, v23
	v_fmac_f32_e32 v106, v55, v105
	v_max_i32_e32 v105, 0, v24
	v_fmac_f32_e32 v106, v56, v105
	v_max_i32_e32 v105, 0, v25
	v_fmac_f32_e32 v106, v57, v105
	v_mfma_f32_32x32x16_bf16 v[0:15], v[40:43], v[96:99], v[0:15]
	v_max_i32_e32 v105, 0, v26
	v_fmac_f32_e32 v106, v58, v105
	v_max_i32_e32 v105, 0, v27
	v_fmac_f32_e32 v106, v59, v105
	v_max_i32_e32 v105, 0, v28
	v_fmac_f32_e32 v106, v60, v105
	v_max_i32_e32 v105, 0, v29
	v_fmac_f32_e32 v106, v61, v105
	v_mfma_f32_32x32x16_bf16 v[0:15], v[44:47], v[108:111], v[0:15]
	v_max_i32_e32 v105, 0, v30
	v_fmac_f32_e32 v106, v62, v105
	v_max_i32_e32 v105, 0, v31
	v_fmac_f32_e32 v106, v63, v105
	s_cmp_eq_u32 s58, 3
	v_or_b32_e32 v105, 64, v130
	s_cselect_b64 s[64:65], -1, 0
	v_cmp_gt_i32_e32 vcc, v105, v203
	s_and_b64 vcc, s[64:65], vcc
	s_nop 0
	v_cndmask_b32_e32 v202, v106, v197, vcc
	s_branch .LBB0_1153

.LBB0_1155:
	s_waitcnt lgkmcnt(0)
	ds_read_b128 v[96:99], v131 offset:0x5a00
	ds_read_b128 v[92:95], v131 offset:0x5a20
	ds_read_b128 v[84:87], v131 offset:0x5a40
	ds_read_b128 v[104:107], v131 offset:0x5a60
	s_cmp_gt_u32 s95, 7
	s_cselect_b64 s[64:65], -1, 0
	s_cmp_lt_u32 s95, 8
	s_cbranch_scc1 .LBB0_1157
	v_mfma_f32_32x32x16_bf16 v[16:31], v[32:35], v[112:115], 0
	v_cndmask_b32_e64 v113, 0, 1, s[66:67]
	v_cmp_ne_u32_e64 s[50:51], 1, v113
	s_andn2_b64 vcc, exec, s[66:67]
	v_max_i32_e32 v113, 0, v0
	v_fma_f32 v114, v48, v113, 0
	v_max_i32_e32 v113, 0, v1
	v_fmac_f32_e32 v114, v49, v113
	v_max_i32_e32 v113, 0, v2
	v_fmac_f32_e32 v114, v50, v113
	v_max_i32_e32 v113, 0, v3
	v_fmac_f32_e32 v114, v51, v113
	v_max_i32_e32 v113, 0, v4
	v_fmac_f32_e32 v114, v52, v113
	v_mfma_f32_32x32x16_bf16 v[16:31], v[36:39], v[88:91], v[16:31]
	v_max_i32_e32 v113, 0, v5
	v_fmac_f32_e32 v114, v53, v113
	v_max_i32_e32 v113, 0, v6
	v_fmac_f32_e32 v114, v54, v113
	v_max_i32_e32 v113, 0, v7
	v_fmac_f32_e32 v114, v55, v113
	v_max_i32_e32 v113, 0, v8
	v_fmac_f32_e32 v114, v56, v113
	v_max_i32_e32 v113, 0, v9
	v_fmac_f32_e32 v114, v57, v113
	v_mfma_f32_32x32x16_bf16 v[16:31], v[40:43], v[80:83], v[16:31]
	v_max_i32_e32 v113, 0, v10
	v_fmac_f32_e32 v114, v58, v113
	v_max_i32_e32 v113, 0, v11
	v_fmac_f32_e32 v114, v59, v113
	v_max_i32_e32 v113, 0, v12
	v_fmac_f32_e32 v114, v60, v113
	v_max_i32_e32 v113, 0, v13
	v_fmac_f32_e32 v114, v61, v113
	v_mfma_f32_32x32x16_bf16 v[16:31], v[44:47], v[116:119], v[16:31]
	v_max_i32_e32 v113, 0, v14
	v_fmac_f32_e32 v114, v62, v113
	v_max_i32_e32 v113, 0, v15
	v_fmac_f32_e32 v114, v63, v113
	s_cmp_eq_u32 s58, 4
	v_or_b32_e32 v113, 0x60, v130
	s_cselect_b64 s[66:67], -1, 0
	v_cmp_gt_i32_e32 vcc, v113, v203
	s_and_b64 vcc, s[66:67], vcc
	s_nop 0
	v_cndmask_b32_e32 v112, v114, v197, vcc
	s_branch .LBB0_1159

.LBB0_1161:
	s_waitcnt lgkmcnt(0)
	ds_read_b128 v[100:103], v131 offset:0x6c00
	ds_read_b128 v[88:91], v131 offset:0x6c20
	ds_read_b128 v[80:83], v131 offset:0x6c40
	ds_read_b128 v[108:111], v131 offset:0x6c60
	s_cmp_gt_u32 s95, 9
	s_cselect_b64 s[66:67], -1, 0
	s_cmp_lt_u32 s95, 10
	s_cbranch_scc1 .LBB0_1163
	v_mfma_f32_32x32x16_bf16 v[0:15], v[32:35], v[96:99], 0
	v_cndmask_b32_e64 v97, 0, 1, s[64:65]
	v_cmp_ne_u32_e64 s[50:51], 1, v97
	s_andn2_b64 vcc, exec, s[64:65]
	v_max_i32_e32 v97, 0, v16
	v_fma_f32 v98, v48, v97, 0
	v_max_i32_e32 v97, 0, v17
	v_fmac_f32_e32 v98, v49, v97
	v_max_i32_e32 v97, 0, v18
	v_fmac_f32_e32 v98, v50, v97
	v_max_i32_e32 v97, 0, v19
	v_fmac_f32_e32 v98, v51, v97
	v_max_i32_e32 v97, 0, v20
	v_fmac_f32_e32 v98, v52, v97
	v_mfma_f32_32x32x16_bf16 v[0:15], v[36:39], v[92:95], v[0:15]
	v_max_i32_e32 v97, 0, v21
	v_fmac_f32_e32 v98, v53, v97
	v_max_i32_e32 v97, 0, v22
	v_fmac_f32_e32 v98, v54, v97
	v_max_i32_e32 v97, 0, v23
	v_fmac_f32_e32 v98, v55, v97
	v_max_i32_e32 v97, 0, v24
	v_fmac_f32_e32 v98, v56, v97
	v_max_i32_e32 v97, 0, v25
	v_fmac_f32_e32 v98, v57, v97
	v_mfma_f32_32x32x16_bf16 v[0:15], v[40:43], v[84:87], v[0:15]
	v_max_i32_e32 v97, 0, v26
	v_fmac_f32_e32 v98, v58, v97
	v_max_i32_e32 v97, 0, v27
	v_fmac_f32_e32 v98, v59, v97
	v_max_i32_e32 v97, 0, v28
	v_fmac_f32_e32 v98, v60, v97
	v_max_i32_e32 v97, 0, v29
	v_fmac_f32_e32 v98, v61, v97
	v_mfma_f32_32x32x16_bf16 v[0:15], v[44:47], v[104:107], v[0:15]
	v_max_i32_e32 v97, 0, v30
	v_fmac_f32_e32 v98, v62, v97
	v_max_i32_e32 v97, 0, v31
	v_fmac_f32_e32 v98, v63, v97
	s_cmp_eq_u32 s58, 5
	v_or_b32_e32 v97, 0x80, v130
	s_cselect_b64 s[64:65], -1, 0
	v_cmp_gt_i32_e32 vcc, v97, v203
	s_and_b64 vcc, s[64:65], vcc
	s_nop 0
	v_cndmask_b32_e32 v113, v98, v197, vcc
	s_branch .LBB0_1165

.LBB0_1167:
	s_waitcnt lgkmcnt(0)
	ds_read_b128 v[96:99], v131 offset:0x7e00
	ds_read_b128 v[92:95], v131 offset:0x7e20
	ds_read_b128 v[84:87], v131 offset:0x7e40
	ds_read_b128 v[104:107], v131 offset:0x7e60
	s_cmp_gt_u32 s95, 11
	s_cselect_b64 s[64:65], -1, 0
	s_cmp_lt_u32 s95, 12
	s_cbranch_scc1 .LBB0_1169
	v_mfma_f32_32x32x16_bf16 v[16:31], v[32:35], v[100:103], 0
	v_cndmask_b32_e64 v101, 0, 1, s[66:67]
	v_cmp_ne_u32_e64 s[50:51], 1, v101
	s_andn2_b64 vcc, exec, s[66:67]
	v_max_i32_e32 v101, 0, v0
	v_fma_f32 v102, v48, v101, 0
	v_max_i32_e32 v101, 0, v1
	v_fmac_f32_e32 v102, v49, v101
	v_max_i32_e32 v101, 0, v2
	v_fmac_f32_e32 v102, v50, v101
	v_max_i32_e32 v101, 0, v3
	v_fmac_f32_e32 v102, v51, v101
	v_max_i32_e32 v101, 0, v4
	v_fmac_f32_e32 v102, v52, v101
	v_mfma_f32_32x32x16_bf16 v[16:31], v[36:39], v[88:91], v[16:31]
	v_max_i32_e32 v101, 0, v5
	v_fmac_f32_e32 v102, v53, v101
	v_max_i32_e32 v101, 0, v6
	v_fmac_f32_e32 v102, v54, v101
	v_max_i32_e32 v101, 0, v7
	v_fmac_f32_e32 v102, v55, v101
	v_max_i32_e32 v101, 0, v8
	v_fmac_f32_e32 v102, v56, v101
	v_max_i32_e32 v101, 0, v9
	v_fmac_f32_e32 v102, v57, v101
	v_mfma_f32_32x32x16_bf16 v[16:31], v[40:43], v[80:83], v[16:31]
	v_max_i32_e32 v101, 0, v10
	v_fmac_f32_e32 v102, v58, v101
	v_max_i32_e32 v101, 0, v11
	v_fmac_f32_e32 v102, v59, v101
	v_max_i32_e32 v101, 0, v12
	v_fmac_f32_e32 v102, v60, v101
	v_max_i32_e32 v101, 0, v13
	v_fmac_f32_e32 v102, v61, v101
	v_mfma_f32_32x32x16_bf16 v[16:31], v[44:47], v[108:111], v[16:31]
	v_max_i32_e32 v101, 0, v14
	v_fmac_f32_e32 v102, v62, v101
	v_max_i32_e32 v101, 0, v15
	v_fmac_f32_e32 v102, v63, v101
	s_cmp_eq_u32 s58, 6
	v_or_b32_e32 v101, 0xa0, v130
	s_cselect_b64 s[66:67], -1, 0
	v_cmp_gt_i32_e32 vcc, v101, v203
	s_and_b64 vcc, s[66:67], vcc
	s_nop 0
	v_cndmask_b32_e32 v114, v102, v197, vcc
	s_branch .LBB0_1171

.LBB0_1173:
	s_waitcnt lgkmcnt(0)
	s_cmp_lt_u32 s95, 14
	s_cbranch_scc1 .LBB0_1175
	v_mfma_f32_32x32x16_bf16 v[0:15], v[32:35], v[96:99], 0
	v_cndmask_b32_e64 v97, 0, 1, s[64:65]
	v_cmp_ne_u32_e64 s[50:51], 1, v97
	s_andn2_b64 vcc, exec, s[64:65]
	v_max_i32_e32 v97, 0, v16
	v_fma_f32 v98, v48, v97, 0
	v_max_i32_e32 v97, 0, v17
	v_fmac_f32_e32 v98, v49, v97
	v_max_i32_e32 v97, 0, v18
	v_fmac_f32_e32 v98, v50, v97
	v_max_i32_e32 v97, 0, v19
	v_fmac_f32_e32 v98, v51, v97
	v_max_i32_e32 v97, 0, v20
	v_fmac_f32_e32 v98, v52, v97
	v_mfma_f32_32x32x16_bf16 v[0:15], v[36:39], v[92:95], v[0:15]
	v_max_i32_e32 v97, 0, v21
	v_fmac_f32_e32 v98, v53, v97
	v_max_i32_e32 v97, 0, v22
	v_fmac_f32_e32 v98, v54, v97
	v_max_i32_e32 v97, 0, v23
	v_fmac_f32_e32 v98, v55, v97
	v_max_i32_e32 v97, 0, v24
	v_fmac_f32_e32 v98, v56, v97
	v_max_i32_e32 v97, 0, v25
	v_fmac_f32_e32 v98, v57, v97
	v_mfma_f32_32x32x16_bf16 v[0:15], v[40:43], v[84:87], v[0:15]
	v_max_i32_e32 v97, 0, v26
	v_fmac_f32_e32 v98, v58, v97
	v_max_i32_e32 v97, 0, v27
	v_fmac_f32_e32 v98, v59, v97
	v_max_i32_e32 v97, 0, v28
	v_fmac_f32_e32 v98, v60, v97
	v_max_i32_e32 v97, 0, v29
	v_fmac_f32_e32 v98, v61, v97
	v_mfma_f32_32x32x16_bf16 v[0:15], v[44:47], v[104:107], v[0:15]
	v_max_i32_e32 v97, 0, v30
	s_cmp_eq_u32 s58, 7
	v_fmac_f32_e32 v98, v62, v97
	v_max_i32_e32 v97, 0, v31
	s_cselect_b64 s[64:65], -1, 0
	v_cmp_gt_i32_e32 vcc, v132, v203
	v_fmac_f32_e32 v98, v63, v97
	s_and_b64 vcc, s[64:65], vcc
	v_cndmask_b32_e32 v115, v98, v197, vcc
	s_branch .LBB0_1177

.LBB0_1188:
	ds_read_b128 v[16:19], v134 offset:0
	ds_read_b128 v[80:83], v134 offset:32
	ds_read_b128 v[84:87], v134 offset:64
	ds_read_b128 v[92:95], v134 offset:0x60
	v_max_i32_e32 v88, 0, v0
	s_waitcnt lgkmcnt(0)
	v_max_i32_e32 v89, 0, v1
	v_mfma_f32_32x32x16_bf16 v[16:31], v[32:35], v[16:19], 0
	v_fma_f32 v116, v48, v88, 0
	v_max_i32_e32 v90, 0, v2
	v_fmac_f32_e32 v116, v49, v89
	v_max_i32_e32 v91, 0, v3
	v_fmac_f32_e32 v116, v50, v90
	v_max_i32_e32 v96, 0, v4
	v_fmac_f32_e32 v116, v51, v91
	v_mfma_f32_32x32x16_bf16 v[16:31], v[36:39], v[80:83], v[16:31]
	v_max_i32_e32 v97, 0, v5
	v_fmac_f32_e32 v116, v52, v96
	v_max_i32_e32 v98, 0, v6
	v_fmac_f32_e32 v116, v53, v97
	v_max_i32_e32 v99, 0, v7
	v_fmac_f32_e32 v116, v54, v98
	v_max_i32_e32 v100, 0, v8
	v_mfma_f32_32x32x16_bf16 v[16:31], v[40:43], v[84:87], v[16:31]
	v_fmac_f32_e32 v116, v55, v99
	v_max_i32_e32 v101, 0, v9
	v_fmac_f32_e32 v116, v56, v100
	v_max_i32_e32 v102, 0, v10
	v_fmac_f32_e32 v116, v57, v101
	v_max_i32_e32 v103, 0, v11
	v_fmac_f32_e32 v116, v58, v102
	v_fmac_f32_e32 v116, v59, v103
	v_max_i32_e32 v84, 0, v12
	ds_read_b128 v[80:83], v134 offset:0x1200
	v_fmac_f32_e32 v116, v60, v84
	v_max_i32_e32 v84, 0, v13
	ds_read_b128 v[88:91], v134 offset:0x1220
	v_fmac_f32_e32 v116, v61, v84
	v_max_i32_e32 v84, 0, v14
	ds_read_b128 v[96:99], v134 offset:0x1240
	v_fmac_f32_e32 v116, v62, v84
	v_max_i32_e32 v84, 0, v15
	ds_read_b128 v[104:107], v134 offset:0x1260
	v_mfma_f32_32x32x16_bf16 v[16:31], v[44:47], v[92:95], v[16:31]
	v_fmac_f32_e32 v116, v63, v84
	s_waitcnt lgkmcnt(0)
	ds_read_b128 v[108:111], v134 offset:0x2400
	ds_read_b128 v[100:103], v134 offset:0x2420
	ds_read_b128 v[92:95], v134 offset:0x2440
	ds_read_b128 v[84:87], v134 offset:0x2460
	s_cmp_eq_u32 s58, 9
	s_cselect_b64 s[52:53], -1, 0
	s_cmp_lg_u32 s58, 9
	s_cselect_b64 s[66:67], -1, 0
	s_and_b64 vcc, exec, s[52:53]
	s_cbranch_vccnz .LBB0_1190
	v_mfma_f32_32x32x16_bf16 v[0:15], v[32:35], v[80:83], 0
	v_max_i32_e32 v81, 0, v16
	v_fma_f32 v82, v48, v81, 0
	v_max_i32_e32 v81, 0, v17
	v_fmac_f32_e32 v82, v49, v81
	v_max_i32_e32 v81, 0, v18
	v_fmac_f32_e32 v82, v50, v81
	v_max_i32_e32 v81, 0, v19
	v_fmac_f32_e32 v82, v51, v81
	v_max_i32_e32 v81, 0, v20
	v_fmac_f32_e32 v82, v52, v81
	v_mfma_f32_32x32x16_bf16 v[0:15], v[36:39], v[88:91], v[0:15]
	v_max_i32_e32 v81, 0, v21
	v_fmac_f32_e32 v82, v53, v81
	v_max_i32_e32 v81, 0, v22
	v_fmac_f32_e32 v82, v54, v81
	v_max_i32_e32 v81, 0, v23
	v_fmac_f32_e32 v82, v55, v81
	v_max_i32_e32 v81, 0, v24
	v_fmac_f32_e32 v82, v56, v81
	v_max_i32_e32 v81, 0, v25
	v_fmac_f32_e32 v82, v57, v81
	v_mfma_f32_32x32x16_bf16 v[0:15], v[40:43], v[96:99], v[0:15]
	v_max_i32_e32 v81, 0, v26
	v_fmac_f32_e32 v82, v58, v81
	v_max_i32_e32 v81, 0, v27
	v_fmac_f32_e32 v82, v59, v81
	v_max_i32_e32 v81, 0, v28
	v_fmac_f32_e32 v82, v60, v81
	v_max_i32_e32 v81, 0, v29
	v_fmac_f32_e32 v82, v61, v81
	v_mfma_f32_32x32x16_bf16 v[0:15], v[44:47], v[104:107], v[0:15]
	v_max_i32_e32 v81, 0, v30
	v_fmac_f32_e32 v82, v62, v81
	v_max_i32_e32 v81, 0, v31
	v_cmp_gt_i32_e32 vcc, v135, v203
	v_fmac_f32_e32 v82, v63, v81
	s_and_b64 vcc, s[52:53], vcc
	v_cndmask_b32_e32 v117, v82, v197, vcc
	s_branch .Lixj105

.Lixj105:
	s_waitcnt lgkmcnt(0)
	ds_read_b128 v[96:99], v134 offset:0x3600
	ds_read_b128 v[88:91], v134 offset:0x3620
	ds_read_b128 v[80:83], v134 offset:0x3640
	ds_read_b128 v[104:107], v134 offset:0x3660
	s_cmp_gt_u32 s95, 19
	s_cselect_b64 s[64:65], -1, 0
	s_cmp_lt_u32 s95, 20
	s_cbranch_scc1 .LBB0_1192
	v_mfma_f32_32x32x16_bf16 v[16:31], v[32:35], v[108:111], 0
	v_cndmask_b32_e64 v109, 0, 1, s[66:67]
	v_cmp_ne_u32_e64 s[52:53], 1, v109
	s_andn2_b64 vcc, exec, s[66:67]
	v_max_i32_e32 v109, 0, v0
	v_fma_f32 v110, v48, v109, 0
	v_max_i32_e32 v109, 0, v1
	v_fmac_f32_e32 v110, v49, v109
	v_max_i32_e32 v109, 0, v2
	v_fmac_f32_e32 v110, v50, v109
	v_max_i32_e32 v109, 0, v3
	v_fmac_f32_e32 v110, v51, v109
	v_max_i32_e32 v109, 0, v4
	v_fmac_f32_e32 v110, v52, v109
	v_mfma_f32_32x32x16_bf16 v[16:31], v[36:39], v[100:103], v[16:31]
	v_max_i32_e32 v109, 0, v5
	v_fmac_f32_e32 v110, v53, v109
	v_max_i32_e32 v109, 0, v6
	v_fmac_f32_e32 v110, v54, v109
	v_max_i32_e32 v109, 0, v7
	v_fmac_f32_e32 v110, v55, v109
	v_max_i32_e32 v109, 0, v8
	v_fmac_f32_e32 v110, v56, v109
	v_max_i32_e32 v109, 0, v9
	v_fmac_f32_e32 v110, v57, v109
	v_mfma_f32_32x32x16_bf16 v[16:31], v[40:43], v[92:95], v[16:31]
	v_max_i32_e32 v109, 0, v10
	v_fmac_f32_e32 v110, v58, v109
	v_max_i32_e32 v109, 0, v11
	v_fmac_f32_e32 v110, v59, v109
	v_max_i32_e32 v109, 0, v12
	v_fmac_f32_e32 v110, v60, v109
	v_max_i32_e32 v109, 0, v13
	v_fmac_f32_e32 v110, v61, v109
	v_mfma_f32_32x32x16_bf16 v[16:31], v[44:47], v[84:87], v[16:31]
	v_max_i32_e32 v109, 0, v14
	s_cmp_eq_u32 s58, 10
	v_fmac_f32_e32 v110, v62, v109
	v_max_i32_e32 v109, 0, v15
	s_cselect_b64 s[66:67], -1, 0
	v_cmp_gt_i32_e32 vcc, v136, v203
	v_fmac_f32_e32 v110, v63, v109
	s_and_b64 vcc, s[66:67], vcc
	v_cndmask_b32_e32 v118, v110, v197, vcc
	s_branch .LBB0_1194

.LBB0_1196:
	s_waitcnt lgkmcnt(0)
	ds_read_b128 v[100:103], v134 offset:0x4800
	ds_read_b128 v[92:95], v134 offset:0x4820
	ds_read_b128 v[84:87], v134 offset:0x4840
	ds_read_b128 v[108:111], v134 offset:0x4860
	s_cmp_gt_u32 s95, 21
	s_cselect_b64 s[66:67], -1, 0
	s_cmp_lt_u32 s95, 22
	s_cbranch_scc1 .LBB0_1198
	v_mfma_f32_32x32x16_bf16 v[0:15], v[32:35], v[96:99], 0
	v_cndmask_b32_e64 v97, 0, 1, s[64:65]
	v_cmp_ne_u32_e64 s[52:53], 1, v97
	s_andn2_b64 vcc, exec, s[64:65]
	v_max_i32_e32 v97, 0, v16
	v_fma_f32 v98, v48, v97, 0
	v_max_i32_e32 v97, 0, v17
	v_fmac_f32_e32 v98, v49, v97
	v_max_i32_e32 v97, 0, v18
	v_fmac_f32_e32 v98, v50, v97
	v_max_i32_e32 v97, 0, v19
	v_fmac_f32_e32 v98, v51, v97
	v_max_i32_e32 v97, 0, v20
	v_fmac_f32_e32 v98, v52, v97
	v_mfma_f32_32x32x16_bf16 v[0:15], v[36:39], v[88:91], v[0:15]
	v_max_i32_e32 v97, 0, v21
	v_fmac_f32_e32 v98, v53, v97
	v_max_i32_e32 v97, 0, v22
	v_fmac_f32_e32 v98, v54, v97
	v_max_i32_e32 v97, 0, v23
	v_fmac_f32_e32 v98, v55, v97
	v_max_i32_e32 v97, 0, v24
	v_fmac_f32_e32 v98, v56, v97
	v_max_i32_e32 v97, 0, v25
	v_fmac_f32_e32 v98, v57, v97
	v_mfma_f32_32x32x16_bf16 v[0:15], v[40:43], v[80:83], v[0:15]
	v_max_i32_e32 v97, 0, v26
	v_fmac_f32_e32 v98, v58, v97
	v_max_i32_e32 v97, 0, v27
	v_fmac_f32_e32 v98, v59, v97
	v_max_i32_e32 v97, 0, v28
	v_fmac_f32_e32 v98, v60, v97
	v_max_i32_e32 v97, 0, v29
	v_fmac_f32_e32 v98, v61, v97
	v_mfma_f32_32x32x16_bf16 v[0:15], v[44:47], v[104:107], v[0:15]
	v_max_i32_e32 v97, 0, v30
	s_cmp_eq_u32 s58, 11
	v_fmac_f32_e32 v98, v62, v97
	v_max_i32_e32 v97, 0, v31
	s_cselect_b64 s[64:65], -1, 0
	v_cmp_gt_i32_e32 vcc, v137, v203
	v_fmac_f32_e32 v98, v63, v97
	s_and_b64 vcc, s[64:65], vcc
	v_cndmask_b32_e32 v119, v98, v197, vcc
	s_branch .LBB0_1200

.LBB0_1202:
	s_waitcnt lgkmcnt(0)
	ds_read_b128 v[96:99], v134 offset:0x5a00
	ds_read_b128 v[88:91], v134 offset:0x5a20
	ds_read_b128 v[80:83], v134 offset:0x5a40
	ds_read_b128 v[104:107], v134 offset:0x5a60
	s_cmp_gt_u32 s95, 23
	s_cselect_b64 s[64:65], -1, 0
	s_cmp_lt_u32 s95, 24
	s_cbranch_scc1 .LBB0_1204
	v_mfma_f32_32x32x16_bf16 v[16:31], v[32:35], v[100:103], 0
	v_cndmask_b32_e64 v101, 0, 1, s[66:67]
	v_cmp_ne_u32_e64 s[52:53], 1, v101
	s_andn2_b64 vcc, exec, s[66:67]
	v_max_i32_e32 v101, 0, v0
	v_fma_f32 v102, v48, v101, 0
	v_max_i32_e32 v101, 0, v1
	v_fmac_f32_e32 v102, v49, v101
	v_max_i32_e32 v101, 0, v2
	v_fmac_f32_e32 v102, v50, v101
	v_max_i32_e32 v101, 0, v3
	v_fmac_f32_e32 v102, v51, v101
	v_max_i32_e32 v101, 0, v4
	v_fmac_f32_e32 v102, v52, v101
	v_mfma_f32_32x32x16_bf16 v[16:31], v[36:39], v[92:95], v[16:31]
	v_max_i32_e32 v101, 0, v5
	v_fmac_f32_e32 v102, v53, v101
	v_max_i32_e32 v101, 0, v6
	v_fmac_f32_e32 v102, v54, v101
	v_max_i32_e32 v101, 0, v7
	v_fmac_f32_e32 v102, v55, v101
	v_max_i32_e32 v101, 0, v8
	v_fmac_f32_e32 v102, v56, v101
	v_max_i32_e32 v101, 0, v9
	v_fmac_f32_e32 v102, v57, v101
	v_mfma_f32_32x32x16_bf16 v[16:31], v[40:43], v[84:87], v[16:31]
	v_max_i32_e32 v101, 0, v10
	v_fmac_f32_e32 v102, v58, v101
	v_max_i32_e32 v101, 0, v11
	v_fmac_f32_e32 v102, v59, v101
	v_max_i32_e32 v101, 0, v12
	v_fmac_f32_e32 v102, v60, v101
	v_max_i32_e32 v101, 0, v13
	v_fmac_f32_e32 v102, v61, v101
	v_mfma_f32_32x32x16_bf16 v[16:31], v[44:47], v[108:111], v[16:31]
	v_max_i32_e32 v101, 0, v14
	s_cmp_eq_u32 s58, 12
	v_fmac_f32_e32 v102, v62, v101
	v_max_i32_e32 v101, 0, v15
	s_cselect_b64 s[66:67], -1, 0
	v_cmp_gt_i32_e32 vcc, v138, v203
	v_fmac_f32_e32 v102, v63, v101
	s_and_b64 vcc, s[66:67], vcc
	v_cndmask_b32_e32 v205, v102, v197, vcc
	s_branch .LBB0_1206

.LBB0_1208:
	s_waitcnt lgkmcnt(0)
	ds_read_b128 v[100:103], v134 offset:0x6c00
	ds_read_b128 v[92:95], v134 offset:0x6c20
	ds_read_b128 v[84:87], v134 offset:0x6c40
	ds_read_b128 v[108:111], v134 offset:0x6c60
	s_cmp_gt_u32 s95, 25
	s_cselect_b64 s[66:67], -1, 0
	s_cmp_lt_u32 s95, 26
	s_cbranch_scc1 .LBB0_1210
	v_mfma_f32_32x32x16_bf16 v[0:15], v[32:35], v[96:99], 0
	v_cndmask_b32_e64 v97, 0, 1, s[64:65]
	v_cmp_ne_u32_e64 s[52:53], 1, v97
	s_andn2_b64 vcc, exec, s[64:65]
	v_max_i32_e32 v97, 0, v16
	v_fma_f32 v98, v48, v97, 0
	v_max_i32_e32 v97, 0, v17
	v_fmac_f32_e32 v98, v49, v97
	v_max_i32_e32 v97, 0, v18
	v_fmac_f32_e32 v98, v50, v97
	v_max_i32_e32 v97, 0, v19
	v_fmac_f32_e32 v98, v51, v97
	v_max_i32_e32 v97, 0, v20
	v_fmac_f32_e32 v98, v52, v97
	v_mfma_f32_32x32x16_bf16 v[0:15], v[36:39], v[88:91], v[0:15]
	v_max_i32_e32 v97, 0, v21
	v_fmac_f32_e32 v98, v53, v97
	v_max_i32_e32 v97, 0, v22
	v_fmac_f32_e32 v98, v54, v97
	v_max_i32_e32 v97, 0, v23
	v_fmac_f32_e32 v98, v55, v97
	v_max_i32_e32 v97, 0, v24
	v_fmac_f32_e32 v98, v56, v97
	v_max_i32_e32 v97, 0, v25
	v_fmac_f32_e32 v98, v57, v97
	v_mfma_f32_32x32x16_bf16 v[0:15], v[40:43], v[80:83], v[0:15]
	v_max_i32_e32 v97, 0, v26
	v_fmac_f32_e32 v98, v58, v97
	v_max_i32_e32 v97, 0, v27
	v_fmac_f32_e32 v98, v59, v97
	v_max_i32_e32 v97, 0, v28
	v_fmac_f32_e32 v98, v60, v97
	v_max_i32_e32 v97, 0, v29
	v_fmac_f32_e32 v98, v61, v97
	v_mfma_f32_32x32x16_bf16 v[0:15], v[44:47], v[104:107], v[0:15]
	v_max_i32_e32 v97, 0, v30
	s_cmp_eq_u32 s58, 13
	v_fmac_f32_e32 v98, v62, v97
	v_max_i32_e32 v97, 0, v31
	s_cselect_b64 s[64:65], -1, 0
	v_cmp_gt_i32_e32 vcc, v139, v203
	v_fmac_f32_e32 v98, v63, v97
	s_and_b64 vcc, s[64:65], vcc
	v_cndmask_b32_e32 v206, v98, v197, vcc
	s_branch .LBB0_1212

.LBB0_1214:
	s_waitcnt lgkmcnt(0)
	ds_read_b128 v[96:99], v134 offset:0x7e00
	ds_read_b128 v[88:91], v134 offset:0x7e20
	ds_read_b128 v[80:83], v134 offset:0x7e40
	ds_read_b128 v[104:107], v134 offset:0x7e60
	s_cmp_gt_u32 s95, 27
	s_cselect_b64 s[64:65], -1, 0
	s_cmp_lt_u32 s95, 28
	s_cbranch_scc1 .LBB0_1216
	v_mfma_f32_32x32x16_bf16 v[16:31], v[32:35], v[100:103], 0
	v_cndmask_b32_e64 v101, 0, 1, s[66:67]
	v_cmp_ne_u32_e64 s[52:53], 1, v101
	s_andn2_b64 vcc, exec, s[66:67]
	v_max_i32_e32 v101, 0, v0
	v_fma_f32 v102, v48, v101, 0
	v_max_i32_e32 v101, 0, v1
	v_fmac_f32_e32 v102, v49, v101
	v_max_i32_e32 v101, 0, v2
	v_fmac_f32_e32 v102, v50, v101
	v_max_i32_e32 v101, 0, v3
	v_fmac_f32_e32 v102, v51, v101
	v_max_i32_e32 v101, 0, v4
	v_fmac_f32_e32 v102, v52, v101
	v_mfma_f32_32x32x16_bf16 v[16:31], v[36:39], v[92:95], v[16:31]
	v_max_i32_e32 v101, 0, v5
	v_fmac_f32_e32 v102, v53, v101
	v_max_i32_e32 v101, 0, v6
	v_fmac_f32_e32 v102, v54, v101
	v_max_i32_e32 v101, 0, v7
	v_fmac_f32_e32 v102, v55, v101
	v_max_i32_e32 v101, 0, v8
	v_fmac_f32_e32 v102, v56, v101
	v_max_i32_e32 v101, 0, v9
	v_fmac_f32_e32 v102, v57, v101
	v_mfma_f32_32x32x16_bf16 v[16:31], v[40:43], v[84:87], v[16:31]
	v_max_i32_e32 v101, 0, v10
	v_fmac_f32_e32 v102, v58, v101
	v_max_i32_e32 v101, 0, v11
	v_fmac_f32_e32 v102, v59, v101
	v_max_i32_e32 v101, 0, v12
	v_fmac_f32_e32 v102, v60, v101
	v_max_i32_e32 v101, 0, v13
	v_fmac_f32_e32 v102, v61, v101
	v_mfma_f32_32x32x16_bf16 v[16:31], v[44:47], v[108:111], v[16:31]
	v_max_i32_e32 v101, 0, v14
	s_cmp_eq_u32 s58, 14
	v_fmac_f32_e32 v102, v62, v101
	v_max_i32_e32 v101, 0, v15
	s_cselect_b64 s[66:67], -1, 0
	v_cmp_gt_i32_e32 vcc, v140, v203
	v_fmac_f32_e32 v102, v63, v101
	s_and_b64 vcc, s[66:67], vcc
	v_cndmask_b32_e32 v207, v102, v197, vcc
	s_branch .LBB0_1218

.LBB0_1220:
	s_waitcnt lgkmcnt(0)
	s_cmp_lt_u32 s95, 30
	s_cbranch_scc1 .LBB0_1222
	v_mfma_f32_32x32x16_bf16 v[0:15], v[32:35], v[96:99], 0
	v_cndmask_b32_e64 v97, 0, 1, s[64:65]
	v_cmp_ne_u32_e64 s[52:53], 1, v97
	s_andn2_b64 vcc, exec, s[64:65]
	v_max_i32_e32 v97, 0, v16
	v_fma_f32 v98, v48, v97, 0
	v_max_i32_e32 v97, 0, v17
	v_fmac_f32_e32 v98, v49, v97
	v_max_i32_e32 v97, 0, v18
	v_fmac_f32_e32 v98, v50, v97
	v_max_i32_e32 v97, 0, v19
	v_fmac_f32_e32 v98, v51, v97
	v_max_i32_e32 v97, 0, v20
	v_fmac_f32_e32 v98, v52, v97
	v_mfma_f32_32x32x16_bf16 v[0:15], v[36:39], v[88:91], v[0:15]
	v_max_i32_e32 v97, 0, v21
	v_fmac_f32_e32 v98, v53, v97
	v_max_i32_e32 v97, 0, v22
	v_fmac_f32_e32 v98, v54, v97
	v_max_i32_e32 v97, 0, v23
	v_fmac_f32_e32 v98, v55, v97
	v_max_i32_e32 v97, 0, v24
	v_fmac_f32_e32 v98, v56, v97
	v_max_i32_e32 v97, 0, v25
	v_fmac_f32_e32 v98, v57, v97
	v_mfma_f32_32x32x16_bf16 v[0:15], v[40:43], v[80:83], v[0:15]
	v_max_i32_e32 v97, 0, v26
	v_fmac_f32_e32 v98, v58, v97
	v_max_i32_e32 v97, 0, v27
	v_fmac_f32_e32 v98, v59, v97
	v_max_i32_e32 v97, 0, v28
	v_fmac_f32_e32 v98, v60, v97
	v_max_i32_e32 v97, 0, v29
	v_fmac_f32_e32 v98, v61, v97
	v_mfma_f32_32x32x16_bf16 v[0:15], v[44:47], v[104:107], v[0:15]
	v_max_i32_e32 v97, 0, v30
	s_cmp_eq_u32 s58, 15
	v_fmac_f32_e32 v98, v62, v97
	v_max_i32_e32 v97, 0, v31
	s_cselect_b64 s[64:65], -1, 0
	v_cmp_gt_i32_e32 vcc, v141, v203
	v_fmac_f32_e32 v98, v63, v97
	s_and_b64 vcc, s[64:65], vcc
	v_cndmask_b32_e32 v208, v98, v197, vcc
	s_branch .LBB0_1224

.LBB0_1232:
	ds_read_b128 v[16:19], v131 offset:0
	ds_read_b128 v[80:83], v131 offset:32
	ds_read_b128 v[84:87], v131 offset:64
	ds_read_b128 v[92:95], v131 offset:0x60
	v_max_i32_e32 v88, 0, v0
	s_waitcnt lgkmcnt(0)
	v_max_i32_e32 v89, 0, v1
	v_mfma_f32_32x32x16_bf16 v[16:31], v[32:35], v[16:19], 0
	v_fma_f32 v209, v48, v88, 0
	v_max_i32_e32 v90, 0, v2
	v_fmac_f32_e32 v209, v49, v89
	v_max_i32_e32 v91, 0, v3
	v_fmac_f32_e32 v209, v50, v90
	v_max_i32_e32 v96, 0, v4
	v_fmac_f32_e32 v209, v51, v91
	v_mfma_f32_32x32x16_bf16 v[16:31], v[36:39], v[80:83], v[16:31]
	v_max_i32_e32 v97, 0, v5
	v_fmac_f32_e32 v209, v52, v96
	v_max_i32_e32 v98, 0, v6
	v_fmac_f32_e32 v209, v53, v97
	v_max_i32_e32 v99, 0, v7
	v_fmac_f32_e32 v209, v54, v98
	v_max_i32_e32 v100, 0, v8
	v_mfma_f32_32x32x16_bf16 v[16:31], v[40:43], v[84:87], v[16:31]
	v_fmac_f32_e32 v209, v55, v99
	v_max_i32_e32 v101, 0, v9
	v_fmac_f32_e32 v209, v56, v100
	v_max_i32_e32 v102, 0, v10
	v_fmac_f32_e32 v209, v57, v101
	v_max_i32_e32 v103, 0, v11
	v_fmac_f32_e32 v209, v58, v102
	v_fmac_f32_e32 v209, v59, v103
	v_max_i32_e32 v84, 0, v12
	ds_read_b128 v[80:83], v131 offset:0x1200
	v_fmac_f32_e32 v209, v60, v84
	v_max_i32_e32 v84, 0, v13
	ds_read_b128 v[88:91], v131 offset:0x1220
	v_fmac_f32_e32 v209, v61, v84
	v_max_i32_e32 v84, 0, v14
	ds_read_b128 v[96:99], v131 offset:0x1240
	v_fmac_f32_e32 v209, v62, v84
	v_max_i32_e32 v84, 0, v15
	ds_read_b128 v[104:107], v131 offset:0x1260
	v_mfma_f32_32x32x16_bf16 v[16:31], v[44:47], v[92:95], v[16:31]
	v_fmac_f32_e32 v209, v63, v84
	s_waitcnt lgkmcnt(0)
	ds_read_b128 v[108:111], v131 offset:0x2400
	ds_read_b128 v[100:103], v131 offset:0x2420
	ds_read_b128 v[92:95], v131 offset:0x2440
	ds_read_b128 v[84:87], v131 offset:0x2460
	s_cmp_eq_u32 s58, 17
	s_cselect_b64 s[52:53], -1, 0
	s_cmp_lg_u32 s58, 17
	s_cselect_b64 s[66:67], -1, 0
	s_and_b64 vcc, exec, s[52:53]
	s_cbranch_vccnz .LBB0_1234
	v_mfma_f32_32x32x16_bf16 v[0:15], v[32:35], v[80:83], 0
	v_max_i32_e32 v81, 0, v16
	v_fma_f32 v82, v48, v81, 0
	v_max_i32_e32 v81, 0, v17
	v_fmac_f32_e32 v82, v49, v81
	v_max_i32_e32 v81, 0, v18
	v_fmac_f32_e32 v82, v50, v81
	v_max_i32_e32 v81, 0, v19
	v_fmac_f32_e32 v82, v51, v81
	v_max_i32_e32 v81, 0, v20
	v_fmac_f32_e32 v82, v52, v81
	v_mfma_f32_32x32x16_bf16 v[0:15], v[36:39], v[88:91], v[0:15]
	v_max_i32_e32 v81, 0, v21
	v_fmac_f32_e32 v82, v53, v81
	v_max_i32_e32 v81, 0, v22
	v_fmac_f32_e32 v82, v54, v81
	v_max_i32_e32 v81, 0, v23
	v_fmac_f32_e32 v82, v55, v81
	v_max_i32_e32 v81, 0, v24
	v_fmac_f32_e32 v82, v56, v81
	v_max_i32_e32 v81, 0, v25
	v_fmac_f32_e32 v82, v57, v81
	v_mfma_f32_32x32x16_bf16 v[0:15], v[40:43], v[96:99], v[0:15]
	v_max_i32_e32 v81, 0, v26
	v_fmac_f32_e32 v82, v58, v81
	v_max_i32_e32 v81, 0, v27
	v_fmac_f32_e32 v82, v59, v81
	v_max_i32_e32 v81, 0, v28
	v_fmac_f32_e32 v82, v60, v81
	v_max_i32_e32 v81, 0, v29
	v_fmac_f32_e32 v82, v61, v81
	v_mfma_f32_32x32x16_bf16 v[0:15], v[44:47], v[104:107], v[0:15]
	v_max_i32_e32 v81, 0, v30
	v_fmac_f32_e32 v82, v62, v81
	v_max_i32_e32 v81, 0, v31
	v_cmp_gt_i32_e32 vcc, v143, v203
	v_fmac_f32_e32 v82, v63, v81
	s_and_b64 vcc, s[52:53], vcc
	v_cndmask_b32_e32 v210, v82, v197, vcc
	s_branch .Lixj98

.Lixj98:
	s_waitcnt lgkmcnt(0)
	ds_read_b128 v[96:99], v131 offset:0x3600
	ds_read_b128 v[88:91], v131 offset:0x3620
	ds_read_b128 v[80:83], v131 offset:0x3640
	ds_read_b128 v[104:107], v131 offset:0x3660
	s_cmp_gt_u32 s95, 35
	s_cselect_b64 s[64:65], -1, 0
	s_cmp_lt_u32 s95, 36
	s_cbranch_scc1 .LBB0_1236
	v_mfma_f32_32x32x16_bf16 v[16:31], v[32:35], v[108:111], 0
	v_cndmask_b32_e64 v109, 0, 1, s[66:67]
	v_cmp_ne_u32_e64 s[52:53], 1, v109
	s_andn2_b64 vcc, exec, s[66:67]
	v_max_i32_e32 v109, 0, v0
	v_fma_f32 v110, v48, v109, 0
	v_max_i32_e32 v109, 0, v1
	v_fmac_f32_e32 v110, v49, v109
	v_max_i32_e32 v109, 0, v2
	v_fmac_f32_e32 v110, v50, v109
	v_max_i32_e32 v109, 0, v3
	v_fmac_f32_e32 v110, v51, v109
	v_max_i32_e32 v109, 0, v4
	v_fmac_f32_e32 v110, v52, v109
	v_mfma_f32_32x32x16_bf16 v[16:31], v[36:39], v[100:103], v[16:31]
	v_max_i32_e32 v109, 0, v5
	v_fmac_f32_e32 v110, v53, v109
	v_max_i32_e32 v109, 0, v6
	v_fmac_f32_e32 v110, v54, v109
	v_max_i32_e32 v109, 0, v7
	v_fmac_f32_e32 v110, v55, v109
	v_max_i32_e32 v109, 0, v8
	v_fmac_f32_e32 v110, v56, v109
	v_max_i32_e32 v109, 0, v9
	v_fmac_f32_e32 v110, v57, v109
	v_mfma_f32_32x32x16_bf16 v[16:31], v[40:43], v[92:95], v[16:31]
	v_max_i32_e32 v109, 0, v10
	v_fmac_f32_e32 v110, v58, v109
	v_max_i32_e32 v109, 0, v11
	v_fmac_f32_e32 v110, v59, v109
	v_max_i32_e32 v109, 0, v12
	v_fmac_f32_e32 v110, v60, v109
	v_max_i32_e32 v109, 0, v13
	v_fmac_f32_e32 v110, v61, v109
	v_mfma_f32_32x32x16_bf16 v[16:31], v[44:47], v[84:87], v[16:31]
	v_max_i32_e32 v109, 0, v14
	s_cmp_eq_u32 s58, 18
	v_fmac_f32_e32 v110, v62, v109
	v_max_i32_e32 v109, 0, v15
	s_cselect_b64 s[66:67], -1, 0
	v_cmp_gt_i32_e32 vcc, v144, v203
	v_fmac_f32_e32 v110, v63, v109
	s_and_b64 vcc, s[66:67], vcc
	v_cndmask_b32_e32 v211, v110, v197, vcc
	s_branch .LBB0_1238

.LBB0_1240:
	s_waitcnt lgkmcnt(0)
	ds_read_b128 v[100:103], v131 offset:0x4800
	ds_read_b128 v[92:95], v131 offset:0x4820
	ds_read_b128 v[84:87], v131 offset:0x4840
	ds_read_b128 v[108:111], v131 offset:0x4860
	s_cmp_gt_u32 s95, 37
	s_cselect_b64 s[66:67], -1, 0
	s_cmp_lt_u32 s95, 38
	s_cbranch_scc1 .LBB0_1242
	v_mfma_f32_32x32x16_bf16 v[0:15], v[32:35], v[96:99], 0
	v_cndmask_b32_e64 v97, 0, 1, s[64:65]
	v_cmp_ne_u32_e64 s[52:53], 1, v97
	s_andn2_b64 vcc, exec, s[64:65]
	v_max_i32_e32 v97, 0, v16
	v_fma_f32 v98, v48, v97, 0
	v_max_i32_e32 v97, 0, v17
	v_fmac_f32_e32 v98, v49, v97
	v_max_i32_e32 v97, 0, v18
	v_fmac_f32_e32 v98, v50, v97
	v_max_i32_e32 v97, 0, v19
	v_fmac_f32_e32 v98, v51, v97
	v_max_i32_e32 v97, 0, v20
	v_fmac_f32_e32 v98, v52, v97
	v_mfma_f32_32x32x16_bf16 v[0:15], v[36:39], v[88:91], v[0:15]
	v_max_i32_e32 v97, 0, v21
	v_fmac_f32_e32 v98, v53, v97
	v_max_i32_e32 v97, 0, v22
	v_fmac_f32_e32 v98, v54, v97
	v_max_i32_e32 v97, 0, v23
	v_fmac_f32_e32 v98, v55, v97
	v_max_i32_e32 v97, 0, v24
	v_fmac_f32_e32 v98, v56, v97
	v_max_i32_e32 v97, 0, v25
	v_fmac_f32_e32 v98, v57, v97
	v_mfma_f32_32x32x16_bf16 v[0:15], v[40:43], v[80:83], v[0:15]
	v_max_i32_e32 v97, 0, v26
	v_fmac_f32_e32 v98, v58, v97
	v_max_i32_e32 v97, 0, v27
	v_fmac_f32_e32 v98, v59, v97
	v_max_i32_e32 v97, 0, v28
	v_fmac_f32_e32 v98, v60, v97
	v_max_i32_e32 v97, 0, v29
	v_fmac_f32_e32 v98, v61, v97
	v_mfma_f32_32x32x16_bf16 v[0:15], v[44:47], v[104:107], v[0:15]
	v_max_i32_e32 v97, 0, v30
	s_cmp_eq_u32 s58, 19
	v_fmac_f32_e32 v98, v62, v97
	v_max_i32_e32 v97, 0, v31
	s_cselect_b64 s[64:65], -1, 0
	v_cmp_gt_i32_e32 vcc, v145, v203
	v_fmac_f32_e32 v98, v63, v97
	s_and_b64 vcc, s[64:65], vcc
	v_cndmask_b32_e32 v212, v98, v197, vcc
	s_branch .LBB0_1244

.LBB0_1246:
	s_waitcnt lgkmcnt(0)
	ds_read_b128 v[96:99], v131 offset:0x5a00
	ds_read_b128 v[88:91], v131 offset:0x5a20
	ds_read_b128 v[80:83], v131 offset:0x5a40
	ds_read_b128 v[104:107], v131 offset:0x5a60
	s_cmp_gt_u32 s95, 39
	s_cselect_b64 s[64:65], -1, 0
	s_cmp_lt_u32 s95, 40
	s_cbranch_scc1 .LBB0_1248
	v_mfma_f32_32x32x16_bf16 v[16:31], v[32:35], v[100:103], 0
	v_cndmask_b32_e64 v101, 0, 1, s[66:67]
	v_cmp_ne_u32_e64 s[52:53], 1, v101
	s_andn2_b64 vcc, exec, s[66:67]
	v_max_i32_e32 v101, 0, v0
	v_fma_f32 v102, v48, v101, 0
	v_max_i32_e32 v101, 0, v1
	v_fmac_f32_e32 v102, v49, v101
	v_max_i32_e32 v101, 0, v2
	v_fmac_f32_e32 v102, v50, v101
	v_max_i32_e32 v101, 0, v3
	v_fmac_f32_e32 v102, v51, v101
	v_max_i32_e32 v101, 0, v4
	v_fmac_f32_e32 v102, v52, v101
	v_mfma_f32_32x32x16_bf16 v[16:31], v[36:39], v[92:95], v[16:31]
	v_max_i32_e32 v101, 0, v5
	v_fmac_f32_e32 v102, v53, v101
	v_max_i32_e32 v101, 0, v6
	v_fmac_f32_e32 v102, v54, v101
	v_max_i32_e32 v101, 0, v7
	v_fmac_f32_e32 v102, v55, v101
	v_max_i32_e32 v101, 0, v8
	v_fmac_f32_e32 v102, v56, v101
	v_max_i32_e32 v101, 0, v9
	v_fmac_f32_e32 v102, v57, v101
	v_mfma_f32_32x32x16_bf16 v[16:31], v[40:43], v[84:87], v[16:31]
	v_max_i32_e32 v101, 0, v10
	v_fmac_f32_e32 v102, v58, v101
	v_max_i32_e32 v101, 0, v11
	v_fmac_f32_e32 v102, v59, v101
	v_max_i32_e32 v101, 0, v12
	v_fmac_f32_e32 v102, v60, v101
	v_max_i32_e32 v101, 0, v13
	v_fmac_f32_e32 v102, v61, v101
	v_mfma_f32_32x32x16_bf16 v[16:31], v[44:47], v[108:111], v[16:31]
	v_max_i32_e32 v101, 0, v14
	s_cmp_eq_u32 s58, 20
	v_fmac_f32_e32 v102, v62, v101
	v_max_i32_e32 v101, 0, v15
	s_cselect_b64 s[66:67], -1, 0
	v_cmp_gt_i32_e32 vcc, v146, v203
	v_fmac_f32_e32 v102, v63, v101
	s_and_b64 vcc, s[66:67], vcc
	v_cndmask_b32_e32 v213, v102, v197, vcc
	s_branch .LBB0_1250

.LBB0_1252:
	s_waitcnt lgkmcnt(0)
	ds_read_b128 v[100:103], v131 offset:0x6c00
	ds_read_b128 v[92:95], v131 offset:0x6c20
	ds_read_b128 v[84:87], v131 offset:0x6c40
	ds_read_b128 v[108:111], v131 offset:0x6c60
	s_cmp_gt_u32 s95, 41
	s_cselect_b64 s[66:67], -1, 0
	s_cmp_lt_u32 s95, 42
	s_cbranch_scc1 .LBB0_1254
	v_mfma_f32_32x32x16_bf16 v[0:15], v[32:35], v[96:99], 0
	v_cndmask_b32_e64 v97, 0, 1, s[64:65]
	v_cmp_ne_u32_e64 s[52:53], 1, v97
	s_andn2_b64 vcc, exec, s[64:65]
	v_max_i32_e32 v97, 0, v16
	v_fma_f32 v98, v48, v97, 0
	v_max_i32_e32 v97, 0, v17
	v_fmac_f32_e32 v98, v49, v97
	v_max_i32_e32 v97, 0, v18
	v_fmac_f32_e32 v98, v50, v97
	v_max_i32_e32 v97, 0, v19
	v_fmac_f32_e32 v98, v51, v97
	v_max_i32_e32 v97, 0, v20
	v_fmac_f32_e32 v98, v52, v97
	v_mfma_f32_32x32x16_bf16 v[0:15], v[36:39], v[88:91], v[0:15]
	v_max_i32_e32 v97, 0, v21
	v_fmac_f32_e32 v98, v53, v97
	v_max_i32_e32 v97, 0, v22
	v_fmac_f32_e32 v98, v54, v97
	v_max_i32_e32 v97, 0, v23
	v_fmac_f32_e32 v98, v55, v97
	v_max_i32_e32 v97, 0, v24
	v_fmac_f32_e32 v98, v56, v97
	v_max_i32_e32 v97, 0, v25
	v_fmac_f32_e32 v98, v57, v97
	v_mfma_f32_32x32x16_bf16 v[0:15], v[40:43], v[80:83], v[0:15]
	v_max_i32_e32 v97, 0, v26
	v_fmac_f32_e32 v98, v58, v97
	v_max_i32_e32 v97, 0, v27
	v_fmac_f32_e32 v98, v59, v97
	v_max_i32_e32 v97, 0, v28
	v_fmac_f32_e32 v98, v60, v97
	v_max_i32_e32 v97, 0, v29
	v_fmac_f32_e32 v98, v61, v97
	v_mfma_f32_32x32x16_bf16 v[0:15], v[44:47], v[104:107], v[0:15]
	v_max_i32_e32 v97, 0, v30
	s_cmp_eq_u32 s58, 21
	v_fmac_f32_e32 v98, v62, v97
	v_max_i32_e32 v97, 0, v31
	s_cselect_b64 s[64:65], -1, 0
	v_cmp_gt_i32_e32 vcc, v147, v203
	v_fmac_f32_e32 v98, v63, v97
	s_and_b64 vcc, s[64:65], vcc
	v_cndmask_b32_e32 v214, v98, v197, vcc
	s_branch .LBB0_1256

.LBB0_1258:
	s_waitcnt lgkmcnt(0)
	ds_read_b128 v[96:99], v131 offset:0x7e00
	ds_read_b128 v[88:91], v131 offset:0x7e20
	ds_read_b128 v[80:83], v131 offset:0x7e40
	ds_read_b128 v[104:107], v131 offset:0x7e60
	s_cmp_gt_u32 s95, 43
	s_cselect_b64 s[64:65], -1, 0
	s_cmp_lt_u32 s95, 44
	s_cbranch_scc1 .LBB0_1260
	v_mfma_f32_32x32x16_bf16 v[16:31], v[32:35], v[100:103], 0
	v_cndmask_b32_e64 v101, 0, 1, s[66:67]
	v_cmp_ne_u32_e64 s[52:53], 1, v101
	s_andn2_b64 vcc, exec, s[66:67]
	v_max_i32_e32 v101, 0, v0
	v_fma_f32 v102, v48, v101, 0
	v_max_i32_e32 v101, 0, v1
	v_fmac_f32_e32 v102, v49, v101
	v_max_i32_e32 v101, 0, v2
	v_fmac_f32_e32 v102, v50, v101
	v_max_i32_e32 v101, 0, v3
	v_fmac_f32_e32 v102, v51, v101
	v_max_i32_e32 v101, 0, v4
	v_fmac_f32_e32 v102, v52, v101
	v_mfma_f32_32x32x16_bf16 v[16:31], v[36:39], v[92:95], v[16:31]
	v_max_i32_e32 v101, 0, v5
	v_fmac_f32_e32 v102, v53, v101
	v_max_i32_e32 v101, 0, v6
	v_fmac_f32_e32 v102, v54, v101
	v_max_i32_e32 v101, 0, v7
	v_fmac_f32_e32 v102, v55, v101
	v_max_i32_e32 v101, 0, v8
	v_fmac_f32_e32 v102, v56, v101
	v_max_i32_e32 v101, 0, v9
	v_fmac_f32_e32 v102, v57, v101
	v_mfma_f32_32x32x16_bf16 v[16:31], v[40:43], v[84:87], v[16:31]
	v_max_i32_e32 v101, 0, v10
	v_fmac_f32_e32 v102, v58, v101
	v_max_i32_e32 v101, 0, v11
	v_fmac_f32_e32 v102, v59, v101
	v_max_i32_e32 v101, 0, v12
	v_fmac_f32_e32 v102, v60, v101
	v_max_i32_e32 v101, 0, v13
	v_fmac_f32_e32 v102, v61, v101
	v_mfma_f32_32x32x16_bf16 v[16:31], v[44:47], v[108:111], v[16:31]
	v_max_i32_e32 v101, 0, v14
	s_cmp_eq_u32 s58, 22
	v_fmac_f32_e32 v102, v62, v101
	v_max_i32_e32 v101, 0, v15
	s_cselect_b64 s[66:67], -1, 0
	v_cmp_gt_i32_e32 vcc, v148, v203
	v_fmac_f32_e32 v102, v63, v101
	s_and_b64 vcc, s[66:67], vcc
	v_cndmask_b32_e32 v216, v102, v197, vcc
	s_branch .LBB0_1262

.LBB0_1264:
	s_waitcnt lgkmcnt(0)
	s_cmp_lt_u32 s95, 46
	s_cbranch_scc1 .LBB0_1266
	v_mfma_f32_32x32x16_bf16 v[0:15], v[32:35], v[96:99], 0
	v_cndmask_b32_e64 v97, 0, 1, s[64:65]
	v_cmp_ne_u32_e64 s[52:53], 1, v97
	s_andn2_b64 vcc, exec, s[64:65]
	v_max_i32_e32 v97, 0, v16
	v_fma_f32 v98, v48, v97, 0
	v_max_i32_e32 v97, 0, v17
	v_fmac_f32_e32 v98, v49, v97
	v_max_i32_e32 v97, 0, v18
	v_fmac_f32_e32 v98, v50, v97
	v_max_i32_e32 v97, 0, v19
	v_fmac_f32_e32 v98, v51, v97
	v_max_i32_e32 v97, 0, v20
	v_fmac_f32_e32 v98, v52, v97
	v_mfma_f32_32x32x16_bf16 v[0:15], v[36:39], v[88:91], v[0:15]
	v_max_i32_e32 v97, 0, v21
	v_fmac_f32_e32 v98, v53, v97
	v_max_i32_e32 v97, 0, v22
	v_fmac_f32_e32 v98, v54, v97
	v_max_i32_e32 v97, 0, v23
	v_fmac_f32_e32 v98, v55, v97
	v_max_i32_e32 v97, 0, v24
	v_fmac_f32_e32 v98, v56, v97
	v_max_i32_e32 v97, 0, v25
	v_fmac_f32_e32 v98, v57, v97
	v_mfma_f32_32x32x16_bf16 v[0:15], v[40:43], v[80:83], v[0:15]
	v_max_i32_e32 v97, 0, v26
	v_fmac_f32_e32 v98, v58, v97
	v_max_i32_e32 v97, 0, v27
	v_fmac_f32_e32 v98, v59, v97
	v_max_i32_e32 v97, 0, v28
	v_fmac_f32_e32 v98, v60, v97
	v_max_i32_e32 v97, 0, v29
	v_fmac_f32_e32 v98, v61, v97
	v_mfma_f32_32x32x16_bf16 v[0:15], v[44:47], v[104:107], v[0:15]
	v_max_i32_e32 v97, 0, v30
	s_cmp_eq_u32 s58, 23
	v_fmac_f32_e32 v98, v62, v97
	v_max_i32_e32 v97, 0, v31
	s_cselect_b64 s[64:65], -1, 0
	v_cmp_gt_i32_e32 vcc, v149, v203
	v_fmac_f32_e32 v98, v63, v97
	s_and_b64 vcc, s[64:65], vcc
	v_cndmask_b32_e32 v217, v98, v197, vcc
	s_branch .LBB0_1268

.LBB0_1276:
	ds_read_b128 v[16:19], v134 offset:0
	ds_read_b128 v[80:83], v134 offset:32
	ds_read_b128 v[84:87], v134 offset:64
	ds_read_b128 v[92:95], v134 offset:0x60
	v_max_i32_e32 v88, 0, v0
	s_waitcnt lgkmcnt(0)
	v_max_i32_e32 v89, 0, v1
	v_mfma_f32_32x32x16_bf16 v[16:31], v[32:35], v[16:19], 0
	v_fma_f32 v218, v48, v88, 0
	v_max_i32_e32 v90, 0, v2
	v_fmac_f32_e32 v218, v49, v89
	v_max_i32_e32 v91, 0, v3
	v_fmac_f32_e32 v218, v50, v90
	v_max_i32_e32 v96, 0, v4
	v_fmac_f32_e32 v218, v51, v91
	v_mfma_f32_32x32x16_bf16 v[16:31], v[36:39], v[80:83], v[16:31]
	v_max_i32_e32 v97, 0, v5
	v_fmac_f32_e32 v218, v52, v96
	v_max_i32_e32 v98, 0, v6
	v_fmac_f32_e32 v218, v53, v97
	v_max_i32_e32 v99, 0, v7
	v_fmac_f32_e32 v218, v54, v98
	v_max_i32_e32 v100, 0, v8
	v_mfma_f32_32x32x16_bf16 v[16:31], v[40:43], v[84:87], v[16:31]
	v_fmac_f32_e32 v218, v55, v99
	v_max_i32_e32 v101, 0, v9
	v_fmac_f32_e32 v218, v56, v100
	v_max_i32_e32 v102, 0, v10
	v_fmac_f32_e32 v218, v57, v101
	v_max_i32_e32 v103, 0, v11
	v_fmac_f32_e32 v218, v58, v102
	v_fmac_f32_e32 v218, v59, v103
	v_max_i32_e32 v84, 0, v12
	ds_read_b128 v[80:83], v134 offset:0x1200
	v_fmac_f32_e32 v218, v60, v84
	v_max_i32_e32 v84, 0, v13
	ds_read_b128 v[88:91], v134 offset:0x1220
	v_fmac_f32_e32 v218, v61, v84
	v_max_i32_e32 v84, 0, v14
	ds_read_b128 v[96:99], v134 offset:0x1240
	v_fmac_f32_e32 v218, v62, v84
	v_max_i32_e32 v84, 0, v15
	ds_read_b128 v[104:107], v134 offset:0x1260
	v_mfma_f32_32x32x16_bf16 v[16:31], v[44:47], v[92:95], v[16:31]
	v_fmac_f32_e32 v218, v63, v84
	s_waitcnt lgkmcnt(0)
	ds_read_b128 v[108:111], v134 offset:0x2400
	ds_read_b128 v[100:103], v134 offset:0x2420
	ds_read_b128 v[92:95], v134 offset:0x2440
	ds_read_b128 v[84:87], v134 offset:0x2460
	s_cmp_eq_u32 s58, 25
	s_cselect_b64 s[52:53], -1, 0
	s_cmp_lg_u32 s58, 25
	s_cselect_b64 s[66:67], -1, 0
	s_and_b64 vcc, exec, s[52:53]
	s_cbranch_vccnz .LBB0_1278
	v_mfma_f32_32x32x16_bf16 v[0:15], v[32:35], v[80:83], 0
	v_max_i32_e32 v81, 0, v16
	v_fma_f32 v82, v48, v81, 0
	v_max_i32_e32 v81, 0, v17
	v_fmac_f32_e32 v82, v49, v81
	v_max_i32_e32 v81, 0, v18
	v_fmac_f32_e32 v82, v50, v81
	v_max_i32_e32 v81, 0, v19
	v_fmac_f32_e32 v82, v51, v81
	v_max_i32_e32 v81, 0, v20
	v_fmac_f32_e32 v82, v52, v81
	v_mfma_f32_32x32x16_bf16 v[0:15], v[36:39], v[88:91], v[0:15]
	v_max_i32_e32 v81, 0, v21
	v_fmac_f32_e32 v82, v53, v81
	v_max_i32_e32 v81, 0, v22
	v_fmac_f32_e32 v82, v54, v81
	v_max_i32_e32 v81, 0, v23
	v_fmac_f32_e32 v82, v55, v81
	v_max_i32_e32 v81, 0, v24
	v_fmac_f32_e32 v82, v56, v81
	v_max_i32_e32 v81, 0, v25
	v_fmac_f32_e32 v82, v57, v81
	v_mfma_f32_32x32x16_bf16 v[0:15], v[40:43], v[96:99], v[0:15]
	v_max_i32_e32 v81, 0, v26
	v_fmac_f32_e32 v82, v58, v81
	v_max_i32_e32 v81, 0, v27
	v_fmac_f32_e32 v82, v59, v81
	v_max_i32_e32 v81, 0, v28
	v_fmac_f32_e32 v82, v60, v81
	v_max_i32_e32 v81, 0, v29
	v_fmac_f32_e32 v82, v61, v81
	v_mfma_f32_32x32x16_bf16 v[0:15], v[44:47], v[104:107], v[0:15]
	v_max_i32_e32 v81, 0, v30
	v_fmac_f32_e32 v82, v62, v81
	v_max_i32_e32 v81, 0, v31
	v_cmp_gt_i32_e32 vcc, v151, v203
	v_fmac_f32_e32 v82, v63, v81
	s_and_b64 vcc, s[52:53], vcc
	v_cndmask_b32_e32 v219, v82, v197, vcc
	s_branch .Lixj91

.Lixj91:
	s_waitcnt lgkmcnt(0)
	ds_read_b128 v[96:99], v134 offset:0x3600
	ds_read_b128 v[88:91], v134 offset:0x3620
	ds_read_b128 v[80:83], v134 offset:0x3640
	ds_read_b128 v[104:107], v134 offset:0x3660
	s_cmp_gt_u32 s95, 51
	s_cselect_b64 s[64:65], -1, 0
	s_cmp_lt_u32 s95, 52
	s_cbranch_scc1 .LBB0_1280
	v_mfma_f32_32x32x16_bf16 v[16:31], v[32:35], v[108:111], 0
	v_cndmask_b32_e64 v109, 0, 1, s[66:67]
	v_cmp_ne_u32_e64 s[52:53], 1, v109
	s_andn2_b64 vcc, exec, s[66:67]
	v_max_i32_e32 v109, 0, v0
	v_fma_f32 v110, v48, v109, 0
	v_max_i32_e32 v109, 0, v1
	v_fmac_f32_e32 v110, v49, v109
	v_max_i32_e32 v109, 0, v2
	v_fmac_f32_e32 v110, v50, v109
	v_max_i32_e32 v109, 0, v3
	v_fmac_f32_e32 v110, v51, v109
	v_max_i32_e32 v109, 0, v4
	v_fmac_f32_e32 v110, v52, v109
	v_mfma_f32_32x32x16_bf16 v[16:31], v[36:39], v[100:103], v[16:31]
	v_max_i32_e32 v109, 0, v5
	v_fmac_f32_e32 v110, v53, v109
	v_max_i32_e32 v109, 0, v6
	v_fmac_f32_e32 v110, v54, v109
	v_max_i32_e32 v109, 0, v7
	v_fmac_f32_e32 v110, v55, v109
	v_max_i32_e32 v109, 0, v8
	v_fmac_f32_e32 v110, v56, v109
	v_max_i32_e32 v109, 0, v9
	v_fmac_f32_e32 v110, v57, v109
	v_mfma_f32_32x32x16_bf16 v[16:31], v[40:43], v[92:95], v[16:31]
	v_max_i32_e32 v109, 0, v10
	v_fmac_f32_e32 v110, v58, v109
	v_max_i32_e32 v109, 0, v11
	v_fmac_f32_e32 v110, v59, v109
	v_max_i32_e32 v109, 0, v12
	v_fmac_f32_e32 v110, v60, v109
	v_max_i32_e32 v109, 0, v13
	v_fmac_f32_e32 v110, v61, v109
	v_mfma_f32_32x32x16_bf16 v[16:31], v[44:47], v[84:87], v[16:31]
	v_max_i32_e32 v109, 0, v14
	s_cmp_eq_u32 s58, 26
	v_fmac_f32_e32 v110, v62, v109
	v_max_i32_e32 v109, 0, v15
	s_cselect_b64 s[66:67], -1, 0
	v_cmp_gt_i32_e32 vcc, v152, v203
	v_fmac_f32_e32 v110, v63, v109
	s_and_b64 vcc, s[66:67], vcc
	v_cndmask_b32_e32 v220, v110, v197, vcc
	s_branch .LBB0_1282

.LBB0_1284:
	s_waitcnt lgkmcnt(0)
	ds_read_b128 v[100:103], v134 offset:0x4800
	ds_read_b128 v[92:95], v134 offset:0x4820
	ds_read_b128 v[84:87], v134 offset:0x4840
	ds_read_b128 v[108:111], v134 offset:0x4860
	s_cmp_gt_u32 s95, 53
	s_cselect_b64 s[66:67], -1, 0
	s_cmp_lt_u32 s95, 54
	s_cbranch_scc1 .LBB0_1286
	v_mfma_f32_32x32x16_bf16 v[0:15], v[32:35], v[96:99], 0
	v_cndmask_b32_e64 v97, 0, 1, s[64:65]
	v_cmp_ne_u32_e64 s[52:53], 1, v97
	s_andn2_b64 vcc, exec, s[64:65]
	v_max_i32_e32 v97, 0, v16
	v_fma_f32 v98, v48, v97, 0
	v_max_i32_e32 v97, 0, v17
	v_fmac_f32_e32 v98, v49, v97
	v_max_i32_e32 v97, 0, v18
	v_fmac_f32_e32 v98, v50, v97
	v_max_i32_e32 v97, 0, v19
	v_fmac_f32_e32 v98, v51, v97
	v_max_i32_e32 v97, 0, v20
	v_fmac_f32_e32 v98, v52, v97
	v_mfma_f32_32x32x16_bf16 v[0:15], v[36:39], v[88:91], v[0:15]
	v_max_i32_e32 v97, 0, v21
	v_fmac_f32_e32 v98, v53, v97
	v_max_i32_e32 v97, 0, v22
	v_fmac_f32_e32 v98, v54, v97
	v_max_i32_e32 v97, 0, v23
	v_fmac_f32_e32 v98, v55, v97
	v_max_i32_e32 v97, 0, v24
	v_fmac_f32_e32 v98, v56, v97
	v_max_i32_e32 v97, 0, v25
	v_fmac_f32_e32 v98, v57, v97
	v_mfma_f32_32x32x16_bf16 v[0:15], v[40:43], v[80:83], v[0:15]
	v_max_i32_e32 v97, 0, v26
	v_fmac_f32_e32 v98, v58, v97
	v_max_i32_e32 v97, 0, v27
	v_fmac_f32_e32 v98, v59, v97
	v_max_i32_e32 v97, 0, v28
	v_fmac_f32_e32 v98, v60, v97
	v_max_i32_e32 v97, 0, v29
	v_fmac_f32_e32 v98, v61, v97
	v_mfma_f32_32x32x16_bf16 v[0:15], v[44:47], v[104:107], v[0:15]
	v_max_i32_e32 v97, 0, v30
	s_cmp_eq_u32 s58, 27
	v_fmac_f32_e32 v98, v62, v97
	v_max_i32_e32 v97, 0, v31
	s_cselect_b64 s[64:65], -1, 0
	v_cmp_gt_i32_e32 vcc, v153, v203
	v_fmac_f32_e32 v98, v63, v97
	s_and_b64 vcc, s[64:65], vcc
	v_cndmask_b32_e32 v221, v98, v197, vcc
	s_branch .LBB0_1288

.LBB0_1290:
	s_waitcnt lgkmcnt(0)
	ds_read_b128 v[96:99], v134 offset:0x5a00
	ds_read_b128 v[88:91], v134 offset:0x5a20
	ds_read_b128 v[80:83], v134 offset:0x5a40
	ds_read_b128 v[104:107], v134 offset:0x5a60
	s_cmp_gt_u32 s95, 55
	s_cselect_b64 s[64:65], -1, 0
	s_cmp_lt_u32 s95, 56
	s_cbranch_scc1 .LBB0_1292
	v_mfma_f32_32x32x16_bf16 v[16:31], v[32:35], v[100:103], 0
	v_cndmask_b32_e64 v101, 0, 1, s[66:67]
	v_cmp_ne_u32_e64 s[52:53], 1, v101
	s_andn2_b64 vcc, exec, s[66:67]
	v_max_i32_e32 v101, 0, v0
	v_fma_f32 v102, v48, v101, 0
	v_max_i32_e32 v101, 0, v1
	v_fmac_f32_e32 v102, v49, v101
	v_max_i32_e32 v101, 0, v2
	v_fmac_f32_e32 v102, v50, v101
	v_max_i32_e32 v101, 0, v3
	v_fmac_f32_e32 v102, v51, v101
	v_max_i32_e32 v101, 0, v4
	v_fmac_f32_e32 v102, v52, v101
	v_mfma_f32_32x32x16_bf16 v[16:31], v[36:39], v[92:95], v[16:31]
	v_max_i32_e32 v101, 0, v5
	v_fmac_f32_e32 v102, v53, v101
	v_max_i32_e32 v101, 0, v6
	v_fmac_f32_e32 v102, v54, v101
	v_max_i32_e32 v101, 0, v7
	v_fmac_f32_e32 v102, v55, v101
	v_max_i32_e32 v101, 0, v8
	v_fmac_f32_e32 v102, v56, v101
	v_max_i32_e32 v101, 0, v9
	v_fmac_f32_e32 v102, v57, v101
	v_mfma_f32_32x32x16_bf16 v[16:31], v[40:43], v[84:87], v[16:31]
	v_max_i32_e32 v101, 0, v10
	v_fmac_f32_e32 v102, v58, v101
	v_max_i32_e32 v101, 0, v11
	v_fmac_f32_e32 v102, v59, v101
	v_max_i32_e32 v101, 0, v12
	v_fmac_f32_e32 v102, v60, v101
	v_max_i32_e32 v101, 0, v13
	v_fmac_f32_e32 v102, v61, v101
	v_mfma_f32_32x32x16_bf16 v[16:31], v[44:47], v[108:111], v[16:31]
	v_max_i32_e32 v101, 0, v14
	s_cmp_eq_u32 s58, 28
	v_fmac_f32_e32 v102, v62, v101
	v_max_i32_e32 v101, 0, v15
	s_cselect_b64 s[66:67], -1, 0
	v_cmp_gt_i32_e32 vcc, v154, v203
	v_fmac_f32_e32 v102, v63, v101
	s_and_b64 vcc, s[66:67], vcc
	v_cndmask_b32_e32 v222, v102, v197, vcc
	s_branch .LBB0_1294

.LBB0_1296:
	s_waitcnt lgkmcnt(0)
	ds_read_b128 v[100:103], v134 offset:0x6c00
	ds_read_b128 v[92:95], v134 offset:0x6c20
	ds_read_b128 v[84:87], v134 offset:0x6c40
	ds_read_b128 v[108:111], v134 offset:0x6c60
	s_cmp_gt_u32 s95, 57
	s_cselect_b64 s[66:67], -1, 0
	s_cmp_lt_u32 s95, 58
	s_cbranch_scc1 .LBB0_1298
	v_mfma_f32_32x32x16_bf16 v[0:15], v[32:35], v[96:99], 0
	v_cndmask_b32_e64 v97, 0, 1, s[64:65]
	v_cmp_ne_u32_e64 s[52:53], 1, v97
	s_andn2_b64 vcc, exec, s[64:65]
	v_max_i32_e32 v97, 0, v16
	v_fma_f32 v98, v48, v97, 0
	v_max_i32_e32 v97, 0, v17
	v_fmac_f32_e32 v98, v49, v97
	v_max_i32_e32 v97, 0, v18
	v_fmac_f32_e32 v98, v50, v97
	v_max_i32_e32 v97, 0, v19
	v_fmac_f32_e32 v98, v51, v97
	v_max_i32_e32 v97, 0, v20
	v_fmac_f32_e32 v98, v52, v97
	v_mfma_f32_32x32x16_bf16 v[0:15], v[36:39], v[88:91], v[0:15]
	v_max_i32_e32 v97, 0, v21
	v_fmac_f32_e32 v98, v53, v97
	v_max_i32_e32 v97, 0, v22
	v_fmac_f32_e32 v98, v54, v97
	v_max_i32_e32 v97, 0, v23
	v_fmac_f32_e32 v98, v55, v97
	v_max_i32_e32 v97, 0, v24
	v_fmac_f32_e32 v98, v56, v97
	v_max_i32_e32 v97, 0, v25
	v_fmac_f32_e32 v98, v57, v97
	v_mfma_f32_32x32x16_bf16 v[0:15], v[40:43], v[80:83], v[0:15]
	v_max_i32_e32 v97, 0, v26
	v_fmac_f32_e32 v98, v58, v97
	v_max_i32_e32 v97, 0, v27
	v_fmac_f32_e32 v98, v59, v97
	v_max_i32_e32 v97, 0, v28
	v_fmac_f32_e32 v98, v60, v97
	v_max_i32_e32 v97, 0, v29
	v_fmac_f32_e32 v98, v61, v97
	v_mfma_f32_32x32x16_bf16 v[0:15], v[44:47], v[104:107], v[0:15]
	v_max_i32_e32 v97, 0, v30
	s_cmp_eq_u32 s58, 29
	v_fmac_f32_e32 v98, v62, v97
	v_max_i32_e32 v97, 0, v31
	s_cselect_b64 s[64:65], -1, 0
	v_cmp_gt_i32_e32 vcc, v155, v203
	v_fmac_f32_e32 v98, v63, v97
	s_and_b64 vcc, s[64:65], vcc
	v_cndmask_b32_e32 v223, v98, v197, vcc
	s_branch .LBB0_1300

.LBB0_1302:
	s_waitcnt lgkmcnt(0)
	ds_read_b128 v[96:99], v134 offset:0x7e00
	ds_read_b128 v[88:91], v134 offset:0x7e20
	ds_read_b128 v[80:83], v134 offset:0x7e40
	ds_read_b128 v[104:107], v134 offset:0x7e60
	s_cmp_gt_u32 s95, 59
	s_cselect_b64 s[64:65], -1, 0
	s_cmp_lt_u32 s95, 60
	s_cbranch_scc1 .LBB0_1304
	v_mfma_f32_32x32x16_bf16 v[16:31], v[32:35], v[100:103], 0
	v_cndmask_b32_e64 v101, 0, 1, s[66:67]
	v_cmp_ne_u32_e64 s[52:53], 1, v101
	s_andn2_b64 vcc, exec, s[66:67]
	v_max_i32_e32 v101, 0, v0
	v_fma_f32 v102, v48, v101, 0
	v_max_i32_e32 v101, 0, v1
	v_fmac_f32_e32 v102, v49, v101
	v_max_i32_e32 v101, 0, v2
	v_fmac_f32_e32 v102, v50, v101
	v_max_i32_e32 v101, 0, v3
	v_fmac_f32_e32 v102, v51, v101
	v_max_i32_e32 v101, 0, v4
	v_fmac_f32_e32 v102, v52, v101
	v_mfma_f32_32x32x16_bf16 v[16:31], v[36:39], v[92:95], v[16:31]
	v_max_i32_e32 v101, 0, v5
	v_fmac_f32_e32 v102, v53, v101
	v_max_i32_e32 v101, 0, v6
	v_fmac_f32_e32 v102, v54, v101
	v_max_i32_e32 v101, 0, v7
	v_fmac_f32_e32 v102, v55, v101
	v_max_i32_e32 v101, 0, v8
	v_fmac_f32_e32 v102, v56, v101
	v_max_i32_e32 v101, 0, v9
	v_fmac_f32_e32 v102, v57, v101
	v_mfma_f32_32x32x16_bf16 v[16:31], v[40:43], v[84:87], v[16:31]
	v_max_i32_e32 v101, 0, v10
	v_fmac_f32_e32 v102, v58, v101
	v_max_i32_e32 v101, 0, v11
	v_fmac_f32_e32 v102, v59, v101
	v_max_i32_e32 v101, 0, v12
	v_fmac_f32_e32 v102, v60, v101
	v_max_i32_e32 v101, 0, v13
	v_fmac_f32_e32 v102, v61, v101
	v_mfma_f32_32x32x16_bf16 v[16:31], v[44:47], v[108:111], v[16:31]
	v_max_i32_e32 v101, 0, v14
	s_cmp_eq_u32 s58, 30
	v_fmac_f32_e32 v102, v62, v101
	v_max_i32_e32 v101, 0, v15
	s_cselect_b64 s[66:67], -1, 0
	v_cmp_gt_i32_e32 vcc, v156, v203
	v_fmac_f32_e32 v102, v63, v101
	s_and_b64 vcc, s[66:67], vcc
	v_cndmask_b32_e32 v224, v102, v197, vcc
	s_branch .LBB0_1306

.LBB0_1308:
	s_waitcnt lgkmcnt(0)
	s_cmp_lt_u32 s95, 62
	s_cbranch_scc1 .LBB0_1310
	v_mfma_f32_32x32x16_bf16 v[0:15], v[32:35], v[96:99], 0
	v_cndmask_b32_e64 v97, 0, 1, s[64:65]
	v_cmp_ne_u32_e64 s[52:53], 1, v97
	s_andn2_b64 vcc, exec, s[64:65]
	v_max_i32_e32 v97, 0, v16
	v_fma_f32 v98, v48, v97, 0
	v_max_i32_e32 v97, 0, v17
	v_fmac_f32_e32 v98, v49, v97
	v_max_i32_e32 v97, 0, v18
	v_fmac_f32_e32 v98, v50, v97
	v_max_i32_e32 v97, 0, v19
	v_fmac_f32_e32 v98, v51, v97
	v_max_i32_e32 v97, 0, v20
	v_fmac_f32_e32 v98, v52, v97
	v_mfma_f32_32x32x16_bf16 v[0:15], v[36:39], v[88:91], v[0:15]
	v_max_i32_e32 v97, 0, v21
	v_fmac_f32_e32 v98, v53, v97
	v_max_i32_e32 v97, 0, v22
	v_fmac_f32_e32 v98, v54, v97
	v_max_i32_e32 v97, 0, v23
	v_fmac_f32_e32 v98, v55, v97
	v_max_i32_e32 v97, 0, v24
	v_fmac_f32_e32 v98, v56, v97
	v_max_i32_e32 v97, 0, v25
	v_fmac_f32_e32 v98, v57, v97
	v_mfma_f32_32x32x16_bf16 v[0:15], v[40:43], v[80:83], v[0:15]
	v_max_i32_e32 v97, 0, v26
	v_fmac_f32_e32 v98, v58, v97
	v_max_i32_e32 v97, 0, v27
	v_fmac_f32_e32 v98, v59, v97
	v_max_i32_e32 v97, 0, v28
	v_fmac_f32_e32 v98, v60, v97
	v_max_i32_e32 v97, 0, v29
	v_fmac_f32_e32 v98, v61, v97
	v_mfma_f32_32x32x16_bf16 v[0:15], v[44:47], v[104:107], v[0:15]
	v_max_i32_e32 v97, 0, v30
	s_cmp_eq_u32 s58, 31
	v_fmac_f32_e32 v98, v62, v97
	v_max_i32_e32 v97, 0, v31
	s_cselect_b64 s[64:65], -1, 0
	v_cmp_gt_i32_e32 vcc, v157, v203
	v_fmac_f32_e32 v98, v63, v97
	s_and_b64 vcc, s[64:65], vcc
	v_cndmask_b32_e32 v225, v98, v197, vcc
	s_branch .LBB0_1312

.LBB0_1320:
	ds_read_b128 v[16:19], v131 offset:0
	ds_read_b128 v[80:83], v131 offset:32
	ds_read_b128 v[84:87], v131 offset:64
	ds_read_b128 v[92:95], v131 offset:0x60
	v_max_i32_e32 v88, 0, v0
	s_waitcnt lgkmcnt(0)
	v_max_i32_e32 v89, 0, v1
	v_mfma_f32_32x32x16_bf16 v[16:31], v[32:35], v[16:19], 0
	v_fma_f32 v226, v48, v88, 0
	v_max_i32_e32 v90, 0, v2
	v_fmac_f32_e32 v226, v49, v89
	v_max_i32_e32 v91, 0, v3
	v_fmac_f32_e32 v226, v50, v90
	v_max_i32_e32 v96, 0, v4
	v_fmac_f32_e32 v226, v51, v91
	v_mfma_f32_32x32x16_bf16 v[16:31], v[36:39], v[80:83], v[16:31]
	v_max_i32_e32 v97, 0, v5
	v_fmac_f32_e32 v226, v52, v96
	v_max_i32_e32 v98, 0, v6
	v_fmac_f32_e32 v226, v53, v97
	v_max_i32_e32 v99, 0, v7
	v_fmac_f32_e32 v226, v54, v98
	v_max_i32_e32 v100, 0, v8
	v_mfma_f32_32x32x16_bf16 v[16:31], v[40:43], v[84:87], v[16:31]
	v_fmac_f32_e32 v226, v55, v99
	v_max_i32_e32 v101, 0, v9
	v_fmac_f32_e32 v226, v56, v100
	v_max_i32_e32 v102, 0, v10
	v_fmac_f32_e32 v226, v57, v101
	v_max_i32_e32 v103, 0, v11
	v_fmac_f32_e32 v226, v58, v102
	v_fmac_f32_e32 v226, v59, v103
	v_max_i32_e32 v84, 0, v12
	ds_read_b128 v[80:83], v131 offset:0x1200
	v_fmac_f32_e32 v226, v60, v84
	v_max_i32_e32 v84, 0, v13
	ds_read_b128 v[88:91], v131 offset:0x1220
	v_fmac_f32_e32 v226, v61, v84
	v_max_i32_e32 v84, 0, v14
	ds_read_b128 v[96:99], v131 offset:0x1240
	v_fmac_f32_e32 v226, v62, v84
	v_max_i32_e32 v84, 0, v15
	ds_read_b128 v[104:107], v131 offset:0x1260
	v_mfma_f32_32x32x16_bf16 v[16:31], v[44:47], v[92:95], v[16:31]
	v_fmac_f32_e32 v226, v63, v84
	s_waitcnt lgkmcnt(0)
	ds_read_b128 v[108:111], v131 offset:0x2400
	ds_read_b128 v[100:103], v131 offset:0x2420
	ds_read_b128 v[92:95], v131 offset:0x2440
	ds_read_b128 v[84:87], v131 offset:0x2460
	s_cmp_eq_u32 s58, 33
	s_cselect_b64 s[52:53], -1, 0
	s_cmp_lg_u32 s58, 33
	s_cselect_b64 s[66:67], -1, 0
	s_and_b64 vcc, exec, s[52:53]
	s_cbranch_vccnz .LBB0_1322
	v_mfma_f32_32x32x16_bf16 v[0:15], v[32:35], v[80:83], 0
	v_max_i32_e32 v81, 0, v16
	v_fma_f32 v82, v48, v81, 0
	v_max_i32_e32 v81, 0, v17
	v_fmac_f32_e32 v82, v49, v81
	v_max_i32_e32 v81, 0, v18
	v_fmac_f32_e32 v82, v50, v81
	v_max_i32_e32 v81, 0, v19
	v_fmac_f32_e32 v82, v51, v81
	v_max_i32_e32 v81, 0, v20
	v_fmac_f32_e32 v82, v52, v81
	v_mfma_f32_32x32x16_bf16 v[0:15], v[36:39], v[88:91], v[0:15]
	v_max_i32_e32 v81, 0, v21
	v_fmac_f32_e32 v82, v53, v81
	v_max_i32_e32 v81, 0, v22
	v_fmac_f32_e32 v82, v54, v81
	v_max_i32_e32 v81, 0, v23
	v_fmac_f32_e32 v82, v55, v81
	v_max_i32_e32 v81, 0, v24
	v_fmac_f32_e32 v82, v56, v81
	v_max_i32_e32 v81, 0, v25
	v_fmac_f32_e32 v82, v57, v81
	v_mfma_f32_32x32x16_bf16 v[0:15], v[40:43], v[96:99], v[0:15]
	v_max_i32_e32 v81, 0, v26
	v_fmac_f32_e32 v82, v58, v81
	v_max_i32_e32 v81, 0, v27
	v_fmac_f32_e32 v82, v59, v81
	v_max_i32_e32 v81, 0, v28
	v_fmac_f32_e32 v82, v60, v81
	v_max_i32_e32 v81, 0, v29
	v_fmac_f32_e32 v82, v61, v81
	v_mfma_f32_32x32x16_bf16 v[0:15], v[44:47], v[104:107], v[0:15]
	v_max_i32_e32 v81, 0, v30
	v_fmac_f32_e32 v82, v62, v81
	v_max_i32_e32 v81, 0, v31
	v_cmp_gt_i32_e32 vcc, v159, v203
	v_fmac_f32_e32 v82, v63, v81
	s_and_b64 vcc, s[52:53], vcc
	v_cndmask_b32_e32 v227, v82, v197, vcc
	s_branch .Lixj84

.Lixj84:
	s_waitcnt lgkmcnt(0)
	ds_read_b128 v[96:99], v131 offset:0x3600
	ds_read_b128 v[88:91], v131 offset:0x3620
	ds_read_b128 v[80:83], v131 offset:0x3640
	ds_read_b128 v[104:107], v131 offset:0x3660
	s_cmpk_gt_u32 s95, 0x43
	s_cselect_b64 s[64:65], -1, 0
	s_cmpk_lt_u32 s95, 0x44
	s_cbranch_scc1 .LBB0_1324
	v_mfma_f32_32x32x16_bf16 v[16:31], v[32:35], v[108:111], 0
	v_cndmask_b32_e64 v109, 0, 1, s[66:67]
	v_cmp_ne_u32_e64 s[52:53], 1, v109
	s_andn2_b64 vcc, exec, s[66:67]
	v_max_i32_e32 v109, 0, v0
	v_fma_f32 v110, v48, v109, 0
	v_max_i32_e32 v109, 0, v1
	v_fmac_f32_e32 v110, v49, v109
	v_max_i32_e32 v109, 0, v2
	v_fmac_f32_e32 v110, v50, v109
	v_max_i32_e32 v109, 0, v3
	v_fmac_f32_e32 v110, v51, v109
	v_max_i32_e32 v109, 0, v4
	v_fmac_f32_e32 v110, v52, v109
	v_mfma_f32_32x32x16_bf16 v[16:31], v[36:39], v[100:103], v[16:31]
	v_max_i32_e32 v109, 0, v5
	v_fmac_f32_e32 v110, v53, v109
	v_max_i32_e32 v109, 0, v6
	v_fmac_f32_e32 v110, v54, v109
	v_max_i32_e32 v109, 0, v7
	v_fmac_f32_e32 v110, v55, v109
	v_max_i32_e32 v109, 0, v8
	v_fmac_f32_e32 v110, v56, v109
	v_max_i32_e32 v109, 0, v9
	v_fmac_f32_e32 v110, v57, v109
	v_mfma_f32_32x32x16_bf16 v[16:31], v[40:43], v[92:95], v[16:31]
	v_max_i32_e32 v109, 0, v10
	v_fmac_f32_e32 v110, v58, v109
	v_max_i32_e32 v109, 0, v11
	v_fmac_f32_e32 v110, v59, v109
	v_max_i32_e32 v109, 0, v12
	v_fmac_f32_e32 v110, v60, v109
	v_max_i32_e32 v109, 0, v13
	v_fmac_f32_e32 v110, v61, v109
	v_mfma_f32_32x32x16_bf16 v[16:31], v[44:47], v[84:87], v[16:31]
	v_max_i32_e32 v109, 0, v14
	s_cmp_eq_u32 s58, 34
	v_fmac_f32_e32 v110, v62, v109
	v_max_i32_e32 v109, 0, v15
	s_cselect_b64 s[66:67], -1, 0
	v_cmp_gt_i32_e32 vcc, v160, v203
	v_fmac_f32_e32 v110, v63, v109
	s_and_b64 vcc, s[66:67], vcc
	v_cndmask_b32_e32 v228, v110, v197, vcc
	s_branch .LBB0_1326

.LBB0_1328:
	s_waitcnt lgkmcnt(0)
	ds_read_b128 v[100:103], v131 offset:0x4800
	ds_read_b128 v[92:95], v131 offset:0x4820
	ds_read_b128 v[84:87], v131 offset:0x4840
	ds_read_b128 v[108:111], v131 offset:0x4860
	s_cmpk_gt_u32 s95, 0x45
	s_cselect_b64 s[66:67], -1, 0
	s_cmpk_lt_u32 s95, 0x46
	s_cbranch_scc1 .LBB0_1330
	v_mfma_f32_32x32x16_bf16 v[0:15], v[32:35], v[96:99], 0
	v_cndmask_b32_e64 v97, 0, 1, s[64:65]
	v_cmp_ne_u32_e64 s[52:53], 1, v97
	s_andn2_b64 vcc, exec, s[64:65]
	v_max_i32_e32 v97, 0, v16
	v_fma_f32 v98, v48, v97, 0
	v_max_i32_e32 v97, 0, v17
	v_fmac_f32_e32 v98, v49, v97
	v_max_i32_e32 v97, 0, v18
	v_fmac_f32_e32 v98, v50, v97
	v_max_i32_e32 v97, 0, v19
	v_fmac_f32_e32 v98, v51, v97
	v_max_i32_e32 v97, 0, v20
	v_fmac_f32_e32 v98, v52, v97
	v_mfma_f32_32x32x16_bf16 v[0:15], v[36:39], v[88:91], v[0:15]
	v_max_i32_e32 v97, 0, v21
	v_fmac_f32_e32 v98, v53, v97
	v_max_i32_e32 v97, 0, v22
	v_fmac_f32_e32 v98, v54, v97
	v_max_i32_e32 v97, 0, v23
	v_fmac_f32_e32 v98, v55, v97
	v_max_i32_e32 v97, 0, v24
	v_fmac_f32_e32 v98, v56, v97
	v_max_i32_e32 v97, 0, v25
	v_fmac_f32_e32 v98, v57, v97
	v_mfma_f32_32x32x16_bf16 v[0:15], v[40:43], v[80:83], v[0:15]
	v_max_i32_e32 v97, 0, v26
	v_fmac_f32_e32 v98, v58, v97
	v_max_i32_e32 v97, 0, v27
	v_fmac_f32_e32 v98, v59, v97
	v_max_i32_e32 v97, 0, v28
	v_fmac_f32_e32 v98, v60, v97
	v_max_i32_e32 v97, 0, v29
	v_fmac_f32_e32 v98, v61, v97
	v_mfma_f32_32x32x16_bf16 v[0:15], v[44:47], v[104:107], v[0:15]
	v_max_i32_e32 v97, 0, v30
	s_cmp_eq_u32 s58, 35
	v_fmac_f32_e32 v98, v62, v97
	v_max_i32_e32 v97, 0, v31
	s_cselect_b64 s[64:65], -1, 0
	v_cmp_gt_i32_e32 vcc, v161, v203
	v_fmac_f32_e32 v98, v63, v97
	s_and_b64 vcc, s[64:65], vcc
	v_cndmask_b32_e32 v229, v98, v197, vcc
	s_branch .LBB0_1332

.LBB0_1334:
	s_waitcnt lgkmcnt(0)
	ds_read_b128 v[96:99], v131 offset:0x5a00
	ds_read_b128 v[88:91], v131 offset:0x5a20
	ds_read_b128 v[80:83], v131 offset:0x5a40
	ds_read_b128 v[104:107], v131 offset:0x5a60
	s_cmpk_gt_u32 s95, 0x47
	s_cselect_b64 s[64:65], -1, 0
	s_cmpk_lt_u32 s95, 0x48
	s_cbranch_scc1 .LBB0_1336
	v_mfma_f32_32x32x16_bf16 v[16:31], v[32:35], v[100:103], 0
	v_cndmask_b32_e64 v101, 0, 1, s[66:67]
	v_cmp_ne_u32_e64 s[52:53], 1, v101
	s_andn2_b64 vcc, exec, s[66:67]
	v_max_i32_e32 v101, 0, v0
	v_fma_f32 v102, v48, v101, 0
	v_max_i32_e32 v101, 0, v1
	v_fmac_f32_e32 v102, v49, v101
	v_max_i32_e32 v101, 0, v2
	v_fmac_f32_e32 v102, v50, v101
	v_max_i32_e32 v101, 0, v3
	v_fmac_f32_e32 v102, v51, v101
	v_max_i32_e32 v101, 0, v4
	v_fmac_f32_e32 v102, v52, v101
	v_mfma_f32_32x32x16_bf16 v[16:31], v[36:39], v[92:95], v[16:31]
	v_max_i32_e32 v101, 0, v5
	v_fmac_f32_e32 v102, v53, v101
	v_max_i32_e32 v101, 0, v6
	v_fmac_f32_e32 v102, v54, v101
	v_max_i32_e32 v101, 0, v7
	v_fmac_f32_e32 v102, v55, v101
	v_max_i32_e32 v101, 0, v8
	v_fmac_f32_e32 v102, v56, v101
	v_max_i32_e32 v101, 0, v9
	v_fmac_f32_e32 v102, v57, v101
	v_mfma_f32_32x32x16_bf16 v[16:31], v[40:43], v[84:87], v[16:31]
	v_max_i32_e32 v101, 0, v10
	v_fmac_f32_e32 v102, v58, v101
	v_max_i32_e32 v101, 0, v11
	v_fmac_f32_e32 v102, v59, v101
	v_max_i32_e32 v101, 0, v12
	v_fmac_f32_e32 v102, v60, v101
	v_max_i32_e32 v101, 0, v13
	v_fmac_f32_e32 v102, v61, v101
	v_mfma_f32_32x32x16_bf16 v[16:31], v[44:47], v[108:111], v[16:31]
	v_max_i32_e32 v101, 0, v14
	s_cmp_eq_u32 s58, 36
	v_fmac_f32_e32 v102, v62, v101
	v_max_i32_e32 v101, 0, v15
	s_cselect_b64 s[66:67], -1, 0
	v_cmp_gt_i32_e32 vcc, v162, v203
	v_fmac_f32_e32 v102, v63, v101
	s_and_b64 vcc, s[66:67], vcc
	v_cndmask_b32_e32 v230, v102, v197, vcc
	s_branch .LBB0_1338

.LBB0_1340:
	s_waitcnt lgkmcnt(0)
	ds_read_b128 v[100:103], v131 offset:0x6c00
	ds_read_b128 v[92:95], v131 offset:0x6c20
	ds_read_b128 v[84:87], v131 offset:0x6c40
	ds_read_b128 v[108:111], v131 offset:0x6c60
	s_cmpk_gt_u32 s95, 0x49
	s_cselect_b64 s[66:67], -1, 0
	s_cmpk_lt_u32 s95, 0x4a
	s_cbranch_scc1 .LBB0_1342
	v_mfma_f32_32x32x16_bf16 v[0:15], v[32:35], v[96:99], 0
	v_cndmask_b32_e64 v97, 0, 1, s[64:65]
	v_cmp_ne_u32_e64 s[52:53], 1, v97
	s_andn2_b64 vcc, exec, s[64:65]
	v_max_i32_e32 v97, 0, v16
	v_fma_f32 v98, v48, v97, 0
	v_max_i32_e32 v97, 0, v17
	v_fmac_f32_e32 v98, v49, v97
	v_max_i32_e32 v97, 0, v18
	v_fmac_f32_e32 v98, v50, v97
	v_max_i32_e32 v97, 0, v19
	v_fmac_f32_e32 v98, v51, v97
	v_max_i32_e32 v97, 0, v20
	v_fmac_f32_e32 v98, v52, v97
	v_mfma_f32_32x32x16_bf16 v[0:15], v[36:39], v[88:91], v[0:15]
	v_max_i32_e32 v97, 0, v21
	v_fmac_f32_e32 v98, v53, v97
	v_max_i32_e32 v97, 0, v22
	v_fmac_f32_e32 v98, v54, v97
	v_max_i32_e32 v97, 0, v23
	v_fmac_f32_e32 v98, v55, v97
	v_max_i32_e32 v97, 0, v24
	v_fmac_f32_e32 v98, v56, v97
	v_max_i32_e32 v97, 0, v25
	v_fmac_f32_e32 v98, v57, v97
	v_mfma_f32_32x32x16_bf16 v[0:15], v[40:43], v[80:83], v[0:15]
	v_max_i32_e32 v97, 0, v26
	v_fmac_f32_e32 v98, v58, v97
	v_max_i32_e32 v97, 0, v27
	v_fmac_f32_e32 v98, v59, v97
	v_max_i32_e32 v97, 0, v28
	v_fmac_f32_e32 v98, v60, v97
	v_max_i32_e32 v97, 0, v29
	v_fmac_f32_e32 v98, v61, v97
	v_mfma_f32_32x32x16_bf16 v[0:15], v[44:47], v[104:107], v[0:15]
	v_max_i32_e32 v97, 0, v30
	s_cmp_eq_u32 s58, 37
	v_fmac_f32_e32 v98, v62, v97
	v_max_i32_e32 v97, 0, v31
	s_cselect_b64 s[64:65], -1, 0
	v_cmp_gt_i32_e32 vcc, v163, v203
	v_fmac_f32_e32 v98, v63, v97
	s_and_b64 vcc, s[64:65], vcc
	v_cndmask_b32_e32 v231, v98, v197, vcc
	s_branch .LBB0_1344

.LBB0_1346:
	s_waitcnt lgkmcnt(0)
	ds_read_b128 v[96:99], v131 offset:0x7e00
	ds_read_b128 v[88:91], v131 offset:0x7e20
	ds_read_b128 v[80:83], v131 offset:0x7e40
	ds_read_b128 v[104:107], v131 offset:0x7e60
	s_cmpk_gt_u32 s95, 0x4b
	s_cselect_b64 s[64:65], -1, 0
	s_cmpk_lt_u32 s95, 0x4c
	s_cbranch_scc1 .LBB0_1348
	v_mfma_f32_32x32x16_bf16 v[16:31], v[32:35], v[100:103], 0
	v_cndmask_b32_e64 v101, 0, 1, s[66:67]
	v_cmp_ne_u32_e64 s[52:53], 1, v101
	s_andn2_b64 vcc, exec, s[66:67]
	v_max_i32_e32 v101, 0, v0
	v_fma_f32 v102, v48, v101, 0
	v_max_i32_e32 v101, 0, v1
	v_fmac_f32_e32 v102, v49, v101
	v_max_i32_e32 v101, 0, v2
	v_fmac_f32_e32 v102, v50, v101
	v_max_i32_e32 v101, 0, v3
	v_fmac_f32_e32 v102, v51, v101
	v_max_i32_e32 v101, 0, v4
	v_fmac_f32_e32 v102, v52, v101
	v_mfma_f32_32x32x16_bf16 v[16:31], v[36:39], v[92:95], v[16:31]
	v_max_i32_e32 v101, 0, v5
	v_fmac_f32_e32 v102, v53, v101
	v_max_i32_e32 v101, 0, v6
	v_fmac_f32_e32 v102, v54, v101
	v_max_i32_e32 v101, 0, v7
	v_fmac_f32_e32 v102, v55, v101
	v_max_i32_e32 v101, 0, v8
	v_fmac_f32_e32 v102, v56, v101
	v_max_i32_e32 v101, 0, v9
	v_fmac_f32_e32 v102, v57, v101
	v_mfma_f32_32x32x16_bf16 v[16:31], v[40:43], v[84:87], v[16:31]
	v_max_i32_e32 v101, 0, v10
	v_fmac_f32_e32 v102, v58, v101
	v_max_i32_e32 v101, 0, v11
	v_fmac_f32_e32 v102, v59, v101
	v_max_i32_e32 v101, 0, v12
	v_fmac_f32_e32 v102, v60, v101
	v_max_i32_e32 v101, 0, v13
	v_fmac_f32_e32 v102, v61, v101
	v_mfma_f32_32x32x16_bf16 v[16:31], v[44:47], v[108:111], v[16:31]
	v_max_i32_e32 v101, 0, v14
	s_cmp_eq_u32 s58, 38
	v_fmac_f32_e32 v102, v62, v101
	v_max_i32_e32 v101, 0, v15
	s_cselect_b64 s[66:67], -1, 0
	v_cmp_gt_i32_e32 vcc, v164, v203
	v_fmac_f32_e32 v102, v63, v101
	s_and_b64 vcc, s[66:67], vcc
	v_cndmask_b32_e32 v232, v102, v197, vcc
	s_branch .LBB0_1350

.LBB0_1352:
	s_waitcnt lgkmcnt(0)
	s_cmpk_lt_u32 s95, 0x4e
	s_cbranch_scc1 .LBB0_1354
	v_mfma_f32_32x32x16_bf16 v[0:15], v[32:35], v[96:99], 0
	v_cndmask_b32_e64 v97, 0, 1, s[64:65]
	v_cmp_ne_u32_e64 s[52:53], 1, v97
	s_andn2_b64 vcc, exec, s[64:65]
	v_max_i32_e32 v97, 0, v16
	v_fma_f32 v98, v48, v97, 0
	v_max_i32_e32 v97, 0, v17
	v_fmac_f32_e32 v98, v49, v97
	v_max_i32_e32 v97, 0, v18
	v_fmac_f32_e32 v98, v50, v97
	v_max_i32_e32 v97, 0, v19
	v_fmac_f32_e32 v98, v51, v97
	v_max_i32_e32 v97, 0, v20
	v_fmac_f32_e32 v98, v52, v97
	v_mfma_f32_32x32x16_bf16 v[0:15], v[36:39], v[88:91], v[0:15]
	v_max_i32_e32 v97, 0, v21
	v_fmac_f32_e32 v98, v53, v97
	v_max_i32_e32 v97, 0, v22
	v_fmac_f32_e32 v98, v54, v97
	v_max_i32_e32 v97, 0, v23
	v_fmac_f32_e32 v98, v55, v97
	v_max_i32_e32 v97, 0, v24
	v_fmac_f32_e32 v98, v56, v97
	v_max_i32_e32 v97, 0, v25
	v_fmac_f32_e32 v98, v57, v97
	v_mfma_f32_32x32x16_bf16 v[0:15], v[40:43], v[80:83], v[0:15]
	v_max_i32_e32 v97, 0, v26
	v_fmac_f32_e32 v98, v58, v97
	v_max_i32_e32 v97, 0, v27
	v_fmac_f32_e32 v98, v59, v97
	v_max_i32_e32 v97, 0, v28
	v_fmac_f32_e32 v98, v60, v97
	v_max_i32_e32 v97, 0, v29
	v_fmac_f32_e32 v98, v61, v97
	v_mfma_f32_32x32x16_bf16 v[0:15], v[44:47], v[104:107], v[0:15]
	v_max_i32_e32 v97, 0, v30
	s_cmp_eq_u32 s58, 39
	v_fmac_f32_e32 v98, v62, v97
	v_max_i32_e32 v97, 0, v31
	s_cselect_b64 s[64:65], -1, 0
	v_cmp_gt_i32_e32 vcc, v165, v203
	v_fmac_f32_e32 v98, v63, v97
	s_and_b64 vcc, s[64:65], vcc
	v_cndmask_b32_e32 v233, v98, v197, vcc
	s_branch .LBB0_1356

.LBB0_1364:
	ds_read_b128 v[16:19], v134 offset:0
	ds_read_b128 v[80:83], v134 offset:32
	ds_read_b128 v[84:87], v134 offset:64
	ds_read_b128 v[92:95], v134 offset:0x60
	v_max_i32_e32 v88, 0, v0
	s_waitcnt lgkmcnt(0)
	v_max_i32_e32 v89, 0, v1
	v_mfma_f32_32x32x16_bf16 v[16:31], v[32:35], v[16:19], 0
	v_fma_f32 v234, v48, v88, 0
	v_max_i32_e32 v90, 0, v2
	v_fmac_f32_e32 v234, v49, v89
	v_max_i32_e32 v91, 0, v3
	v_fmac_f32_e32 v234, v50, v90
	v_max_i32_e32 v96, 0, v4
	v_fmac_f32_e32 v234, v51, v91
	v_mfma_f32_32x32x16_bf16 v[16:31], v[36:39], v[80:83], v[16:31]
	v_max_i32_e32 v97, 0, v5
	v_fmac_f32_e32 v234, v52, v96
	v_max_i32_e32 v98, 0, v6
	v_fmac_f32_e32 v234, v53, v97
	v_max_i32_e32 v99, 0, v7
	v_fmac_f32_e32 v234, v54, v98
	v_max_i32_e32 v100, 0, v8
	v_mfma_f32_32x32x16_bf16 v[16:31], v[40:43], v[84:87], v[16:31]
	v_fmac_f32_e32 v234, v55, v99
	v_max_i32_e32 v101, 0, v9
	v_fmac_f32_e32 v234, v56, v100
	v_max_i32_e32 v102, 0, v10
	v_fmac_f32_e32 v234, v57, v101
	v_max_i32_e32 v103, 0, v11
	v_fmac_f32_e32 v234, v58, v102
	v_fmac_f32_e32 v234, v59, v103
	v_max_i32_e32 v84, 0, v12
	ds_read_b128 v[80:83], v134 offset:0x1200
	v_fmac_f32_e32 v234, v60, v84
	v_max_i32_e32 v84, 0, v13
	ds_read_b128 v[88:91], v134 offset:0x1220
	v_fmac_f32_e32 v234, v61, v84
	v_max_i32_e32 v84, 0, v14
	ds_read_b128 v[96:99], v134 offset:0x1240
	v_fmac_f32_e32 v234, v62, v84
	v_max_i32_e32 v84, 0, v15
	ds_read_b128 v[104:107], v134 offset:0x1260
	v_mfma_f32_32x32x16_bf16 v[16:31], v[44:47], v[92:95], v[16:31]
	v_fmac_f32_e32 v234, v63, v84
	s_waitcnt lgkmcnt(0)
	ds_read_b128 v[108:111], v134 offset:0x2400
	ds_read_b128 v[100:103], v134 offset:0x2420
	ds_read_b128 v[92:95], v134 offset:0x2440
	ds_read_b128 v[84:87], v134 offset:0x2460
	s_cmp_eq_u32 s58, 41
	s_cselect_b64 s[52:53], -1, 0
	s_cmp_lg_u32 s58, 41
	s_cselect_b64 s[66:67], -1, 0
	s_and_b64 vcc, exec, s[52:53]
	s_cbranch_vccnz .LBB0_1366
	v_mfma_f32_32x32x16_bf16 v[0:15], v[32:35], v[80:83], 0
	v_max_i32_e32 v81, 0, v16
	v_fma_f32 v82, v48, v81, 0
	v_max_i32_e32 v81, 0, v17
	v_fmac_f32_e32 v82, v49, v81
	v_max_i32_e32 v81, 0, v18
	v_fmac_f32_e32 v82, v50, v81
	v_max_i32_e32 v81, 0, v19
	v_fmac_f32_e32 v82, v51, v81
	v_max_i32_e32 v81, 0, v20
	v_fmac_f32_e32 v82, v52, v81
	v_mfma_f32_32x32x16_bf16 v[0:15], v[36:39], v[88:91], v[0:15]
	v_max_i32_e32 v81, 0, v21
	v_fmac_f32_e32 v82, v53, v81
	v_max_i32_e32 v81, 0, v22
	v_fmac_f32_e32 v82, v54, v81
	v_max_i32_e32 v81, 0, v23
	v_fmac_f32_e32 v82, v55, v81
	v_max_i32_e32 v81, 0, v24
	v_fmac_f32_e32 v82, v56, v81
	v_max_i32_e32 v81, 0, v25
	v_fmac_f32_e32 v82, v57, v81
	v_mfma_f32_32x32x16_bf16 v[0:15], v[40:43], v[96:99], v[0:15]
	v_max_i32_e32 v81, 0, v26
	v_fmac_f32_e32 v82, v58, v81
	v_max_i32_e32 v81, 0, v27
	v_fmac_f32_e32 v82, v59, v81
	v_max_i32_e32 v81, 0, v28
	v_fmac_f32_e32 v82, v60, v81
	v_max_i32_e32 v81, 0, v29
	v_fmac_f32_e32 v82, v61, v81
	v_mfma_f32_32x32x16_bf16 v[0:15], v[44:47], v[104:107], v[0:15]
	v_max_i32_e32 v81, 0, v30
	v_fmac_f32_e32 v82, v62, v81
	v_max_i32_e32 v81, 0, v31
	v_cmp_gt_i32_e32 vcc, v167, v203
	v_fmac_f32_e32 v82, v63, v81
	s_and_b64 vcc, s[52:53], vcc
	v_cndmask_b32_e32 v235, v82, v197, vcc
	s_branch .Lixj77

.Lixj77:
	s_waitcnt lgkmcnt(0)
	ds_read_b128 v[96:99], v134 offset:0x3600
	ds_read_b128 v[88:91], v134 offset:0x3620
	ds_read_b128 v[80:83], v134 offset:0x3640
	ds_read_b128 v[104:107], v134 offset:0x3660
	s_cmpk_gt_u32 s95, 0x53
	s_cselect_b64 s[64:65], -1, 0
	s_cmpk_lt_u32 s95, 0x54
	s_cbranch_scc1 .LBB0_1368
	v_mfma_f32_32x32x16_bf16 v[16:31], v[32:35], v[108:111], 0
	v_cndmask_b32_e64 v109, 0, 1, s[66:67]
	v_cmp_ne_u32_e64 s[52:53], 1, v109
	s_andn2_b64 vcc, exec, s[66:67]
	v_max_i32_e32 v109, 0, v0
	v_fma_f32 v110, v48, v109, 0
	v_max_i32_e32 v109, 0, v1
	v_fmac_f32_e32 v110, v49, v109
	v_max_i32_e32 v109, 0, v2
	v_fmac_f32_e32 v110, v50, v109
	v_max_i32_e32 v109, 0, v3
	v_fmac_f32_e32 v110, v51, v109
	v_max_i32_e32 v109, 0, v4
	v_fmac_f32_e32 v110, v52, v109
	v_mfma_f32_32x32x16_bf16 v[16:31], v[36:39], v[100:103], v[16:31]
	v_max_i32_e32 v109, 0, v5
	v_fmac_f32_e32 v110, v53, v109
	v_max_i32_e32 v109, 0, v6
	v_fmac_f32_e32 v110, v54, v109
	v_max_i32_e32 v109, 0, v7
	v_fmac_f32_e32 v110, v55, v109
	v_max_i32_e32 v109, 0, v8
	v_fmac_f32_e32 v110, v56, v109
	v_max_i32_e32 v109, 0, v9
	v_fmac_f32_e32 v110, v57, v109
	v_mfma_f32_32x32x16_bf16 v[16:31], v[40:43], v[92:95], v[16:31]
	v_max_i32_e32 v109, 0, v10
	v_fmac_f32_e32 v110, v58, v109
	v_max_i32_e32 v109, 0, v11
	v_fmac_f32_e32 v110, v59, v109
	v_max_i32_e32 v109, 0, v12
	v_fmac_f32_e32 v110, v60, v109
	v_max_i32_e32 v109, 0, v13
	v_fmac_f32_e32 v110, v61, v109
	v_mfma_f32_32x32x16_bf16 v[16:31], v[44:47], v[84:87], v[16:31]
	v_max_i32_e32 v109, 0, v14
	s_cmp_eq_u32 s58, 42
	v_fmac_f32_e32 v110, v62, v109
	v_max_i32_e32 v109, 0, v15
	s_cselect_b64 s[66:67], -1, 0
	v_cmp_gt_i32_e32 vcc, v168, v203
	v_fmac_f32_e32 v110, v63, v109
	s_and_b64 vcc, s[66:67], vcc
	v_cndmask_b32_e32 v236, v110, v197, vcc
	s_branch .LBB0_1370

.LBB0_1372:
	s_waitcnt lgkmcnt(0)
	ds_read_b128 v[100:103], v134 offset:0x4800
	ds_read_b128 v[92:95], v134 offset:0x4820
	ds_read_b128 v[84:87], v134 offset:0x4840
	ds_read_b128 v[108:111], v134 offset:0x4860
	s_cmpk_gt_u32 s95, 0x55
	s_cselect_b64 s[66:67], -1, 0
	s_cmpk_lt_u32 s95, 0x56
	s_cbranch_scc1 .LBB0_1374
	v_mfma_f32_32x32x16_bf16 v[0:15], v[32:35], v[96:99], 0
	v_cndmask_b32_e64 v97, 0, 1, s[64:65]
	v_cmp_ne_u32_e64 s[52:53], 1, v97
	s_andn2_b64 vcc, exec, s[64:65]
	v_max_i32_e32 v97, 0, v16
	v_fma_f32 v98, v48, v97, 0
	v_max_i32_e32 v97, 0, v17
	v_fmac_f32_e32 v98, v49, v97
	v_max_i32_e32 v97, 0, v18
	v_fmac_f32_e32 v98, v50, v97
	v_max_i32_e32 v97, 0, v19
	v_fmac_f32_e32 v98, v51, v97
	v_max_i32_e32 v97, 0, v20
	v_fmac_f32_e32 v98, v52, v97
	v_mfma_f32_32x32x16_bf16 v[0:15], v[36:39], v[88:91], v[0:15]
	v_max_i32_e32 v97, 0, v21
	v_fmac_f32_e32 v98, v53, v97
	v_max_i32_e32 v97, 0, v22
	v_fmac_f32_e32 v98, v54, v97
	v_max_i32_e32 v97, 0, v23
	v_fmac_f32_e32 v98, v55, v97
	v_max_i32_e32 v97, 0, v24
	v_fmac_f32_e32 v98, v56, v97
	v_max_i32_e32 v97, 0, v25
	v_fmac_f32_e32 v98, v57, v97
	v_mfma_f32_32x32x16_bf16 v[0:15], v[40:43], v[80:83], v[0:15]
	v_max_i32_e32 v97, 0, v26
	v_fmac_f32_e32 v98, v58, v97
	v_max_i32_e32 v97, 0, v27
	v_fmac_f32_e32 v98, v59, v97
	v_max_i32_e32 v97, 0, v28
	v_fmac_f32_e32 v98, v60, v97
	v_max_i32_e32 v97, 0, v29
	v_fmac_f32_e32 v98, v61, v97
	v_mfma_f32_32x32x16_bf16 v[0:15], v[44:47], v[104:107], v[0:15]
	v_max_i32_e32 v97, 0, v30
	s_cmp_eq_u32 s58, 43
	v_fmac_f32_e32 v98, v62, v97
	v_max_i32_e32 v97, 0, v31
	s_cselect_b64 s[64:65], -1, 0
	v_cmp_gt_i32_e32 vcc, v169, v203
	v_fmac_f32_e32 v98, v63, v97
	s_and_b64 vcc, s[64:65], vcc
	v_cndmask_b32_e32 v237, v98, v197, vcc
	s_branch .LBB0_1376

.LBB0_1378:
	s_waitcnt lgkmcnt(0)
	ds_read_b128 v[96:99], v134 offset:0x5a00
	ds_read_b128 v[88:91], v134 offset:0x5a20
	ds_read_b128 v[80:83], v134 offset:0x5a40
	ds_read_b128 v[104:107], v134 offset:0x5a60
	s_cmpk_gt_u32 s95, 0x57
	s_cselect_b64 s[64:65], -1, 0
	s_cmpk_lt_u32 s95, 0x58
	s_cbranch_scc1 .LBB0_1380
	v_mfma_f32_32x32x16_bf16 v[16:31], v[32:35], v[100:103], 0
	v_cndmask_b32_e64 v101, 0, 1, s[66:67]
	v_cmp_ne_u32_e64 s[52:53], 1, v101
	s_andn2_b64 vcc, exec, s[66:67]
	v_max_i32_e32 v101, 0, v0
	v_fma_f32 v102, v48, v101, 0
	v_max_i32_e32 v101, 0, v1
	v_fmac_f32_e32 v102, v49, v101
	v_max_i32_e32 v101, 0, v2
	v_fmac_f32_e32 v102, v50, v101
	v_max_i32_e32 v101, 0, v3
	v_fmac_f32_e32 v102, v51, v101
	v_max_i32_e32 v101, 0, v4
	v_fmac_f32_e32 v102, v52, v101
	v_mfma_f32_32x32x16_bf16 v[16:31], v[36:39], v[92:95], v[16:31]
	v_max_i32_e32 v101, 0, v5
	v_fmac_f32_e32 v102, v53, v101
	v_max_i32_e32 v101, 0, v6
	v_fmac_f32_e32 v102, v54, v101
	v_max_i32_e32 v101, 0, v7
	v_fmac_f32_e32 v102, v55, v101
	v_max_i32_e32 v101, 0, v8
	v_fmac_f32_e32 v102, v56, v101
	v_max_i32_e32 v101, 0, v9
	v_fmac_f32_e32 v102, v57, v101
	v_mfma_f32_32x32x16_bf16 v[16:31], v[40:43], v[84:87], v[16:31]
	v_max_i32_e32 v101, 0, v10
	v_fmac_f32_e32 v102, v58, v101
	v_max_i32_e32 v101, 0, v11
	v_fmac_f32_e32 v102, v59, v101
	v_max_i32_e32 v101, 0, v12
	v_fmac_f32_e32 v102, v60, v101
	v_max_i32_e32 v101, 0, v13
	v_fmac_f32_e32 v102, v61, v101
	v_mfma_f32_32x32x16_bf16 v[16:31], v[44:47], v[108:111], v[16:31]
	v_max_i32_e32 v101, 0, v14
	s_cmp_eq_u32 s58, 44
	v_fmac_f32_e32 v102, v62, v101
	v_max_i32_e32 v101, 0, v15
	s_cselect_b64 s[66:67], -1, 0
	v_cmp_gt_i32_e32 vcc, v170, v203
	v_fmac_f32_e32 v102, v63, v101
	s_and_b64 vcc, s[66:67], vcc
	v_cndmask_b32_e32 v238, v102, v197, vcc
	s_branch .LBB0_1382

.LBB0_1384:
	s_waitcnt lgkmcnt(0)
	ds_read_b128 v[100:103], v134 offset:0x6c00
	ds_read_b128 v[92:95], v134 offset:0x6c20
	ds_read_b128 v[84:87], v134 offset:0x6c40
	ds_read_b128 v[108:111], v134 offset:0x6c60
	s_cmpk_gt_u32 s95, 0x59
	s_cselect_b64 s[66:67], -1, 0
	s_cmpk_lt_u32 s95, 0x5a
	s_cbranch_scc1 .LBB0_1386
	v_mfma_f32_32x32x16_bf16 v[0:15], v[32:35], v[96:99], 0
	v_cndmask_b32_e64 v97, 0, 1, s[64:65]
	v_cmp_ne_u32_e64 s[52:53], 1, v97
	s_andn2_b64 vcc, exec, s[64:65]
	v_max_i32_e32 v97, 0, v16
	v_fma_f32 v98, v48, v97, 0
	v_max_i32_e32 v97, 0, v17
	v_fmac_f32_e32 v98, v49, v97
	v_max_i32_e32 v97, 0, v18
	v_fmac_f32_e32 v98, v50, v97
	v_max_i32_e32 v97, 0, v19
	v_fmac_f32_e32 v98, v51, v97
	v_max_i32_e32 v97, 0, v20
	v_fmac_f32_e32 v98, v52, v97
	v_mfma_f32_32x32x16_bf16 v[0:15], v[36:39], v[88:91], v[0:15]
	v_max_i32_e32 v97, 0, v21
	v_fmac_f32_e32 v98, v53, v97
	v_max_i32_e32 v97, 0, v22
	v_fmac_f32_e32 v98, v54, v97
	v_max_i32_e32 v97, 0, v23
	v_fmac_f32_e32 v98, v55, v97
	v_max_i32_e32 v97, 0, v24
	v_fmac_f32_e32 v98, v56, v97
	v_max_i32_e32 v97, 0, v25
	v_fmac_f32_e32 v98, v57, v97
	v_mfma_f32_32x32x16_bf16 v[0:15], v[40:43], v[80:83], v[0:15]
	v_max_i32_e32 v97, 0, v26
	v_fmac_f32_e32 v98, v58, v97
	v_max_i32_e32 v97, 0, v27
	v_fmac_f32_e32 v98, v59, v97
	v_max_i32_e32 v97, 0, v28
	v_fmac_f32_e32 v98, v60, v97
	v_max_i32_e32 v97, 0, v29
	v_fmac_f32_e32 v98, v61, v97
	v_mfma_f32_32x32x16_bf16 v[0:15], v[44:47], v[104:107], v[0:15]
	v_max_i32_e32 v97, 0, v30
	s_cmp_eq_u32 s58, 45
	v_fmac_f32_e32 v98, v62, v97
	v_max_i32_e32 v97, 0, v31
	s_cselect_b64 s[64:65], -1, 0
	v_cmp_gt_i32_e32 vcc, v171, v203
	v_fmac_f32_e32 v98, v63, v97
	s_and_b64 vcc, s[64:65], vcc
	v_cndmask_b32_e32 v239, v98, v197, vcc
	s_branch .LBB0_1388

.LBB0_1390:
	s_waitcnt lgkmcnt(0)
	ds_read_b128 v[96:99], v134 offset:0x7e00
	ds_read_b128 v[88:91], v134 offset:0x7e20
	ds_read_b128 v[80:83], v134 offset:0x7e40
	ds_read_b128 v[104:107], v134 offset:0x7e60
	s_cmpk_gt_u32 s95, 0x5b
	s_cselect_b64 s[64:65], -1, 0
	s_cmpk_lt_u32 s95, 0x5c
	s_cbranch_scc1 .LBB0_1392
	v_mfma_f32_32x32x16_bf16 v[16:31], v[32:35], v[100:103], 0
	v_cndmask_b32_e64 v101, 0, 1, s[66:67]
	v_cmp_ne_u32_e64 s[52:53], 1, v101
	s_andn2_b64 vcc, exec, s[66:67]
	v_max_i32_e32 v101, 0, v0
	v_fma_f32 v102, v48, v101, 0
	v_max_i32_e32 v101, 0, v1
	v_fmac_f32_e32 v102, v49, v101
	v_max_i32_e32 v101, 0, v2
	v_fmac_f32_e32 v102, v50, v101
	v_max_i32_e32 v101, 0, v3
	v_fmac_f32_e32 v102, v51, v101
	v_max_i32_e32 v101, 0, v4
	v_fmac_f32_e32 v102, v52, v101
	v_mfma_f32_32x32x16_bf16 v[16:31], v[36:39], v[92:95], v[16:31]
	v_max_i32_e32 v101, 0, v5
	v_fmac_f32_e32 v102, v53, v101
	v_max_i32_e32 v101, 0, v6
	v_fmac_f32_e32 v102, v54, v101
	v_max_i32_e32 v101, 0, v7
	v_fmac_f32_e32 v102, v55, v101
	v_max_i32_e32 v101, 0, v8
	v_fmac_f32_e32 v102, v56, v101
	v_max_i32_e32 v101, 0, v9
	v_fmac_f32_e32 v102, v57, v101
	v_mfma_f32_32x32x16_bf16 v[16:31], v[40:43], v[84:87], v[16:31]
	v_max_i32_e32 v101, 0, v10
	v_fmac_f32_e32 v102, v58, v101
	v_max_i32_e32 v101, 0, v11
	v_fmac_f32_e32 v102, v59, v101
	v_max_i32_e32 v101, 0, v12
	v_fmac_f32_e32 v102, v60, v101
	v_max_i32_e32 v101, 0, v13
	v_fmac_f32_e32 v102, v61, v101
	v_mfma_f32_32x32x16_bf16 v[16:31], v[44:47], v[108:111], v[16:31]
	v_max_i32_e32 v101, 0, v14
	s_cmp_eq_u32 s58, 46
	v_fmac_f32_e32 v102, v62, v101
	v_max_i32_e32 v101, 0, v15
	s_cselect_b64 s[66:67], -1, 0
	v_cmp_gt_i32_e32 vcc, v172, v203
	v_fmac_f32_e32 v102, v63, v101
	s_and_b64 vcc, s[66:67], vcc
	v_cndmask_b32_e32 v240, v102, v197, vcc
	s_branch .LBB0_1394

.LBB0_1396:
	s_waitcnt lgkmcnt(0)
	s_cmpk_lt_u32 s95, 0x5e
	s_cbranch_scc1 .LBB0_1398
	v_mfma_f32_32x32x16_bf16 v[0:15], v[32:35], v[96:99], 0
	v_cndmask_b32_e64 v97, 0, 1, s[64:65]
	v_cmp_ne_u32_e64 s[52:53], 1, v97
	s_andn2_b64 vcc, exec, s[64:65]
	v_max_i32_e32 v97, 0, v16
	v_fma_f32 v98, v48, v97, 0
	v_max_i32_e32 v97, 0, v17
	v_fmac_f32_e32 v98, v49, v97
	v_max_i32_e32 v97, 0, v18
	v_fmac_f32_e32 v98, v50, v97
	v_max_i32_e32 v97, 0, v19
	v_fmac_f32_e32 v98, v51, v97
	v_max_i32_e32 v97, 0, v20
	v_fmac_f32_e32 v98, v52, v97
	v_mfma_f32_32x32x16_bf16 v[0:15], v[36:39], v[88:91], v[0:15]
	v_max_i32_e32 v97, 0, v21
	v_fmac_f32_e32 v98, v53, v97
	v_max_i32_e32 v97, 0, v22
	v_fmac_f32_e32 v98, v54, v97
	v_max_i32_e32 v97, 0, v23
	v_fmac_f32_e32 v98, v55, v97
	v_max_i32_e32 v97, 0, v24
	v_fmac_f32_e32 v98, v56, v97
	v_max_i32_e32 v97, 0, v25
	v_fmac_f32_e32 v98, v57, v97
	v_mfma_f32_32x32x16_bf16 v[0:15], v[40:43], v[80:83], v[0:15]
	v_max_i32_e32 v97, 0, v26
	v_fmac_f32_e32 v98, v58, v97
	v_max_i32_e32 v97, 0, v27
	v_fmac_f32_e32 v98, v59, v97
	v_max_i32_e32 v97, 0, v28
	v_fmac_f32_e32 v98, v60, v97
	v_max_i32_e32 v97, 0, v29
	v_fmac_f32_e32 v98, v61, v97
	v_mfma_f32_32x32x16_bf16 v[0:15], v[44:47], v[104:107], v[0:15]
	v_max_i32_e32 v97, 0, v30
	s_cmp_eq_u32 s58, 47
	v_fmac_f32_e32 v98, v62, v97
	v_max_i32_e32 v97, 0, v31
	s_cselect_b64 s[64:65], -1, 0
	v_cmp_gt_i32_e32 vcc, v173, v203
	v_fmac_f32_e32 v98, v63, v97
	s_and_b64 vcc, s[64:65], vcc
	v_cndmask_b32_e32 v241, v98, v197, vcc
	s_branch .LBB0_1400

.LBB0_1408:
	ds_read_b128 v[16:19], v131 offset:0
	ds_read_b128 v[80:83], v131 offset:32
	ds_read_b128 v[84:87], v131 offset:64
	ds_read_b128 v[92:95], v131 offset:0x60
	v_max_i32_e32 v88, 0, v0
	s_waitcnt lgkmcnt(0)
	v_max_i32_e32 v89, 0, v1
	v_mfma_f32_32x32x16_bf16 v[16:31], v[32:35], v[16:19], 0
	v_fma_f32 v242, v48, v88, 0
	v_max_i32_e32 v90, 0, v2
	v_fmac_f32_e32 v242, v49, v89
	v_max_i32_e32 v91, 0, v3
	v_fmac_f32_e32 v242, v50, v90
	v_max_i32_e32 v96, 0, v4
	v_fmac_f32_e32 v242, v51, v91
	v_mfma_f32_32x32x16_bf16 v[16:31], v[36:39], v[80:83], v[16:31]
	v_max_i32_e32 v97, 0, v5
	v_fmac_f32_e32 v242, v52, v96
	v_max_i32_e32 v98, 0, v6
	v_fmac_f32_e32 v242, v53, v97
	v_max_i32_e32 v99, 0, v7
	v_fmac_f32_e32 v242, v54, v98
	v_max_i32_e32 v100, 0, v8
	v_mfma_f32_32x32x16_bf16 v[16:31], v[40:43], v[84:87], v[16:31]
	v_fmac_f32_e32 v242, v55, v99
	v_max_i32_e32 v101, 0, v9
	v_fmac_f32_e32 v242, v56, v100
	v_max_i32_e32 v102, 0, v10
	v_fmac_f32_e32 v242, v57, v101
	v_max_i32_e32 v103, 0, v11
	v_fmac_f32_e32 v242, v58, v102
	v_fmac_f32_e32 v242, v59, v103
	v_max_i32_e32 v84, 0, v12
	ds_read_b128 v[80:83], v131 offset:0x1200
	v_fmac_f32_e32 v242, v60, v84
	v_max_i32_e32 v84, 0, v13
	ds_read_b128 v[88:91], v131 offset:0x1220
	v_fmac_f32_e32 v242, v61, v84
	v_max_i32_e32 v84, 0, v14
	ds_read_b128 v[96:99], v131 offset:0x1240
	v_fmac_f32_e32 v242, v62, v84
	v_max_i32_e32 v84, 0, v15
	ds_read_b128 v[104:107], v131 offset:0x1260
	v_mfma_f32_32x32x16_bf16 v[16:31], v[44:47], v[92:95], v[16:31]
	v_fmac_f32_e32 v242, v63, v84
	s_waitcnt lgkmcnt(0)
	ds_read_b128 v[108:111], v131 offset:0x2400
	ds_read_b128 v[100:103], v131 offset:0x2420
	ds_read_b128 v[92:95], v131 offset:0x2440
	ds_read_b128 v[84:87], v131 offset:0x2460
	s_cmp_eq_u32 s58, 49
	s_cselect_b64 s[52:53], -1, 0
	s_cmp_lg_u32 s58, 49
	s_cselect_b64 s[64:65], -1, 0
	s_and_b64 vcc, exec, s[52:53]
	s_cbranch_vccnz .LBB0_1410
	v_mfma_f32_32x32x16_bf16 v[0:15], v[32:35], v[80:83], 0
	v_max_i32_e32 v81, 0, v16
	v_fma_f32 v82, v48, v81, 0
	v_max_i32_e32 v81, 0, v17
	v_fmac_f32_e32 v82, v49, v81
	v_max_i32_e32 v81, 0, v18
	v_fmac_f32_e32 v82, v50, v81
	v_max_i32_e32 v81, 0, v19
	v_fmac_f32_e32 v82, v51, v81
	v_max_i32_e32 v81, 0, v20
	v_fmac_f32_e32 v82, v52, v81
	v_mfma_f32_32x32x16_bf16 v[0:15], v[36:39], v[88:91], v[0:15]
	v_max_i32_e32 v81, 0, v21
	v_fmac_f32_e32 v82, v53, v81
	v_max_i32_e32 v81, 0, v22
	v_fmac_f32_e32 v82, v54, v81
	v_max_i32_e32 v81, 0, v23
	v_fmac_f32_e32 v82, v55, v81
	v_max_i32_e32 v81, 0, v24
	v_fmac_f32_e32 v82, v56, v81
	v_max_i32_e32 v81, 0, v25
	v_fmac_f32_e32 v82, v57, v81
	v_mfma_f32_32x32x16_bf16 v[0:15], v[40:43], v[96:99], v[0:15]
	v_max_i32_e32 v81, 0, v26
	v_fmac_f32_e32 v82, v58, v81
	v_max_i32_e32 v81, 0, v27
	v_fmac_f32_e32 v82, v59, v81
	v_max_i32_e32 v81, 0, v28
	v_fmac_f32_e32 v82, v60, v81
	v_max_i32_e32 v81, 0, v29
	v_fmac_f32_e32 v82, v61, v81
	v_mfma_f32_32x32x16_bf16 v[0:15], v[44:47], v[104:107], v[0:15]
	v_max_i32_e32 v81, 0, v30
	v_fmac_f32_e32 v82, v62, v81
	v_max_i32_e32 v81, 0, v31
	v_cmp_gt_i32_e32 vcc, v175, v203
	v_fmac_f32_e32 v82, v63, v81
	s_and_b64 vcc, s[52:53], vcc
	v_cndmask_b32_e32 v243, v82, v197, vcc
	s_branch .Lixj70

.Lixj70:
	s_waitcnt lgkmcnt(0)
	ds_read_b128 v[96:99], v131 offset:0x3600
	ds_read_b128 v[88:91], v131 offset:0x3620
	ds_read_b128 v[80:83], v131 offset:0x3640
	ds_read_b128 v[104:107], v131 offset:0x3660
	s_cmpk_gt_u32 s95, 0x63
	s_cselect_b64 s[60:61], -1, 0
	s_cmpk_lt_u32 s95, 0x64
	s_cbranch_scc1 .LBB0_1412
	v_mfma_f32_32x32x16_bf16 v[16:31], v[32:35], v[108:111], 0
	v_cndmask_b32_e64 v109, 0, 1, s[64:65]
	v_cmp_ne_u32_e64 s[52:53], 1, v109
	s_andn2_b64 vcc, exec, s[64:65]
	v_max_i32_e32 v109, 0, v0
	v_fma_f32 v110, v48, v109, 0
	v_max_i32_e32 v109, 0, v1
	v_fmac_f32_e32 v110, v49, v109
	v_max_i32_e32 v109, 0, v2
	v_fmac_f32_e32 v110, v50, v109
	v_max_i32_e32 v109, 0, v3
	v_fmac_f32_e32 v110, v51, v109
	v_max_i32_e32 v109, 0, v4
	v_fmac_f32_e32 v110, v52, v109
	v_mfma_f32_32x32x16_bf16 v[16:31], v[36:39], v[100:103], v[16:31]
	v_max_i32_e32 v109, 0, v5
	v_fmac_f32_e32 v110, v53, v109
	v_max_i32_e32 v109, 0, v6
	v_fmac_f32_e32 v110, v54, v109
	v_max_i32_e32 v109, 0, v7
	v_fmac_f32_e32 v110, v55, v109
	v_max_i32_e32 v109, 0, v8
	v_fmac_f32_e32 v110, v56, v109
	v_max_i32_e32 v109, 0, v9
	v_fmac_f32_e32 v110, v57, v109
	v_mfma_f32_32x32x16_bf16 v[16:31], v[40:43], v[92:95], v[16:31]
	v_max_i32_e32 v109, 0, v10
	v_fmac_f32_e32 v110, v58, v109
	v_max_i32_e32 v109, 0, v11
	v_fmac_f32_e32 v110, v59, v109
	v_max_i32_e32 v109, 0, v12
	v_fmac_f32_e32 v110, v60, v109
	v_max_i32_e32 v109, 0, v13
	v_fmac_f32_e32 v110, v61, v109
	v_mfma_f32_32x32x16_bf16 v[16:31], v[44:47], v[84:87], v[16:31]
	v_max_i32_e32 v109, 0, v14
	s_cmp_eq_u32 s58, 50
	v_fmac_f32_e32 v110, v62, v109
	v_max_i32_e32 v109, 0, v15
	s_cselect_b64 s[64:65], -1, 0
	v_cmp_gt_i32_e32 vcc, v176, v203
	v_fmac_f32_e32 v110, v63, v109
	s_and_b64 vcc, s[64:65], vcc
	v_cndmask_b32_e32 v244, v110, v197, vcc
	s_branch .LBB0_1414

.LBB0_1416:
	s_waitcnt lgkmcnt(0)
	ds_read_b128 v[100:103], v131 offset:0x4800
	ds_read_b128 v[92:95], v131 offset:0x4820
	ds_read_b128 v[84:87], v131 offset:0x4840
	ds_read_b128 v[108:111], v131 offset:0x4860
	s_cmpk_gt_u32 s95, 0x65
	s_cselect_b64 s[64:65], -1, 0
	s_cmpk_lt_u32 s95, 0x66
	s_cbranch_scc1 .LBB0_1418
	v_mfma_f32_32x32x16_bf16 v[0:15], v[32:35], v[96:99], 0
	v_cndmask_b32_e64 v97, 0, 1, s[60:61]
	v_cmp_ne_u32_e64 s[52:53], 1, v97
	s_andn2_b64 vcc, exec, s[60:61]
	v_max_i32_e32 v97, 0, v16
	v_fma_f32 v98, v48, v97, 0
	v_max_i32_e32 v97, 0, v17
	v_fmac_f32_e32 v98, v49, v97
	v_max_i32_e32 v97, 0, v18
	v_fmac_f32_e32 v98, v50, v97
	v_max_i32_e32 v97, 0, v19
	v_fmac_f32_e32 v98, v51, v97
	v_max_i32_e32 v97, 0, v20
	v_fmac_f32_e32 v98, v52, v97
	v_mfma_f32_32x32x16_bf16 v[0:15], v[36:39], v[88:91], v[0:15]
	v_max_i32_e32 v97, 0, v21
	v_fmac_f32_e32 v98, v53, v97
	v_max_i32_e32 v97, 0, v22
	v_fmac_f32_e32 v98, v54, v97
	v_max_i32_e32 v97, 0, v23
	v_fmac_f32_e32 v98, v55, v97
	v_max_i32_e32 v97, 0, v24
	v_fmac_f32_e32 v98, v56, v97
	v_max_i32_e32 v97, 0, v25
	v_fmac_f32_e32 v98, v57, v97
	v_mfma_f32_32x32x16_bf16 v[0:15], v[40:43], v[80:83], v[0:15]
	v_max_i32_e32 v97, 0, v26
	v_fmac_f32_e32 v98, v58, v97
	v_max_i32_e32 v97, 0, v27
	v_fmac_f32_e32 v98, v59, v97
	v_max_i32_e32 v97, 0, v28
	v_fmac_f32_e32 v98, v60, v97
	v_max_i32_e32 v97, 0, v29
	v_fmac_f32_e32 v98, v61, v97
	v_mfma_f32_32x32x16_bf16 v[0:15], v[44:47], v[104:107], v[0:15]
	v_max_i32_e32 v97, 0, v30
	s_cmp_eq_u32 s58, 51
	v_fmac_f32_e32 v98, v62, v97
	v_max_i32_e32 v97, 0, v31
	s_cselect_b64 s[60:61], -1, 0
	v_cmp_gt_i32_e32 vcc, v177, v203
	v_fmac_f32_e32 v98, v63, v97
	s_and_b64 vcc, s[60:61], vcc
	v_cndmask_b32_e32 v245, v98, v197, vcc
	s_branch .LBB0_1420

.LBB0_1422:
	s_waitcnt lgkmcnt(0)
	ds_read_b128 v[96:99], v131 offset:0x5a00
	ds_read_b128 v[88:91], v131 offset:0x5a20
	ds_read_b128 v[80:83], v131 offset:0x5a40
	ds_read_b128 v[104:107], v131 offset:0x5a60
	s_cmpk_gt_u32 s95, 0x67
	s_cselect_b64 s[60:61], -1, 0
	s_cmpk_lt_u32 s95, 0x68
	s_cbranch_scc1 .LBB0_1424
	v_mfma_f32_32x32x16_bf16 v[16:31], v[32:35], v[100:103], 0
	v_cndmask_b32_e64 v101, 0, 1, s[64:65]
	v_cmp_ne_u32_e64 s[52:53], 1, v101
	s_andn2_b64 vcc, exec, s[64:65]
	v_max_i32_e32 v101, 0, v0
	v_fma_f32 v102, v48, v101, 0
	v_max_i32_e32 v101, 0, v1
	v_fmac_f32_e32 v102, v49, v101
	v_max_i32_e32 v101, 0, v2
	v_fmac_f32_e32 v102, v50, v101
	v_max_i32_e32 v101, 0, v3
	v_fmac_f32_e32 v102, v51, v101
	v_max_i32_e32 v101, 0, v4
	v_fmac_f32_e32 v102, v52, v101
	v_mfma_f32_32x32x16_bf16 v[16:31], v[36:39], v[92:95], v[16:31]
	v_max_i32_e32 v101, 0, v5
	v_fmac_f32_e32 v102, v53, v101
	v_max_i32_e32 v101, 0, v6
	v_fmac_f32_e32 v102, v54, v101
	v_max_i32_e32 v101, 0, v7
	v_fmac_f32_e32 v102, v55, v101
	v_max_i32_e32 v101, 0, v8
	v_fmac_f32_e32 v102, v56, v101
	v_max_i32_e32 v101, 0, v9
	v_fmac_f32_e32 v102, v57, v101
	v_mfma_f32_32x32x16_bf16 v[16:31], v[40:43], v[84:87], v[16:31]
	v_max_i32_e32 v101, 0, v10
	v_fmac_f32_e32 v102, v58, v101
	v_max_i32_e32 v101, 0, v11
	v_fmac_f32_e32 v102, v59, v101
	v_max_i32_e32 v101, 0, v12
	v_fmac_f32_e32 v102, v60, v101
	v_max_i32_e32 v101, 0, v13
	v_fmac_f32_e32 v102, v61, v101
	v_mfma_f32_32x32x16_bf16 v[16:31], v[44:47], v[108:111], v[16:31]
	v_max_i32_e32 v101, 0, v14
	s_cmp_eq_u32 s58, 52
	v_fmac_f32_e32 v102, v62, v101
	v_max_i32_e32 v101, 0, v15
	s_cselect_b64 s[64:65], -1, 0
	v_cmp_gt_i32_e32 vcc, v178, v203
	v_fmac_f32_e32 v102, v63, v101
	s_and_b64 vcc, s[64:65], vcc
	v_cndmask_b32_e32 v246, v102, v197, vcc
	s_branch .LBB0_1426

.LBB0_1428:
	s_waitcnt lgkmcnt(0)
	ds_read_b128 v[100:103], v131 offset:0x6c00
	ds_read_b128 v[92:95], v131 offset:0x6c20
	ds_read_b128 v[84:87], v131 offset:0x6c40
	ds_read_b128 v[108:111], v131 offset:0x6c60
	s_cmpk_gt_u32 s95, 0x69
	s_cselect_b64 s[64:65], -1, 0
	s_cmpk_lt_u32 s95, 0x6a
	s_cbranch_scc1 .LBB0_1430
	v_mfma_f32_32x32x16_bf16 v[0:15], v[32:35], v[96:99], 0
	v_cndmask_b32_e64 v97, 0, 1, s[60:61]
	v_cmp_ne_u32_e64 s[52:53], 1, v97
	s_andn2_b64 vcc, exec, s[60:61]
	v_max_i32_e32 v97, 0, v16
	v_fma_f32 v98, v48, v97, 0
	v_max_i32_e32 v97, 0, v17
	v_fmac_f32_e32 v98, v49, v97
	v_max_i32_e32 v97, 0, v18
	v_fmac_f32_e32 v98, v50, v97
	v_max_i32_e32 v97, 0, v19
	v_fmac_f32_e32 v98, v51, v97
	v_max_i32_e32 v97, 0, v20
	v_fmac_f32_e32 v98, v52, v97
	v_mfma_f32_32x32x16_bf16 v[0:15], v[36:39], v[88:91], v[0:15]
	v_max_i32_e32 v97, 0, v21
	v_fmac_f32_e32 v98, v53, v97
	v_max_i32_e32 v97, 0, v22
	v_fmac_f32_e32 v98, v54, v97
	v_max_i32_e32 v97, 0, v23
	v_fmac_f32_e32 v98, v55, v97
	v_max_i32_e32 v97, 0, v24
	v_fmac_f32_e32 v98, v56, v97
	v_max_i32_e32 v97, 0, v25
	v_fmac_f32_e32 v98, v57, v97
	v_mfma_f32_32x32x16_bf16 v[0:15], v[40:43], v[80:83], v[0:15]
	v_max_i32_e32 v97, 0, v26
	v_fmac_f32_e32 v98, v58, v97
	v_max_i32_e32 v97, 0, v27
	v_fmac_f32_e32 v98, v59, v97
	v_max_i32_e32 v97, 0, v28
	v_fmac_f32_e32 v98, v60, v97
	v_max_i32_e32 v97, 0, v29
	v_fmac_f32_e32 v98, v61, v97
	v_mfma_f32_32x32x16_bf16 v[0:15], v[44:47], v[104:107], v[0:15]
	v_max_i32_e32 v97, 0, v30
	s_cmp_eq_u32 s58, 53
	v_fmac_f32_e32 v98, v62, v97
	v_max_i32_e32 v97, 0, v31
	s_cselect_b64 s[60:61], -1, 0
	v_cmp_gt_i32_e32 vcc, v179, v203
	v_fmac_f32_e32 v98, v63, v97
	s_and_b64 vcc, s[60:61], vcc
	v_cndmask_b32_e32 v247, v98, v197, vcc
	s_branch .LBB0_1432

.LBB0_1434:
	s_waitcnt lgkmcnt(0)
	ds_read_b128 v[96:99], v131 offset:0x7e00
	ds_read_b128 v[88:91], v131 offset:0x7e20
	ds_read_b128 v[80:83], v131 offset:0x7e40
	ds_read_b128 v[104:107], v131 offset:0x7e60
	s_cmpk_gt_u32 s95, 0x6b
	s_cselect_b64 s[60:61], -1, 0
	s_cmpk_lt_u32 s95, 0x6c
	s_cbranch_scc1 .LBB0_1436
	v_mfma_f32_32x32x16_bf16 v[16:31], v[32:35], v[100:103], 0
	v_cndmask_b32_e64 v101, 0, 1, s[64:65]
	v_cmp_ne_u32_e64 s[52:53], 1, v101
	s_andn2_b64 vcc, exec, s[64:65]
	v_max_i32_e32 v101, 0, v0
	v_fma_f32 v102, v48, v101, 0
	v_max_i32_e32 v101, 0, v1
	v_fmac_f32_e32 v102, v49, v101
	v_max_i32_e32 v101, 0, v2
	v_fmac_f32_e32 v102, v50, v101
	v_max_i32_e32 v101, 0, v3
	v_fmac_f32_e32 v102, v51, v101
	v_max_i32_e32 v101, 0, v4
	v_fmac_f32_e32 v102, v52, v101
	v_mfma_f32_32x32x16_bf16 v[16:31], v[36:39], v[92:95], v[16:31]
	v_max_i32_e32 v101, 0, v5
	v_fmac_f32_e32 v102, v53, v101
	v_max_i32_e32 v101, 0, v6
	v_fmac_f32_e32 v102, v54, v101
	v_max_i32_e32 v101, 0, v7
	v_fmac_f32_e32 v102, v55, v101
	v_max_i32_e32 v101, 0, v8
	v_fmac_f32_e32 v102, v56, v101
	v_max_i32_e32 v101, 0, v9
	v_fmac_f32_e32 v102, v57, v101
	v_mfma_f32_32x32x16_bf16 v[16:31], v[40:43], v[84:87], v[16:31]
	v_max_i32_e32 v101, 0, v10
	v_fmac_f32_e32 v102, v58, v101
	v_max_i32_e32 v101, 0, v11
	v_fmac_f32_e32 v102, v59, v101
	v_max_i32_e32 v101, 0, v12
	v_fmac_f32_e32 v102, v60, v101
	v_max_i32_e32 v101, 0, v13
	v_fmac_f32_e32 v102, v61, v101
	v_mfma_f32_32x32x16_bf16 v[16:31], v[44:47], v[108:111], v[16:31]
	v_max_i32_e32 v101, 0, v14
	s_cmp_eq_u32 s58, 54
	v_fmac_f32_e32 v102, v62, v101
	v_max_i32_e32 v101, 0, v15
	s_cselect_b64 s[64:65], -1, 0
	v_cmp_gt_i32_e32 vcc, v180, v203
	v_fmac_f32_e32 v102, v63, v101
	s_and_b64 vcc, s[64:65], vcc
	v_cndmask_b32_e32 v248, v102, v197, vcc
	s_branch .LBB0_1438

.LBB0_1440:
	s_waitcnt lgkmcnt(0)
	s_cmpk_lt_u32 s95, 0x6e
	s_cbranch_scc1 .LBB0_1442
	v_mfma_f32_32x32x16_bf16 v[0:15], v[32:35], v[96:99], 0
	v_cndmask_b32_e64 v97, 0, 1, s[60:61]
	v_cmp_ne_u32_e64 s[52:53], 1, v97
	s_andn2_b64 vcc, exec, s[60:61]
	v_max_i32_e32 v97, 0, v16
	v_fma_f32 v98, v48, v97, 0
	v_max_i32_e32 v97, 0, v17
	v_fmac_f32_e32 v98, v49, v97
	v_max_i32_e32 v97, 0, v18
	v_fmac_f32_e32 v98, v50, v97
	v_max_i32_e32 v97, 0, v19
	v_fmac_f32_e32 v98, v51, v97
	v_max_i32_e32 v97, 0, v20
	v_fmac_f32_e32 v98, v52, v97
	v_mfma_f32_32x32x16_bf16 v[0:15], v[36:39], v[88:91], v[0:15]
	v_max_i32_e32 v97, 0, v21
	v_fmac_f32_e32 v98, v53, v97
	v_max_i32_e32 v97, 0, v22
	v_fmac_f32_e32 v98, v54, v97
	v_max_i32_e32 v97, 0, v23
	v_fmac_f32_e32 v98, v55, v97
	v_max_i32_e32 v97, 0, v24
	v_fmac_f32_e32 v98, v56, v97
	v_max_i32_e32 v97, 0, v25
	v_fmac_f32_e32 v98, v57, v97
	v_mfma_f32_32x32x16_bf16 v[0:15], v[40:43], v[80:83], v[0:15]
	v_max_i32_e32 v97, 0, v26
	v_fmac_f32_e32 v98, v58, v97
	v_max_i32_e32 v97, 0, v27
	v_fmac_f32_e32 v98, v59, v97
	v_max_i32_e32 v97, 0, v28
	v_fmac_f32_e32 v98, v60, v97
	v_max_i32_e32 v97, 0, v29
	v_fmac_f32_e32 v98, v61, v97
	v_mfma_f32_32x32x16_bf16 v[0:15], v[44:47], v[104:107], v[0:15]
	v_max_i32_e32 v97, 0, v30
	s_cmp_eq_u32 s58, 55
	v_fmac_f32_e32 v98, v62, v97
	v_max_i32_e32 v97, 0, v31
	s_cselect_b64 s[60:61], -1, 0
	v_cmp_gt_i32_e32 vcc, v181, v203
	v_fmac_f32_e32 v98, v63, v97
	s_and_b64 vcc, s[60:61], vcc
	v_cndmask_b32_e32 v249, v98, v197, vcc
	s_branch .LBB0_1444

.LBB0_1450:
	ds_read_b128 v[16:19], v134 offset:0
	ds_read_b128 v[80:83], v134 offset:32
	ds_read_b128 v[84:87], v134 offset:64
	ds_read_b128 v[92:95], v134 offset:0x60
	v_max_i32_e32 v88, 0, v0
	s_waitcnt lgkmcnt(0)
	v_max_i32_e32 v89, 0, v1
	v_mfma_f32_32x32x16_bf16 v[16:31], v[32:35], v[16:19], 0
	v_fma_f32 v250, v48, v88, 0
	v_max_i32_e32 v90, 0, v2
	v_fmac_f32_e32 v250, v49, v89
	v_max_i32_e32 v91, 0, v3
	v_fmac_f32_e32 v250, v50, v90
	v_max_i32_e32 v96, 0, v4
	v_fmac_f32_e32 v250, v51, v91
	v_mfma_f32_32x32x16_bf16 v[16:31], v[36:39], v[80:83], v[16:31]
	v_max_i32_e32 v97, 0, v5
	v_fmac_f32_e32 v250, v52, v96
	v_max_i32_e32 v98, 0, v6
	v_fmac_f32_e32 v250, v53, v97
	v_max_i32_e32 v99, 0, v7
	v_fmac_f32_e32 v250, v54, v98
	v_max_i32_e32 v100, 0, v8
	v_mfma_f32_32x32x16_bf16 v[16:31], v[40:43], v[84:87], v[16:31]
	v_fmac_f32_e32 v250, v55, v99
	v_max_i32_e32 v101, 0, v9
	v_fmac_f32_e32 v250, v56, v100
	v_max_i32_e32 v102, 0, v10
	v_fmac_f32_e32 v250, v57, v101
	v_max_i32_e32 v103, 0, v11
	v_fmac_f32_e32 v250, v58, v102
	v_fmac_f32_e32 v250, v59, v103
	v_max_i32_e32 v84, 0, v12
	ds_read_b128 v[80:83], v134 offset:0x1200
	v_fmac_f32_e32 v250, v60, v84
	v_max_i32_e32 v84, 0, v13
	ds_read_b128 v[88:91], v134 offset:0x1220
	v_fmac_f32_e32 v250, v61, v84
	v_max_i32_e32 v84, 0, v14
	ds_read_b128 v[96:99], v134 offset:0x1240
	v_fmac_f32_e32 v250, v62, v84
	v_max_i32_e32 v84, 0, v15
	ds_read_b128 v[104:107], v134 offset:0x1260
	v_mfma_f32_32x32x16_bf16 v[16:31], v[44:47], v[92:95], v[16:31]
	v_fmac_f32_e32 v250, v63, v84
	s_waitcnt lgkmcnt(0)
	ds_read_b128 v[108:111], v134 offset:0x2400
	ds_read_b128 v[100:103], v134 offset:0x2420
	ds_read_b128 v[92:95], v134 offset:0x2440
	ds_read_b128 v[84:87], v134 offset:0x2460
	s_cmp_eq_u32 s58, 57
	s_cselect_b64 s[52:53], -1, 0
	s_cmp_lg_u32 s58, 57
	s_cselect_b64 s[62:63], -1, 0
	s_and_b64 vcc, exec, s[52:53]
	s_cbranch_vccnz .LBB0_1452
	v_mfma_f32_32x32x16_bf16 v[0:15], v[32:35], v[80:83], 0
	v_max_i32_e32 v81, 0, v16
	v_fma_f32 v82, v48, v81, 0
	v_max_i32_e32 v81, 0, v17
	v_fmac_f32_e32 v82, v49, v81
	v_max_i32_e32 v81, 0, v18
	v_fmac_f32_e32 v82, v50, v81
	v_max_i32_e32 v81, 0, v19
	v_fmac_f32_e32 v82, v51, v81
	v_max_i32_e32 v81, 0, v20
	v_fmac_f32_e32 v82, v52, v81
	v_mfma_f32_32x32x16_bf16 v[0:15], v[36:39], v[88:91], v[0:15]
	v_max_i32_e32 v81, 0, v21
	v_fmac_f32_e32 v82, v53, v81
	v_max_i32_e32 v81, 0, v22
	v_fmac_f32_e32 v82, v54, v81
	v_max_i32_e32 v81, 0, v23
	v_fmac_f32_e32 v82, v55, v81
	v_max_i32_e32 v81, 0, v24
	v_fmac_f32_e32 v82, v56, v81
	v_max_i32_e32 v81, 0, v25
	v_fmac_f32_e32 v82, v57, v81
	v_mfma_f32_32x32x16_bf16 v[0:15], v[40:43], v[96:99], v[0:15]
	v_max_i32_e32 v81, 0, v26
	v_fmac_f32_e32 v82, v58, v81
	v_max_i32_e32 v81, 0, v27
	v_fmac_f32_e32 v82, v59, v81
	v_max_i32_e32 v81, 0, v28
	v_fmac_f32_e32 v82, v60, v81
	v_max_i32_e32 v81, 0, v29
	v_fmac_f32_e32 v82, v61, v81
	v_mfma_f32_32x32x16_bf16 v[0:15], v[44:47], v[104:107], v[0:15]
	v_max_i32_e32 v81, 0, v30
	v_fmac_f32_e32 v82, v62, v81
	v_max_i32_e32 v81, 0, v31
	v_cmp_gt_i32_e32 vcc, v183, v203
	v_fmac_f32_e32 v82, v63, v81
	s_and_b64 vcc, s[52:53], vcc
	v_cndmask_b32_e32 v251, v82, v197, vcc
	s_branch .Lixj63

.Lixj63:
	s_waitcnt lgkmcnt(0)
	ds_read_b128 v[96:99], v134 offset:0x3600
	ds_read_b128 v[88:91], v134 offset:0x3620
	ds_read_b128 v[80:83], v134 offset:0x3640
	ds_read_b128 v[104:107], v134 offset:0x3660
	s_cmpk_gt_u32 s95, 0x73
	s_cselect_b64 s[60:61], -1, 0
	s_cmpk_lt_u32 s95, 0x74
	s_cbranch_scc1 .LBB0_1454
	v_mfma_f32_32x32x16_bf16 v[16:31], v[32:35], v[108:111], 0
	v_cndmask_b32_e64 v109, 0, 1, s[62:63]
	v_cmp_ne_u32_e64 s[52:53], 1, v109
	s_andn2_b64 vcc, exec, s[62:63]
	v_max_i32_e32 v109, 0, v0
	v_fma_f32 v110, v48, v109, 0
	v_max_i32_e32 v109, 0, v1
	v_fmac_f32_e32 v110, v49, v109
	v_max_i32_e32 v109, 0, v2
	v_fmac_f32_e32 v110, v50, v109
	v_max_i32_e32 v109, 0, v3
	v_fmac_f32_e32 v110, v51, v109
	v_max_i32_e32 v109, 0, v4
	v_fmac_f32_e32 v110, v52, v109
	v_mfma_f32_32x32x16_bf16 v[16:31], v[36:39], v[100:103], v[16:31]
	v_max_i32_e32 v109, 0, v5
	v_fmac_f32_e32 v110, v53, v109
	v_max_i32_e32 v109, 0, v6
	v_fmac_f32_e32 v110, v54, v109
	v_max_i32_e32 v109, 0, v7
	v_fmac_f32_e32 v110, v55, v109
	v_max_i32_e32 v109, 0, v8
	v_fmac_f32_e32 v110, v56, v109
	v_max_i32_e32 v109, 0, v9
	v_fmac_f32_e32 v110, v57, v109
	v_mfma_f32_32x32x16_bf16 v[16:31], v[40:43], v[92:95], v[16:31]
	v_max_i32_e32 v109, 0, v10
	v_fmac_f32_e32 v110, v58, v109
	v_max_i32_e32 v109, 0, v11
	v_fmac_f32_e32 v110, v59, v109
	v_max_i32_e32 v109, 0, v12
	v_fmac_f32_e32 v110, v60, v109
	v_max_i32_e32 v109, 0, v13
	v_fmac_f32_e32 v110, v61, v109
	v_mfma_f32_32x32x16_bf16 v[16:31], v[44:47], v[84:87], v[16:31]
	v_max_i32_e32 v109, 0, v14
	s_cmp_eq_u32 s58, 58
	v_fmac_f32_e32 v110, v62, v109
	v_max_i32_e32 v109, 0, v15
	s_cselect_b64 s[62:63], -1, 0
	v_cmp_gt_i32_e32 vcc, v184, v203
	v_fmac_f32_e32 v110, v63, v109
	s_and_b64 vcc, s[62:63], vcc
	v_cndmask_b32_e32 v252, v110, v197, vcc
	s_branch .LBB0_1456

.LBB0_1458:
	s_waitcnt lgkmcnt(0)
	ds_read_b128 v[100:103], v134 offset:0x4800
	ds_read_b128 v[92:95], v134 offset:0x4820
	ds_read_b128 v[84:87], v134 offset:0x4840
	ds_read_b128 v[108:111], v134 offset:0x4860
	s_cmpk_gt_u32 s95, 0x75
	s_cselect_b64 s[62:63], -1, 0
	s_cmpk_lt_u32 s95, 0x76
	s_cbranch_scc1 .LBB0_1460
	v_mfma_f32_32x32x16_bf16 v[0:15], v[32:35], v[96:99], 0
	v_cndmask_b32_e64 v97, 0, 1, s[60:61]
	v_cmp_ne_u32_e64 s[52:53], 1, v97
	s_andn2_b64 vcc, exec, s[60:61]
	v_max_i32_e32 v97, 0, v16
	v_fma_f32 v98, v48, v97, 0
	v_max_i32_e32 v97, 0, v17
	v_fmac_f32_e32 v98, v49, v97
	v_max_i32_e32 v97, 0, v18
	v_fmac_f32_e32 v98, v50, v97
	v_max_i32_e32 v97, 0, v19
	v_fmac_f32_e32 v98, v51, v97
	v_max_i32_e32 v97, 0, v20
	v_fmac_f32_e32 v98, v52, v97
	v_mfma_f32_32x32x16_bf16 v[0:15], v[36:39], v[88:91], v[0:15]
	v_max_i32_e32 v97, 0, v21
	v_fmac_f32_e32 v98, v53, v97
	v_max_i32_e32 v97, 0, v22
	v_fmac_f32_e32 v98, v54, v97
	v_max_i32_e32 v97, 0, v23
	v_fmac_f32_e32 v98, v55, v97
	v_max_i32_e32 v97, 0, v24
	v_fmac_f32_e32 v98, v56, v97
	v_max_i32_e32 v97, 0, v25
	v_fmac_f32_e32 v98, v57, v97
	v_mfma_f32_32x32x16_bf16 v[0:15], v[40:43], v[80:83], v[0:15]
	v_max_i32_e32 v97, 0, v26
	v_fmac_f32_e32 v98, v58, v97
	v_max_i32_e32 v97, 0, v27
	v_fmac_f32_e32 v98, v59, v97
	v_max_i32_e32 v97, 0, v28
	v_fmac_f32_e32 v98, v60, v97
	v_max_i32_e32 v97, 0, v29
	v_fmac_f32_e32 v98, v61, v97
	v_mfma_f32_32x32x16_bf16 v[0:15], v[44:47], v[104:107], v[0:15]
	v_max_i32_e32 v97, 0, v30
	s_cmp_eq_u32 s58, 59
	v_fmac_f32_e32 v98, v62, v97
	v_max_i32_e32 v97, 0, v31
	s_cselect_b64 s[60:61], -1, 0
	v_cmp_gt_i32_e32 vcc, v185, v203
	v_fmac_f32_e32 v98, v63, v97
	s_and_b64 vcc, s[60:61], vcc
	v_cndmask_b32_e32 v253, v98, v197, vcc
	s_branch .LBB0_1462

.LBB0_1464:
	s_waitcnt lgkmcnt(0)
	ds_read_b128 v[96:99], v134 offset:0x5a00
	ds_read_b128 v[88:91], v134 offset:0x5a20
	ds_read_b128 v[80:83], v134 offset:0x5a40
	ds_read_b128 v[104:107], v134 offset:0x5a60
	s_cmpk_gt_u32 s95, 0x77
	s_cselect_b64 s[60:61], -1, 0
	s_cmpk_lt_u32 s95, 0x78
	s_cbranch_scc1 .LBB0_1466
	v_mfma_f32_32x32x16_bf16 v[16:31], v[32:35], v[100:103], 0
	v_cndmask_b32_e64 v101, 0, 1, s[62:63]
	v_cmp_ne_u32_e64 s[52:53], 1, v101
	s_andn2_b64 vcc, exec, s[62:63]
	v_max_i32_e32 v101, 0, v0
	v_fma_f32 v102, v48, v101, 0
	v_max_i32_e32 v101, 0, v1
	v_fmac_f32_e32 v102, v49, v101
	v_max_i32_e32 v101, 0, v2
	v_fmac_f32_e32 v102, v50, v101
	v_max_i32_e32 v101, 0, v3
	v_fmac_f32_e32 v102, v51, v101
	v_max_i32_e32 v101, 0, v4
	v_fmac_f32_e32 v102, v52, v101
	v_mfma_f32_32x32x16_bf16 v[16:31], v[36:39], v[92:95], v[16:31]
	v_max_i32_e32 v101, 0, v5
	v_fmac_f32_e32 v102, v53, v101
	v_max_i32_e32 v101, 0, v6
	v_fmac_f32_e32 v102, v54, v101
	v_max_i32_e32 v101, 0, v7
	v_fmac_f32_e32 v102, v55, v101
	v_max_i32_e32 v101, 0, v8
	v_fmac_f32_e32 v102, v56, v101
	v_max_i32_e32 v101, 0, v9
	v_fmac_f32_e32 v102, v57, v101
	v_mfma_f32_32x32x16_bf16 v[16:31], v[40:43], v[84:87], v[16:31]
	v_max_i32_e32 v101, 0, v10
	v_fmac_f32_e32 v102, v58, v101
	v_max_i32_e32 v101, 0, v11
	v_fmac_f32_e32 v102, v59, v101
	v_max_i32_e32 v101, 0, v12
	v_fmac_f32_e32 v102, v60, v101
	v_max_i32_e32 v101, 0, v13
	v_fmac_f32_e32 v102, v61, v101
	v_mfma_f32_32x32x16_bf16 v[16:31], v[44:47], v[108:111], v[16:31]
	v_max_i32_e32 v101, 0, v14
	s_cmp_eq_u32 s58, 60
	v_fmac_f32_e32 v102, v62, v101
	v_max_i32_e32 v101, 0, v15
	s_cselect_b64 s[62:63], -1, 0
	v_cmp_gt_i32_e32 vcc, v186, v203
	v_fmac_f32_e32 v102, v63, v101
	s_and_b64 vcc, s[62:63], vcc
	v_cndmask_b32_e32 v215, v102, v197, vcc
	s_branch .LBB0_1468

.LBB0_1470:
	s_waitcnt lgkmcnt(0)
	ds_read_b128 v[100:103], v134 offset:0x6c00
	ds_read_b128 v[92:95], v134 offset:0x6c20
	ds_read_b128 v[84:87], v134 offset:0x6c40
	ds_read_b128 v[108:111], v134 offset:0x6c60
	s_cmpk_gt_u32 s95, 0x79
	s_cselect_b64 s[62:63], -1, 0
	s_cmpk_lt_u32 s95, 0x7a
	s_cbranch_scc1 .LBB0_1472
	v_mfma_f32_32x32x16_bf16 v[0:15], v[32:35], v[96:99], 0
	v_cndmask_b32_e64 v97, 0, 1, s[60:61]
	v_cmp_ne_u32_e64 s[52:53], 1, v97
	s_andn2_b64 vcc, exec, s[60:61]
	v_max_i32_e32 v97, 0, v16
	v_fma_f32 v98, v48, v97, 0
	v_max_i32_e32 v97, 0, v17
	v_fmac_f32_e32 v98, v49, v97
	v_max_i32_e32 v97, 0, v18
	v_fmac_f32_e32 v98, v50, v97
	v_max_i32_e32 v97, 0, v19
	v_fmac_f32_e32 v98, v51, v97
	v_max_i32_e32 v97, 0, v20
	v_fmac_f32_e32 v98, v52, v97
	v_mfma_f32_32x32x16_bf16 v[0:15], v[36:39], v[88:91], v[0:15]
	v_max_i32_e32 v97, 0, v21
	v_fmac_f32_e32 v98, v53, v97
	v_max_i32_e32 v97, 0, v22
	v_fmac_f32_e32 v98, v54, v97
	v_max_i32_e32 v97, 0, v23
	v_fmac_f32_e32 v98, v55, v97
	v_max_i32_e32 v97, 0, v24
	v_fmac_f32_e32 v98, v56, v97
	v_max_i32_e32 v97, 0, v25
	v_fmac_f32_e32 v98, v57, v97
	v_mfma_f32_32x32x16_bf16 v[0:15], v[40:43], v[80:83], v[0:15]
	v_max_i32_e32 v97, 0, v26
	v_fmac_f32_e32 v98, v58, v97
	v_max_i32_e32 v97, 0, v27
	v_fmac_f32_e32 v98, v59, v97
	v_max_i32_e32 v97, 0, v28
	v_fmac_f32_e32 v98, v60, v97
	v_max_i32_e32 v97, 0, v29
	v_fmac_f32_e32 v98, v61, v97
	v_mfma_f32_32x32x16_bf16 v[0:15], v[44:47], v[104:107], v[0:15]
	v_max_i32_e32 v97, 0, v30
	s_cmp_eq_u32 s58, 61
	v_fmac_f32_e32 v98, v62, v97
	v_max_i32_e32 v97, 0, v31
	s_cselect_b64 s[60:61], -1, 0
	v_cmp_gt_i32_e32 vcc, v187, v203
	v_fmac_f32_e32 v98, v63, v97
	s_and_b64 vcc, s[60:61], vcc
	v_cndmask_b32_e32 v133, v98, v197, vcc
	s_branch .LBB0_1474

.LBB0_1476:
	s_waitcnt lgkmcnt(0)
	ds_read_b128 v[96:99], v134 offset:0x7e00
	ds_read_b128 v[88:91], v134 offset:0x7e20
	ds_read_b128 v[80:83], v134 offset:0x7e40
	ds_read_b128 v[104:107], v134 offset:0x7e60
	s_cmpk_gt_u32 s95, 0x7b
	s_cselect_b64 s[60:61], -1, 0
	s_cmpk_lt_u32 s95, 0x7c
	s_cbranch_scc1 .LBB0_1478
	v_mfma_f32_32x32x16_bf16 v[16:31], v[32:35], v[100:103], 0
	v_cndmask_b32_e64 v101, 0, 1, s[62:63]
	v_cmp_ne_u32_e64 s[52:53], 1, v101
	s_andn2_b64 vcc, exec, s[62:63]
	v_max_i32_e32 v101, 0, v0
	v_fma_f32 v102, v48, v101, 0
	v_max_i32_e32 v101, 0, v1
	v_fmac_f32_e32 v102, v49, v101
	v_max_i32_e32 v101, 0, v2
	v_fmac_f32_e32 v102, v50, v101
	v_max_i32_e32 v101, 0, v3
	v_fmac_f32_e32 v102, v51, v101
	v_max_i32_e32 v101, 0, v4
	v_fmac_f32_e32 v102, v52, v101
	v_mfma_f32_32x32x16_bf16 v[16:31], v[36:39], v[92:95], v[16:31]
	v_max_i32_e32 v101, 0, v5
	v_fmac_f32_e32 v102, v53, v101
	v_max_i32_e32 v101, 0, v6
	v_fmac_f32_e32 v102, v54, v101
	v_max_i32_e32 v101, 0, v7
	v_fmac_f32_e32 v102, v55, v101
	v_max_i32_e32 v101, 0, v8
	v_fmac_f32_e32 v102, v56, v101
	v_max_i32_e32 v101, 0, v9
	v_fmac_f32_e32 v102, v57, v101
	v_mfma_f32_32x32x16_bf16 v[16:31], v[40:43], v[84:87], v[16:31]
	v_max_i32_e32 v101, 0, v10
	v_fmac_f32_e32 v102, v58, v101
	v_max_i32_e32 v101, 0, v11
	v_fmac_f32_e32 v102, v59, v101
	v_max_i32_e32 v101, 0, v12
	v_fmac_f32_e32 v102, v60, v101
	v_max_i32_e32 v101, 0, v13
	v_fmac_f32_e32 v102, v61, v101
	v_mfma_f32_32x32x16_bf16 v[16:31], v[44:47], v[108:111], v[16:31]
	v_max_i32_e32 v101, 0, v14
	s_cmp_eq_u32 s58, 62
	v_fmac_f32_e32 v102, v62, v101
	v_max_i32_e32 v101, 0, v15
	s_cselect_b64 s[62:63], -1, 0
	v_cmp_gt_i32_e32 vcc, v188, v203
	v_fmac_f32_e32 v102, v63, v101
	s_and_b64 vcc, s[62:63], vcc
	v_cndmask_b32_e32 v84, v102, v197, vcc
	s_branch .LBB0_1480

.LBB0_1482:
	s_waitcnt lgkmcnt(0)
	s_cmpk_lt_u32 s95, 0x7e
	s_cbranch_scc1 .LBB0_1484
	v_mfma_f32_32x32x16_bf16 v[0:15], v[32:35], v[96:99], 0
	v_cndmask_b32_e64 v97, 0, 1, s[60:61]
	v_cmp_ne_u32_e64 s[52:53], 1, v97
	s_andn2_b64 vcc, exec, s[60:61]
	v_max_i32_e32 v97, 0, v16
	v_fma_f32 v98, v48, v97, 0
	v_max_i32_e32 v97, 0, v17
	v_fmac_f32_e32 v98, v49, v97
	v_max_i32_e32 v97, 0, v18
	v_fmac_f32_e32 v98, v50, v97
	v_max_i32_e32 v97, 0, v19
	v_fmac_f32_e32 v98, v51, v97
	v_max_i32_e32 v97, 0, v20
	v_fmac_f32_e32 v98, v52, v97
	v_mfma_f32_32x32x16_bf16 v[0:15], v[36:39], v[88:91], v[0:15]
	v_max_i32_e32 v97, 0, v21
	v_fmac_f32_e32 v98, v53, v97
	v_max_i32_e32 v97, 0, v22
	v_fmac_f32_e32 v98, v54, v97
	v_max_i32_e32 v97, 0, v23
	v_fmac_f32_e32 v98, v55, v97
	v_max_i32_e32 v97, 0, v24
	v_fmac_f32_e32 v98, v56, v97
	v_max_i32_e32 v97, 0, v25
	v_fmac_f32_e32 v98, v57, v97
	v_mfma_f32_32x32x16_bf16 v[0:15], v[40:43], v[80:83], v[0:15]
	v_max_i32_e32 v97, 0, v26
	v_fmac_f32_e32 v98, v58, v97
	v_max_i32_e32 v97, 0, v27
	v_fmac_f32_e32 v98, v59, v97
	v_max_i32_e32 v97, 0, v28
	v_fmac_f32_e32 v98, v60, v97
	v_max_i32_e32 v97, 0, v29
	v_fmac_f32_e32 v98, v61, v97
	v_mfma_f32_32x32x16_bf16 v[0:15], v[44:47], v[104:107], v[0:15]
	v_max_i32_e32 v97, 0, v30
	s_cmp_eq_u32 s58, 63
	v_fmac_f32_e32 v98, v62, v97
	v_max_i32_e32 v97, 0, v31
	s_cselect_b64 s[60:61], -1, 0
	v_cmp_gt_i32_e32 vcc, v189, v203
	v_fmac_f32_e32 v98, v63, v97
	s_and_b64 vcc, s[60:61], vcc
	v_cndmask_b32_e32 v80, v98, v197, vcc
	s_branch .LBB0_1486

.LBB0_1744:
	ds_read_b128 v[0:3], v131 offset:0
	ds_read_b128 v[4:7], v131 offset:32
	ds_read_b128 v[10:13], v131 offset:64
	ds_read_b128 v[80:83], v131 offset:0x60
	s_cmp_lt_u32 s94, 2
	s_waitcnt lgkmcnt(0)
	ds_read_b128 v[108:111], v131 offset:0x1200
	ds_read_b128 v[104:107], v131 offset:0x1220
	ds_read_b128 v[100:103], v131 offset:0x1240
	ds_read_b128 v[96:99], v131 offset:0x1260
	s_cselect_b64 s[50:51], -1, 0
	v_mfma_f32_32x32x16_bf16 v[16:31], v[32:35], v[0:3], 0
	s_cmp_gt_u32 s94, 1
	v_mov_b32_e32 v0, 0
	v_mov_b32_e32 v1, 0
	v_mov_b32_e32 v2, 0
	v_mov_b32_e32 v3, 0
	v_mov_b32_e32 v8, 0
	v_mov_b32_e32 v9, 0
	v_mfma_f32_32x32x16_bf16 v[16:31], v[36:39], v[4:7], v[16:31]
	v_mov_b32_e32 v4, 0
	v_mov_b32_e32 v5, 0
	v_mov_b32_e32 v6, 0
	v_mov_b32_e32 v7, 0
	s_cselect_b64 s[52:53], -1, 0
	s_and_b64 vcc, exec, s[50:51]
	v_mov_b32_e32 v14, 0
	v_mfma_f32_32x32x16_bf16 v[16:31], v[40:43], v[10:13], v[16:31]
	v_mov_b32_e32 v10, 0
	v_mov_b32_e32 v11, 0
	v_mov_b32_e32 v12, 0
	v_mov_b32_e32 v13, 0
	v_mov_b32_e32 v15, 0
	v_mfma_f32_32x32x16_bf16 v[16:31], v[44:47], v[80:83], v[16:31]
	s_waitcnt lgkmcnt(0)
	ds_read_b128 v[92:95], v131 offset:0x2400
	ds_read_b128 v[88:91], v131 offset:0x2420
	ds_read_b128 v[84:87], v131 offset:0x2440
	ds_read_b128 v[80:83], v131 offset:0x2460
	s_cbranch_vccnz .LBB0_1746
	v_mfma_f32_32x32x16_bf16 v[0:15], v[32:35], v[108:111], 0
	s_nop 5
	v_max_i32_e32 v109, 0, v16
	v_fma_f32 v110, v48, v109, 0
	v_max_i32_e32 v109, 0, v17
	v_fmac_f32_e32 v110, v49, v109
	v_max_i32_e32 v109, 0, v18
	v_fmac_f32_e32 v110, v50, v109
	v_max_i32_e32 v109, 0, v19
	v_fmac_f32_e32 v110, v51, v109
	v_max_i32_e32 v109, 0, v20
	v_fmac_f32_e32 v110, v52, v109
	v_mfma_f32_32x32x16_bf16 v[0:15], v[36:39], v[104:107], v[0:15]
	v_max_i32_e32 v109, 0, v21
	v_fmac_f32_e32 v110, v53, v109
	v_max_i32_e32 v109, 0, v22
	v_fmac_f32_e32 v110, v54, v109
	v_max_i32_e32 v109, 0, v23
	v_fmac_f32_e32 v110, v55, v109
	v_max_i32_e32 v109, 0, v24
	v_fmac_f32_e32 v110, v56, v109
	v_max_i32_e32 v109, 0, v25
	v_fmac_f32_e32 v110, v57, v109
	v_mfma_f32_32x32x16_bf16 v[0:15], v[40:43], v[100:103], v[0:15]
	v_max_i32_e32 v109, 0, v26
	s_ashr_i32 s1, s60, 5
	v_fmac_f32_e32 v110, v58, v109
	v_max_i32_e32 v109, 0, v27
	s_lshl_b32 s0, s94, 4
	s_and_b32 s95, s1, -2
	v_fmac_f32_e32 v110, v59, v109
	v_max_i32_e32 v109, 0, v28
	s_add_i32 s95, s95, s0
	v_fmac_f32_e32 v110, v60, v109
	v_max_i32_e32 v109, 0, v29
	v_or_b32_e32 v203, s95, v129
	v_fmac_f32_e32 v110, v61, v109
	v_mfma_f32_32x32x16_bf16 v[0:15], v[44:47], v[96:99], v[0:15]
	v_max_i32_e32 v109, 0, v30
	v_fmac_f32_e32 v110, v62, v109
	v_max_i32_e32 v109, 0, v31
	v_cmp_gt_i32_e32 vcc, v130, v203
	v_fmac_f32_e32 v110, v63, v109
	s_and_b64 vcc, s[50:51], vcc
	v_cndmask_b32_e32 v200, v110, v197, vcc
	s_branch .Lixj56

.Lixj56:
	s_waitcnt lgkmcnt(0)
	ds_read_b128 v[104:107], v131 offset:0x3600
	ds_read_b128 v[100:103], v131 offset:0x3620
	ds_read_b128 v[96:99], v131 offset:0x3640
	ds_read_b128 v[108:111], v131 offset:0x3660
	s_cmp_gt_u32 s94, 3
	s_cselect_b64 s[66:67], -1, 0
	s_cmp_lt_u32 s94, 4
	s_cbranch_scc1 .LBB0_1748
	v_mfma_f32_32x32x16_bf16 v[16:31], v[32:35], v[92:95], 0
	s_lshr_b32 s60, s94, 1
	v_cndmask_b32_e64 v93, 0, 1, s[52:53]
	s_add_i32 s60, s60, 1
	v_cmp_ne_u32_e64 s[50:51], 1, v93
	s_andn2_b64 vcc, exec, s[52:53]
	v_max_i32_e32 v93, 0, v0
	v_fma_f32 v94, v48, v93, 0
	v_max_i32_e32 v93, 0, v1
	v_fmac_f32_e32 v94, v49, v93
	v_max_i32_e32 v93, 0, v2
	v_fmac_f32_e32 v94, v50, v93
	v_max_i32_e32 v93, 0, v3
	v_fmac_f32_e32 v94, v51, v93
	v_max_i32_e32 v93, 0, v4
	v_fmac_f32_e32 v94, v52, v93
	v_mfma_f32_32x32x16_bf16 v[16:31], v[36:39], v[88:91], v[16:31]
	v_max_i32_e32 v93, 0, v5
	v_fmac_f32_e32 v94, v53, v93
	v_max_i32_e32 v93, 0, v6
	v_fmac_f32_e32 v94, v54, v93
	v_max_i32_e32 v93, 0, v7
	v_fmac_f32_e32 v94, v55, v93
	v_max_i32_e32 v93, 0, v8
	v_fmac_f32_e32 v94, v56, v93
	v_max_i32_e32 v93, 0, v9
	v_fmac_f32_e32 v94, v57, v93
	v_mfma_f32_32x32x16_bf16 v[16:31], v[40:43], v[84:87], v[16:31]
	v_max_i32_e32 v93, 0, v10
	v_fmac_f32_e32 v94, v58, v93
	v_max_i32_e32 v93, 0, v11
	v_fmac_f32_e32 v94, v59, v93
	v_max_i32_e32 v93, 0, v12
	v_fmac_f32_e32 v94, v60, v93
	v_max_i32_e32 v93, 0, v13
	v_fmac_f32_e32 v94, v61, v93
	v_mfma_f32_32x32x16_bf16 v[16:31], v[44:47], v[80:83], v[16:31]
	v_max_i32_e32 v93, 0, v14
	v_fmac_f32_e32 v94, v62, v93
	v_max_i32_e32 v93, 0, v15
	v_fmac_f32_e32 v94, v63, v93
	s_cmp_eq_u32 s60, 2
	v_or_b32_e32 v93, 32, v130
	s_cselect_b64 s[0:1], -1, 0
	v_cmp_gt_i32_e32 vcc, v93, v203
	s_and_b64 vcc, s[0:1], vcc
	s_nop 0
	v_cndmask_b32_e32 v201, v94, v197, vcc
	s_branch .LBB0_1750

.LBB0_1752:
	s_waitcnt lgkmcnt(0)
	ds_read_b128 v[112:115], v131 offset:0x4800
	ds_read_b128 v[88:91], v131 offset:0x4820
	ds_read_b128 v[80:83], v131 offset:0x4840
	ds_read_b128 v[116:119], v131 offset:0x4860
	s_cmp_gt_u32 s94, 5
	s_cselect_b64 s[68:69], -1, 0
	s_cmp_lt_u32 s94, 6
	s_cbranch_scc1 .LBB0_1754
	v_mfma_f32_32x32x16_bf16 v[0:15], v[32:35], v[104:107], 0
	v_cndmask_b32_e64 v105, 0, 1, s[66:67]
	v_cmp_ne_u32_e64 s[52:53], 1, v105
	s_andn2_b64 vcc, exec, s[66:67]
	v_max_i32_e32 v105, 0, v16
	v_fma_f32 v106, v48, v105, 0
	v_max_i32_e32 v105, 0, v17
	v_fmac_f32_e32 v106, v49, v105
	v_max_i32_e32 v105, 0, v18
	v_fmac_f32_e32 v106, v50, v105
	v_max_i32_e32 v105, 0, v19
	v_fmac_f32_e32 v106, v51, v105
	v_max_i32_e32 v105, 0, v20
	v_fmac_f32_e32 v106, v52, v105
	v_mfma_f32_32x32x16_bf16 v[0:15], v[36:39], v[100:103], v[0:15]
	v_max_i32_e32 v105, 0, v21
	v_fmac_f32_e32 v106, v53, v105
	v_max_i32_e32 v105, 0, v22
	v_fmac_f32_e32 v106, v54, v105
	v_max_i32_e32 v105, 0, v23
	v_fmac_f32_e32 v106, v55, v105
	v_max_i32_e32 v105, 0, v24
	v_fmac_f32_e32 v106, v56, v105
	v_max_i32_e32 v105, 0, v25
	v_fmac_f32_e32 v106, v57, v105
	v_mfma_f32_32x32x16_bf16 v[0:15], v[40:43], v[96:99], v[0:15]
	v_max_i32_e32 v105, 0, v26
	v_fmac_f32_e32 v106, v58, v105
	v_max_i32_e32 v105, 0, v27
	v_fmac_f32_e32 v106, v59, v105
	v_max_i32_e32 v105, 0, v28
	v_fmac_f32_e32 v106, v60, v105
	v_max_i32_e32 v105, 0, v29
	v_fmac_f32_e32 v106, v61, v105
	v_mfma_f32_32x32x16_bf16 v[0:15], v[44:47], v[108:111], v[0:15]
	v_max_i32_e32 v105, 0, v30
	v_fmac_f32_e32 v106, v62, v105
	v_max_i32_e32 v105, 0, v31
	v_fmac_f32_e32 v106, v63, v105
	s_cmp_eq_u32 s60, 3
	v_or_b32_e32 v105, 64, v130
	s_cselect_b64 s[0:1], -1, 0
	v_cmp_gt_i32_e32 vcc, v105, v203
	s_and_b64 vcc, s[0:1], vcc
	s_nop 0
	v_cndmask_b32_e32 v202, v106, v197, vcc
	s_branch .LBB0_1756

.LBB0_1758:
	s_waitcnt lgkmcnt(0)
	ds_read_b128 v[96:99], v131 offset:0x5a00
	ds_read_b128 v[92:95], v131 offset:0x5a20
	ds_read_b128 v[84:87], v131 offset:0x5a40
	ds_read_b128 v[104:107], v131 offset:0x5a60
	s_cmp_gt_u32 s94, 7
	s_cselect_b64 s[66:67], -1, 0
	s_cmp_lt_u32 s94, 8
	s_cbranch_scc1 .LBB0_1760
	v_mfma_f32_32x32x16_bf16 v[16:31], v[32:35], v[112:115], 0
	v_cndmask_b32_e64 v113, 0, 1, s[68:69]
	v_cmp_ne_u32_e64 s[52:53], 1, v113
	s_andn2_b64 vcc, exec, s[68:69]
	v_max_i32_e32 v113, 0, v0
	v_fma_f32 v114, v48, v113, 0
	v_max_i32_e32 v113, 0, v1
	v_fmac_f32_e32 v114, v49, v113
	v_max_i32_e32 v113, 0, v2
	v_fmac_f32_e32 v114, v50, v113
	v_max_i32_e32 v113, 0, v3
	v_fmac_f32_e32 v114, v51, v113
	v_max_i32_e32 v113, 0, v4
	v_fmac_f32_e32 v114, v52, v113
	v_mfma_f32_32x32x16_bf16 v[16:31], v[36:39], v[88:91], v[16:31]
	v_max_i32_e32 v113, 0, v5
	v_fmac_f32_e32 v114, v53, v113
	v_max_i32_e32 v113, 0, v6
	v_fmac_f32_e32 v114, v54, v113
	v_max_i32_e32 v113, 0, v7
	v_fmac_f32_e32 v114, v55, v113
	v_max_i32_e32 v113, 0, v8
	v_fmac_f32_e32 v114, v56, v113
	v_max_i32_e32 v113, 0, v9
	v_fmac_f32_e32 v114, v57, v113
	v_mfma_f32_32x32x16_bf16 v[16:31], v[40:43], v[80:83], v[16:31]
	v_max_i32_e32 v113, 0, v10
	v_fmac_f32_e32 v114, v58, v113
	v_max_i32_e32 v113, 0, v11
	v_fmac_f32_e32 v114, v59, v113
	v_max_i32_e32 v113, 0, v12
	v_fmac_f32_e32 v114, v60, v113
	v_max_i32_e32 v113, 0, v13
	v_fmac_f32_e32 v114, v61, v113
	v_mfma_f32_32x32x16_bf16 v[16:31], v[44:47], v[116:119], v[16:31]
	v_max_i32_e32 v113, 0, v14
	v_fmac_f32_e32 v114, v62, v113
	v_max_i32_e32 v113, 0, v15
	v_fmac_f32_e32 v114, v63, v113
	s_cmp_eq_u32 s60, 4
	v_or_b32_e32 v113, 0x60, v130
	s_cselect_b64 s[0:1], -1, 0
	v_cmp_gt_i32_e32 vcc, v113, v203
	s_and_b64 vcc, s[0:1], vcc
	s_nop 0
	v_cndmask_b32_e32 v112, v114, v197, vcc
	s_branch .LBB0_1762

.LBB0_1764:
	s_waitcnt lgkmcnt(0)
	ds_read_b128 v[100:103], v131 offset:0x6c00
	ds_read_b128 v[88:91], v131 offset:0x6c20
	ds_read_b128 v[80:83], v131 offset:0x6c40
	ds_read_b128 v[108:111], v131 offset:0x6c60
	s_cmp_gt_u32 s94, 9
	s_cselect_b64 s[68:69], -1, 0
	s_cmp_lt_u32 s94, 10
	s_cbranch_scc1 .LBB0_1766
	v_mfma_f32_32x32x16_bf16 v[0:15], v[32:35], v[96:99], 0
	v_cndmask_b32_e64 v97, 0, 1, s[66:67]
	v_cmp_ne_u32_e64 s[52:53], 1, v97
	s_andn2_b64 vcc, exec, s[66:67]
	v_max_i32_e32 v97, 0, v16
	v_fma_f32 v98, v48, v97, 0
	v_max_i32_e32 v97, 0, v17
	v_fmac_f32_e32 v98, v49, v97
	v_max_i32_e32 v97, 0, v18
	v_fmac_f32_e32 v98, v50, v97
	v_max_i32_e32 v97, 0, v19
	v_fmac_f32_e32 v98, v51, v97
	v_max_i32_e32 v97, 0, v20
	v_fmac_f32_e32 v98, v52, v97
	v_mfma_f32_32x32x16_bf16 v[0:15], v[36:39], v[92:95], v[0:15]
	v_max_i32_e32 v97, 0, v21
	v_fmac_f32_e32 v98, v53, v97
	v_max_i32_e32 v97, 0, v22
	v_fmac_f32_e32 v98, v54, v97
	v_max_i32_e32 v97, 0, v23
	v_fmac_f32_e32 v98, v55, v97
	v_max_i32_e32 v97, 0, v24
	v_fmac_f32_e32 v98, v56, v97
	v_max_i32_e32 v97, 0, v25
	v_fmac_f32_e32 v98, v57, v97
	v_mfma_f32_32x32x16_bf16 v[0:15], v[40:43], v[84:87], v[0:15]
	v_max_i32_e32 v97, 0, v26
	v_fmac_f32_e32 v98, v58, v97
	v_max_i32_e32 v97, 0, v27
	v_fmac_f32_e32 v98, v59, v97
	v_max_i32_e32 v97, 0, v28
	v_fmac_f32_e32 v98, v60, v97
	v_max_i32_e32 v97, 0, v29
	v_fmac_f32_e32 v98, v61, v97
	v_mfma_f32_32x32x16_bf16 v[0:15], v[44:47], v[104:107], v[0:15]
	v_max_i32_e32 v97, 0, v30
	v_fmac_f32_e32 v98, v62, v97
	v_max_i32_e32 v97, 0, v31
	v_fmac_f32_e32 v98, v63, v97
	s_cmp_eq_u32 s60, 5
	v_or_b32_e32 v97, 0x80, v130
	s_cselect_b64 s[0:1], -1, 0
	v_cmp_gt_i32_e32 vcc, v97, v203
	s_and_b64 vcc, s[0:1], vcc
	s_nop 0
	v_cndmask_b32_e32 v113, v98, v197, vcc
	s_branch .LBB0_1768

.LBB0_1770:
	s_waitcnt lgkmcnt(0)
	ds_read_b128 v[96:99], v131 offset:0x7e00
	ds_read_b128 v[92:95], v131 offset:0x7e20
	ds_read_b128 v[84:87], v131 offset:0x7e40
	ds_read_b128 v[104:107], v131 offset:0x7e60
	s_cmp_gt_u32 s94, 11
	s_cselect_b64 s[66:67], -1, 0
	s_cmp_lt_u32 s94, 12
	s_cbranch_scc1 .LBB0_1772
	v_mfma_f32_32x32x16_bf16 v[16:31], v[32:35], v[100:103], 0
	v_cndmask_b32_e64 v101, 0, 1, s[68:69]
	v_cmp_ne_u32_e64 s[52:53], 1, v101
	s_andn2_b64 vcc, exec, s[68:69]
	v_max_i32_e32 v101, 0, v0
	v_fma_f32 v102, v48, v101, 0
	v_max_i32_e32 v101, 0, v1
	v_fmac_f32_e32 v102, v49, v101
	v_max_i32_e32 v101, 0, v2
	v_fmac_f32_e32 v102, v50, v101
	v_max_i32_e32 v101, 0, v3
	v_fmac_f32_e32 v102, v51, v101
	v_max_i32_e32 v101, 0, v4
	v_fmac_f32_e32 v102, v52, v101
	v_mfma_f32_32x32x16_bf16 v[16:31], v[36:39], v[88:91], v[16:31]
	v_max_i32_e32 v101, 0, v5
	v_fmac_f32_e32 v102, v53, v101
	v_max_i32_e32 v101, 0, v6
	v_fmac_f32_e32 v102, v54, v101
	v_max_i32_e32 v101, 0, v7
	v_fmac_f32_e32 v102, v55, v101
	v_max_i32_e32 v101, 0, v8
	v_fmac_f32_e32 v102, v56, v101
	v_max_i32_e32 v101, 0, v9
	v_fmac_f32_e32 v102, v57, v101
	v_mfma_f32_32x32x16_bf16 v[16:31], v[40:43], v[80:83], v[16:31]
	v_max_i32_e32 v101, 0, v10
	v_fmac_f32_e32 v102, v58, v101
	v_max_i32_e32 v101, 0, v11
	v_fmac_f32_e32 v102, v59, v101
	v_max_i32_e32 v101, 0, v12
	v_fmac_f32_e32 v102, v60, v101
	v_max_i32_e32 v101, 0, v13
	v_fmac_f32_e32 v102, v61, v101
	v_mfma_f32_32x32x16_bf16 v[16:31], v[44:47], v[108:111], v[16:31]
	v_max_i32_e32 v101, 0, v14
	v_fmac_f32_e32 v102, v62, v101
	v_max_i32_e32 v101, 0, v15
	v_fmac_f32_e32 v102, v63, v101
	s_cmp_eq_u32 s60, 6
	v_or_b32_e32 v101, 0xa0, v130
	s_cselect_b64 s[0:1], -1, 0
	v_cmp_gt_i32_e32 vcc, v101, v203
	s_and_b64 vcc, s[0:1], vcc
	s_nop 0
	v_cndmask_b32_e32 v114, v102, v197, vcc
	s_branch .LBB0_1774

.LBB0_1776:
	s_waitcnt lgkmcnt(0)
	s_cmp_lt_u32 s94, 14
	s_cbranch_scc1 .LBB0_1778
	v_mfma_f32_32x32x16_bf16 v[0:15], v[32:35], v[96:99], 0
	v_cndmask_b32_e64 v97, 0, 1, s[66:67]
	v_cmp_ne_u32_e64 s[52:53], 1, v97
	s_andn2_b64 vcc, exec, s[66:67]
	v_max_i32_e32 v97, 0, v16
	v_fma_f32 v98, v48, v97, 0
	v_max_i32_e32 v97, 0, v17
	v_fmac_f32_e32 v98, v49, v97
	v_max_i32_e32 v97, 0, v18
	v_fmac_f32_e32 v98, v50, v97
	v_max_i32_e32 v97, 0, v19
	v_fmac_f32_e32 v98, v51, v97
	v_max_i32_e32 v97, 0, v20
	v_fmac_f32_e32 v98, v52, v97
	v_mfma_f32_32x32x16_bf16 v[0:15], v[36:39], v[92:95], v[0:15]
	v_max_i32_e32 v97, 0, v21
	v_fmac_f32_e32 v98, v53, v97
	v_max_i32_e32 v97, 0, v22
	v_fmac_f32_e32 v98, v54, v97
	v_max_i32_e32 v97, 0, v23
	v_fmac_f32_e32 v98, v55, v97
	v_max_i32_e32 v97, 0, v24
	v_fmac_f32_e32 v98, v56, v97
	v_max_i32_e32 v97, 0, v25
	v_fmac_f32_e32 v98, v57, v97
	v_mfma_f32_32x32x16_bf16 v[0:15], v[40:43], v[84:87], v[0:15]
	v_max_i32_e32 v97, 0, v26
	v_fmac_f32_e32 v98, v58, v97
	v_max_i32_e32 v97, 0, v27
	v_fmac_f32_e32 v98, v59, v97
	v_max_i32_e32 v97, 0, v28
	v_fmac_f32_e32 v98, v60, v97
	v_max_i32_e32 v97, 0, v29
	v_fmac_f32_e32 v98, v61, v97
	v_mfma_f32_32x32x16_bf16 v[0:15], v[44:47], v[104:107], v[0:15]
	v_max_i32_e32 v97, 0, v30
	s_cmp_eq_u32 s60, 7
	v_fmac_f32_e32 v98, v62, v97
	v_max_i32_e32 v97, 0, v31
	s_cselect_b64 s[0:1], -1, 0
	v_cmp_gt_i32_e32 vcc, v132, v203
	v_fmac_f32_e32 v98, v63, v97
	s_and_b64 vcc, s[0:1], vcc
	v_cndmask_b32_e32 v115, v98, v197, vcc
	s_branch .LBB0_1780

.LBB0_1791:
	ds_read_b128 v[16:19], v134 offset:0
	ds_read_b128 v[80:83], v134 offset:32
	ds_read_b128 v[84:87], v134 offset:64
	ds_read_b128 v[92:95], v134 offset:0x60
	v_max_i32_e32 v88, 0, v0
	s_waitcnt lgkmcnt(0)
	v_max_i32_e32 v89, 0, v1
	v_mfma_f32_32x32x16_bf16 v[16:31], v[32:35], v[16:19], 0
	v_fma_f32 v116, v48, v88, 0
	v_max_i32_e32 v90, 0, v2
	v_fmac_f32_e32 v116, v49, v89
	v_max_i32_e32 v91, 0, v3
	v_fmac_f32_e32 v116, v50, v90
	v_max_i32_e32 v96, 0, v4
	v_fmac_f32_e32 v116, v51, v91
	v_mfma_f32_32x32x16_bf16 v[16:31], v[36:39], v[80:83], v[16:31]
	v_max_i32_e32 v97, 0, v5
	v_fmac_f32_e32 v116, v52, v96
	v_max_i32_e32 v98, 0, v6
	v_fmac_f32_e32 v116, v53, v97
	v_max_i32_e32 v99, 0, v7
	v_fmac_f32_e32 v116, v54, v98
	v_max_i32_e32 v100, 0, v8
	v_mfma_f32_32x32x16_bf16 v[16:31], v[40:43], v[84:87], v[16:31]
	v_fmac_f32_e32 v116, v55, v99
	v_max_i32_e32 v101, 0, v9
	v_fmac_f32_e32 v116, v56, v100
	v_max_i32_e32 v102, 0, v10
	v_fmac_f32_e32 v116, v57, v101
	v_max_i32_e32 v103, 0, v11
	v_fmac_f32_e32 v116, v58, v102
	v_fmac_f32_e32 v116, v59, v103
	v_max_i32_e32 v84, 0, v12
	ds_read_b128 v[80:83], v134 offset:0x1200
	v_fmac_f32_e32 v116, v60, v84
	v_max_i32_e32 v84, 0, v13
	ds_read_b128 v[88:91], v134 offset:0x1220
	v_fmac_f32_e32 v116, v61, v84
	v_max_i32_e32 v84, 0, v14
	ds_read_b128 v[96:99], v134 offset:0x1240
	v_fmac_f32_e32 v116, v62, v84
	v_max_i32_e32 v84, 0, v15
	ds_read_b128 v[104:107], v134 offset:0x1260
	v_mfma_f32_32x32x16_bf16 v[16:31], v[44:47], v[92:95], v[16:31]
	v_fmac_f32_e32 v116, v63, v84
	s_waitcnt lgkmcnt(0)
	ds_read_b128 v[108:111], v134 offset:0x2400
	ds_read_b128 v[100:103], v134 offset:0x2420
	ds_read_b128 v[92:95], v134 offset:0x2440
	ds_read_b128 v[84:87], v134 offset:0x2460
	s_cmp_eq_u32 s60, 9
	s_cselect_b64 s[54:55], -1, 0
	s_cmp_lg_u32 s60, 9
	s_cselect_b64 s[0:1], -1, 0
	s_and_b64 vcc, exec, s[54:55]
	s_cbranch_vccnz .LBB0_1793
	v_mfma_f32_32x32x16_bf16 v[0:15], v[32:35], v[80:83], 0
	v_max_i32_e32 v81, 0, v16
	v_fma_f32 v82, v48, v81, 0
	v_max_i32_e32 v81, 0, v17
	v_fmac_f32_e32 v82, v49, v81
	v_max_i32_e32 v81, 0, v18
	v_fmac_f32_e32 v82, v50, v81
	v_max_i32_e32 v81, 0, v19
	v_fmac_f32_e32 v82, v51, v81
	v_max_i32_e32 v81, 0, v20
	v_fmac_f32_e32 v82, v52, v81
	v_mfma_f32_32x32x16_bf16 v[0:15], v[36:39], v[88:91], v[0:15]
	v_max_i32_e32 v81, 0, v21
	v_fmac_f32_e32 v82, v53, v81
	v_max_i32_e32 v81, 0, v22
	v_fmac_f32_e32 v82, v54, v81
	v_max_i32_e32 v81, 0, v23
	v_fmac_f32_e32 v82, v55, v81
	v_max_i32_e32 v81, 0, v24
	v_fmac_f32_e32 v82, v56, v81
	v_max_i32_e32 v81, 0, v25
	v_fmac_f32_e32 v82, v57, v81
	v_mfma_f32_32x32x16_bf16 v[0:15], v[40:43], v[96:99], v[0:15]
	v_max_i32_e32 v81, 0, v26
	v_fmac_f32_e32 v82, v58, v81
	v_max_i32_e32 v81, 0, v27
	v_fmac_f32_e32 v82, v59, v81
	v_max_i32_e32 v81, 0, v28
	v_fmac_f32_e32 v82, v60, v81
	v_max_i32_e32 v81, 0, v29
	v_fmac_f32_e32 v82, v61, v81
	v_mfma_f32_32x32x16_bf16 v[0:15], v[44:47], v[104:107], v[0:15]
	v_max_i32_e32 v81, 0, v30
	v_fmac_f32_e32 v82, v62, v81
	v_max_i32_e32 v81, 0, v31
	v_cmp_gt_i32_e32 vcc, v135, v203
	v_fmac_f32_e32 v82, v63, v81
	s_and_b64 vcc, s[54:55], vcc
	v_cndmask_b32_e32 v117, v82, v197, vcc
	s_branch .Lixj49

.Lixj49:
	s_waitcnt lgkmcnt(0)
	ds_read_b128 v[96:99], v134 offset:0x3600
	ds_read_b128 v[88:91], v134 offset:0x3620
	ds_read_b128 v[80:83], v134 offset:0x3640
	ds_read_b128 v[104:107], v134 offset:0x3660
	s_cmp_gt_u32 s94, 19
	s_cselect_b64 s[66:67], -1, 0
	s_cmp_lt_u32 s94, 20
	s_cbranch_scc1 .LBB0_1795
	v_mfma_f32_32x32x16_bf16 v[16:31], v[32:35], v[108:111], 0
	v_cndmask_b32_e64 v109, 0, 1, s[0:1]
	v_cmp_ne_u32_e64 s[54:55], 1, v109
	s_andn2_b64 vcc, exec, s[0:1]
	v_max_i32_e32 v109, 0, v0
	v_fma_f32 v110, v48, v109, 0
	v_max_i32_e32 v109, 0, v1
	v_fmac_f32_e32 v110, v49, v109
	v_max_i32_e32 v109, 0, v2
	v_fmac_f32_e32 v110, v50, v109
	v_max_i32_e32 v109, 0, v3
	v_fmac_f32_e32 v110, v51, v109
	v_max_i32_e32 v109, 0, v4
	v_fmac_f32_e32 v110, v52, v109
	v_mfma_f32_32x32x16_bf16 v[16:31], v[36:39], v[100:103], v[16:31]
	v_max_i32_e32 v109, 0, v5
	v_fmac_f32_e32 v110, v53, v109
	v_max_i32_e32 v109, 0, v6
	v_fmac_f32_e32 v110, v54, v109
	v_max_i32_e32 v109, 0, v7
	v_fmac_f32_e32 v110, v55, v109
	v_max_i32_e32 v109, 0, v8
	v_fmac_f32_e32 v110, v56, v109
	v_max_i32_e32 v109, 0, v9
	v_fmac_f32_e32 v110, v57, v109
	v_mfma_f32_32x32x16_bf16 v[16:31], v[40:43], v[92:95], v[16:31]
	v_max_i32_e32 v109, 0, v10
	v_fmac_f32_e32 v110, v58, v109
	v_max_i32_e32 v109, 0, v11
	v_fmac_f32_e32 v110, v59, v109
	v_max_i32_e32 v109, 0, v12
	v_fmac_f32_e32 v110, v60, v109
	v_max_i32_e32 v109, 0, v13
	v_fmac_f32_e32 v110, v61, v109
	v_mfma_f32_32x32x16_bf16 v[16:31], v[44:47], v[84:87], v[16:31]
	v_max_i32_e32 v109, 0, v14
	s_cmp_eq_u32 s60, 10
	v_fmac_f32_e32 v110, v62, v109
	v_max_i32_e32 v109, 0, v15
	s_cselect_b64 s[0:1], -1, 0
	v_cmp_gt_i32_e32 vcc, v136, v203
	v_fmac_f32_e32 v110, v63, v109
	s_and_b64 vcc, s[0:1], vcc
	v_cndmask_b32_e32 v118, v110, v197, vcc
	s_branch .LBB0_1797

.LBB0_1799:
	s_waitcnt lgkmcnt(0)
	ds_read_b128 v[100:103], v134 offset:0x4800
	ds_read_b128 v[92:95], v134 offset:0x4820
	ds_read_b128 v[84:87], v134 offset:0x4840
	ds_read_b128 v[108:111], v134 offset:0x4860
	s_cmp_gt_u32 s94, 21
	s_cselect_b64 s[68:69], -1, 0
	s_cmp_lt_u32 s94, 22
	s_cbranch_scc1 .LBB0_1801
	v_mfma_f32_32x32x16_bf16 v[0:15], v[32:35], v[96:99], 0
	v_cndmask_b32_e64 v97, 0, 1, s[66:67]
	v_cmp_ne_u32_e64 s[54:55], 1, v97
	s_andn2_b64 vcc, exec, s[66:67]
	v_max_i32_e32 v97, 0, v16
	v_fma_f32 v98, v48, v97, 0
	v_max_i32_e32 v97, 0, v17
	v_fmac_f32_e32 v98, v49, v97
	v_max_i32_e32 v97, 0, v18
	v_fmac_f32_e32 v98, v50, v97
	v_max_i32_e32 v97, 0, v19
	v_fmac_f32_e32 v98, v51, v97
	v_max_i32_e32 v97, 0, v20
	v_fmac_f32_e32 v98, v52, v97
	v_mfma_f32_32x32x16_bf16 v[0:15], v[36:39], v[88:91], v[0:15]
	v_max_i32_e32 v97, 0, v21
	v_fmac_f32_e32 v98, v53, v97
	v_max_i32_e32 v97, 0, v22
	v_fmac_f32_e32 v98, v54, v97
	v_max_i32_e32 v97, 0, v23
	v_fmac_f32_e32 v98, v55, v97
	v_max_i32_e32 v97, 0, v24
	v_fmac_f32_e32 v98, v56, v97
	v_max_i32_e32 v97, 0, v25
	v_fmac_f32_e32 v98, v57, v97
	v_mfma_f32_32x32x16_bf16 v[0:15], v[40:43], v[80:83], v[0:15]
	v_max_i32_e32 v97, 0, v26
	v_fmac_f32_e32 v98, v58, v97
	v_max_i32_e32 v97, 0, v27
	v_fmac_f32_e32 v98, v59, v97
	v_max_i32_e32 v97, 0, v28
	v_fmac_f32_e32 v98, v60, v97
	v_max_i32_e32 v97, 0, v29
	v_fmac_f32_e32 v98, v61, v97
	v_mfma_f32_32x32x16_bf16 v[0:15], v[44:47], v[104:107], v[0:15]
	v_max_i32_e32 v97, 0, v30
	s_cmp_eq_u32 s60, 11
	v_fmac_f32_e32 v98, v62, v97
	v_max_i32_e32 v97, 0, v31
	s_cselect_b64 s[0:1], -1, 0
	v_cmp_gt_i32_e32 vcc, v137, v203
	v_fmac_f32_e32 v98, v63, v97
	s_and_b64 vcc, s[0:1], vcc
	v_cndmask_b32_e32 v119, v98, v197, vcc
	s_branch .LBB0_1803

.LBB0_1805:
	s_waitcnt lgkmcnt(0)
	ds_read_b128 v[96:99], v134 offset:0x5a00
	ds_read_b128 v[88:91], v134 offset:0x5a20
	ds_read_b128 v[80:83], v134 offset:0x5a40
	ds_read_b128 v[104:107], v134 offset:0x5a60
	s_cmp_gt_u32 s94, 23
	s_cselect_b64 s[66:67], -1, 0
	s_cmp_lt_u32 s94, 24
	s_cbranch_scc1 .LBB0_1807
	v_mfma_f32_32x32x16_bf16 v[16:31], v[32:35], v[100:103], 0
	v_cndmask_b32_e64 v101, 0, 1, s[68:69]
	v_cmp_ne_u32_e64 s[54:55], 1, v101
	s_andn2_b64 vcc, exec, s[68:69]
	v_max_i32_e32 v101, 0, v0
	v_fma_f32 v102, v48, v101, 0
	v_max_i32_e32 v101, 0, v1
	v_fmac_f32_e32 v102, v49, v101
	v_max_i32_e32 v101, 0, v2
	v_fmac_f32_e32 v102, v50, v101
	v_max_i32_e32 v101, 0, v3
	v_fmac_f32_e32 v102, v51, v101
	v_max_i32_e32 v101, 0, v4
	v_fmac_f32_e32 v102, v52, v101
	v_mfma_f32_32x32x16_bf16 v[16:31], v[36:39], v[92:95], v[16:31]
	v_max_i32_e32 v101, 0, v5
	v_fmac_f32_e32 v102, v53, v101
	v_max_i32_e32 v101, 0, v6
	v_fmac_f32_e32 v102, v54, v101
	v_max_i32_e32 v101, 0, v7
	v_fmac_f32_e32 v102, v55, v101
	v_max_i32_e32 v101, 0, v8
	v_fmac_f32_e32 v102, v56, v101
	v_max_i32_e32 v101, 0, v9
	v_fmac_f32_e32 v102, v57, v101
	v_mfma_f32_32x32x16_bf16 v[16:31], v[40:43], v[84:87], v[16:31]
	v_max_i32_e32 v101, 0, v10
	v_fmac_f32_e32 v102, v58, v101
	v_max_i32_e32 v101, 0, v11
	v_fmac_f32_e32 v102, v59, v101
	v_max_i32_e32 v101, 0, v12
	v_fmac_f32_e32 v102, v60, v101
	v_max_i32_e32 v101, 0, v13
	v_fmac_f32_e32 v102, v61, v101
	v_mfma_f32_32x32x16_bf16 v[16:31], v[44:47], v[108:111], v[16:31]
	v_max_i32_e32 v101, 0, v14
	s_cmp_eq_u32 s60, 12
	v_fmac_f32_e32 v102, v62, v101
	v_max_i32_e32 v101, 0, v15
	s_cselect_b64 s[0:1], -1, 0
	v_cmp_gt_i32_e32 vcc, v138, v203
	v_fmac_f32_e32 v102, v63, v101
	s_and_b64 vcc, s[0:1], vcc
	v_cndmask_b32_e32 v205, v102, v197, vcc
	s_branch .LBB0_1809

.LBB0_1811:
	s_waitcnt lgkmcnt(0)
	ds_read_b128 v[100:103], v134 offset:0x6c00
	ds_read_b128 v[92:95], v134 offset:0x6c20
	ds_read_b128 v[84:87], v134 offset:0x6c40
	ds_read_b128 v[108:111], v134 offset:0x6c60
	s_cmp_gt_u32 s94, 25
	s_cselect_b64 s[68:69], -1, 0
	s_cmp_lt_u32 s94, 26
	s_cbranch_scc1 .LBB0_1813
	v_mfma_f32_32x32x16_bf16 v[0:15], v[32:35], v[96:99], 0
	v_cndmask_b32_e64 v97, 0, 1, s[66:67]
	v_cmp_ne_u32_e64 s[54:55], 1, v97
	s_andn2_b64 vcc, exec, s[66:67]
	v_max_i32_e32 v97, 0, v16
	v_fma_f32 v98, v48, v97, 0
	v_max_i32_e32 v97, 0, v17
	v_fmac_f32_e32 v98, v49, v97
	v_max_i32_e32 v97, 0, v18
	v_fmac_f32_e32 v98, v50, v97
	v_max_i32_e32 v97, 0, v19
	v_fmac_f32_e32 v98, v51, v97
	v_max_i32_e32 v97, 0, v20
	v_fmac_f32_e32 v98, v52, v97
	v_mfma_f32_32x32x16_bf16 v[0:15], v[36:39], v[88:91], v[0:15]
	v_max_i32_e32 v97, 0, v21
	v_fmac_f32_e32 v98, v53, v97
	v_max_i32_e32 v97, 0, v22
	v_fmac_f32_e32 v98, v54, v97
	v_max_i32_e32 v97, 0, v23
	v_fmac_f32_e32 v98, v55, v97
	v_max_i32_e32 v97, 0, v24
	v_fmac_f32_e32 v98, v56, v97
	v_max_i32_e32 v97, 0, v25
	v_fmac_f32_e32 v98, v57, v97
	v_mfma_f32_32x32x16_bf16 v[0:15], v[40:43], v[80:83], v[0:15]
	v_max_i32_e32 v97, 0, v26
	v_fmac_f32_e32 v98, v58, v97
	v_max_i32_e32 v97, 0, v27
	v_fmac_f32_e32 v98, v59, v97
	v_max_i32_e32 v97, 0, v28
	v_fmac_f32_e32 v98, v60, v97
	v_max_i32_e32 v97, 0, v29
	v_fmac_f32_e32 v98, v61, v97
	v_mfma_f32_32x32x16_bf16 v[0:15], v[44:47], v[104:107], v[0:15]
	v_max_i32_e32 v97, 0, v30
	s_cmp_eq_u32 s60, 13
	v_fmac_f32_e32 v98, v62, v97
	v_max_i32_e32 v97, 0, v31
	s_cselect_b64 s[0:1], -1, 0
	v_cmp_gt_i32_e32 vcc, v139, v203
	v_fmac_f32_e32 v98, v63, v97
	s_and_b64 vcc, s[0:1], vcc
	v_cndmask_b32_e32 v206, v98, v197, vcc
	s_branch .LBB0_1815

.LBB0_1817:
	s_waitcnt lgkmcnt(0)
	ds_read_b128 v[96:99], v134 offset:0x7e00
	ds_read_b128 v[88:91], v134 offset:0x7e20
	ds_read_b128 v[80:83], v134 offset:0x7e40
	ds_read_b128 v[104:107], v134 offset:0x7e60
	s_cmp_gt_u32 s94, 27
	s_cselect_b64 s[66:67], -1, 0
	s_cmp_lt_u32 s94, 28
	s_cbranch_scc1 .LBB0_1819
	v_mfma_f32_32x32x16_bf16 v[16:31], v[32:35], v[100:103], 0
	v_cndmask_b32_e64 v101, 0, 1, s[68:69]
	v_cmp_ne_u32_e64 s[54:55], 1, v101
	s_andn2_b64 vcc, exec, s[68:69]
	v_max_i32_e32 v101, 0, v0
	v_fma_f32 v102, v48, v101, 0
	v_max_i32_e32 v101, 0, v1
	v_fmac_f32_e32 v102, v49, v101
	v_max_i32_e32 v101, 0, v2
	v_fmac_f32_e32 v102, v50, v101
	v_max_i32_e32 v101, 0, v3
	v_fmac_f32_e32 v102, v51, v101
	v_max_i32_e32 v101, 0, v4
	v_fmac_f32_e32 v102, v52, v101
	v_mfma_f32_32x32x16_bf16 v[16:31], v[36:39], v[92:95], v[16:31]
	v_max_i32_e32 v101, 0, v5
	v_fmac_f32_e32 v102, v53, v101
	v_max_i32_e32 v101, 0, v6
	v_fmac_f32_e32 v102, v54, v101
	v_max_i32_e32 v101, 0, v7
	v_fmac_f32_e32 v102, v55, v101
	v_max_i32_e32 v101, 0, v8
	v_fmac_f32_e32 v102, v56, v101
	v_max_i32_e32 v101, 0, v9
	v_fmac_f32_e32 v102, v57, v101
	v_mfma_f32_32x32x16_bf16 v[16:31], v[40:43], v[84:87], v[16:31]
	v_max_i32_e32 v101, 0, v10
	v_fmac_f32_e32 v102, v58, v101
	v_max_i32_e32 v101, 0, v11
	v_fmac_f32_e32 v102, v59, v101
	v_max_i32_e32 v101, 0, v12
	v_fmac_f32_e32 v102, v60, v101
	v_max_i32_e32 v101, 0, v13
	v_fmac_f32_e32 v102, v61, v101
	v_mfma_f32_32x32x16_bf16 v[16:31], v[44:47], v[108:111], v[16:31]
	v_max_i32_e32 v101, 0, v14
	s_cmp_eq_u32 s60, 14
	v_fmac_f32_e32 v102, v62, v101
	v_max_i32_e32 v101, 0, v15
	s_cselect_b64 s[0:1], -1, 0
	v_cmp_gt_i32_e32 vcc, v140, v203
	v_fmac_f32_e32 v102, v63, v101
	s_and_b64 vcc, s[0:1], vcc
	v_cndmask_b32_e32 v207, v102, v197, vcc
	s_branch .LBB0_1821

.LBB0_1823:
	s_waitcnt lgkmcnt(0)
	s_cmp_lt_u32 s94, 30
	s_cbranch_scc1 .LBB0_1825
	v_mfma_f32_32x32x16_bf16 v[0:15], v[32:35], v[96:99], 0
	v_cndmask_b32_e64 v97, 0, 1, s[66:67]
	v_cmp_ne_u32_e64 s[54:55], 1, v97
	s_andn2_b64 vcc, exec, s[66:67]
	v_max_i32_e32 v97, 0, v16
	v_fma_f32 v98, v48, v97, 0
	v_max_i32_e32 v97, 0, v17
	v_fmac_f32_e32 v98, v49, v97
	v_max_i32_e32 v97, 0, v18
	v_fmac_f32_e32 v98, v50, v97
	v_max_i32_e32 v97, 0, v19
	v_fmac_f32_e32 v98, v51, v97
	v_max_i32_e32 v97, 0, v20
	v_fmac_f32_e32 v98, v52, v97
	v_mfma_f32_32x32x16_bf16 v[0:15], v[36:39], v[88:91], v[0:15]
	v_max_i32_e32 v97, 0, v21
	v_fmac_f32_e32 v98, v53, v97
	v_max_i32_e32 v97, 0, v22
	v_fmac_f32_e32 v98, v54, v97
	v_max_i32_e32 v97, 0, v23
	v_fmac_f32_e32 v98, v55, v97
	v_max_i32_e32 v97, 0, v24
	v_fmac_f32_e32 v98, v56, v97
	v_max_i32_e32 v97, 0, v25
	v_fmac_f32_e32 v98, v57, v97
	v_mfma_f32_32x32x16_bf16 v[0:15], v[40:43], v[80:83], v[0:15]
	v_max_i32_e32 v97, 0, v26
	v_fmac_f32_e32 v98, v58, v97
	v_max_i32_e32 v97, 0, v27
	v_fmac_f32_e32 v98, v59, v97
	v_max_i32_e32 v97, 0, v28
	v_fmac_f32_e32 v98, v60, v97
	v_max_i32_e32 v97, 0, v29
	v_fmac_f32_e32 v98, v61, v97
	v_mfma_f32_32x32x16_bf16 v[0:15], v[44:47], v[104:107], v[0:15]
	v_max_i32_e32 v97, 0, v30
	s_cmp_eq_u32 s60, 15
	v_fmac_f32_e32 v98, v62, v97
	v_max_i32_e32 v97, 0, v31
	s_cselect_b64 s[0:1], -1, 0
	v_cmp_gt_i32_e32 vcc, v141, v203
	v_fmac_f32_e32 v98, v63, v97
	s_and_b64 vcc, s[0:1], vcc
	v_cndmask_b32_e32 v208, v98, v197, vcc
	s_branch .LBB0_1827

.LBB0_1835:
	ds_read_b128 v[16:19], v131 offset:0
	ds_read_b128 v[80:83], v131 offset:32
	ds_read_b128 v[84:87], v131 offset:64
	ds_read_b128 v[92:95], v131 offset:0x60
	v_max_i32_e32 v88, 0, v0
	s_waitcnt lgkmcnt(0)
	v_max_i32_e32 v89, 0, v1
	v_mfma_f32_32x32x16_bf16 v[16:31], v[32:35], v[16:19], 0
	v_fma_f32 v209, v48, v88, 0
	v_max_i32_e32 v90, 0, v2
	v_fmac_f32_e32 v209, v49, v89
	v_max_i32_e32 v91, 0, v3
	v_fmac_f32_e32 v209, v50, v90
	v_max_i32_e32 v96, 0, v4
	v_fmac_f32_e32 v209, v51, v91
	v_mfma_f32_32x32x16_bf16 v[16:31], v[36:39], v[80:83], v[16:31]
	v_max_i32_e32 v97, 0, v5
	v_fmac_f32_e32 v209, v52, v96
	v_max_i32_e32 v98, 0, v6
	v_fmac_f32_e32 v209, v53, v97
	v_max_i32_e32 v99, 0, v7
	v_fmac_f32_e32 v209, v54, v98
	v_max_i32_e32 v100, 0, v8
	v_mfma_f32_32x32x16_bf16 v[16:31], v[40:43], v[84:87], v[16:31]
	v_fmac_f32_e32 v209, v55, v99
	v_max_i32_e32 v101, 0, v9
	v_fmac_f32_e32 v209, v56, v100
	v_max_i32_e32 v102, 0, v10
	v_fmac_f32_e32 v209, v57, v101
	v_max_i32_e32 v103, 0, v11
	v_fmac_f32_e32 v209, v58, v102
	v_fmac_f32_e32 v209, v59, v103
	v_max_i32_e32 v84, 0, v12
	ds_read_b128 v[80:83], v131 offset:0x1200
	v_fmac_f32_e32 v209, v60, v84
	v_max_i32_e32 v84, 0, v13
	ds_read_b128 v[88:91], v131 offset:0x1220
	v_fmac_f32_e32 v209, v61, v84
	v_max_i32_e32 v84, 0, v14
	ds_read_b128 v[96:99], v131 offset:0x1240
	v_fmac_f32_e32 v209, v62, v84
	v_max_i32_e32 v84, 0, v15
	ds_read_b128 v[104:107], v131 offset:0x1260
	v_mfma_f32_32x32x16_bf16 v[16:31], v[44:47], v[92:95], v[16:31]
	v_fmac_f32_e32 v209, v63, v84
	s_waitcnt lgkmcnt(0)
	ds_read_b128 v[108:111], v131 offset:0x2400
	ds_read_b128 v[100:103], v131 offset:0x2420
	ds_read_b128 v[92:95], v131 offset:0x2440
	ds_read_b128 v[84:87], v131 offset:0x2460
	s_cmp_eq_u32 s60, 17
	s_cselect_b64 s[54:55], -1, 0
	s_cmp_lg_u32 s60, 17
	s_cselect_b64 s[0:1], -1, 0
	s_and_b64 vcc, exec, s[54:55]
	s_cbranch_vccnz .LBB0_1837
	v_mfma_f32_32x32x16_bf16 v[0:15], v[32:35], v[80:83], 0
	v_max_i32_e32 v81, 0, v16
	v_fma_f32 v82, v48, v81, 0
	v_max_i32_e32 v81, 0, v17
	v_fmac_f32_e32 v82, v49, v81
	v_max_i32_e32 v81, 0, v18
	v_fmac_f32_e32 v82, v50, v81
	v_max_i32_e32 v81, 0, v19
	v_fmac_f32_e32 v82, v51, v81
	v_max_i32_e32 v81, 0, v20
	v_fmac_f32_e32 v82, v52, v81
	v_mfma_f32_32x32x16_bf16 v[0:15], v[36:39], v[88:91], v[0:15]
	v_max_i32_e32 v81, 0, v21
	v_fmac_f32_e32 v82, v53, v81
	v_max_i32_e32 v81, 0, v22
	v_fmac_f32_e32 v82, v54, v81
	v_max_i32_e32 v81, 0, v23
	v_fmac_f32_e32 v82, v55, v81
	v_max_i32_e32 v81, 0, v24
	v_fmac_f32_e32 v82, v56, v81
	v_max_i32_e32 v81, 0, v25
	v_fmac_f32_e32 v82, v57, v81
	v_mfma_f32_32x32x16_bf16 v[0:15], v[40:43], v[96:99], v[0:15]
	v_max_i32_e32 v81, 0, v26
	v_fmac_f32_e32 v82, v58, v81
	v_max_i32_e32 v81, 0, v27
	v_fmac_f32_e32 v82, v59, v81
	v_max_i32_e32 v81, 0, v28
	v_fmac_f32_e32 v82, v60, v81
	v_max_i32_e32 v81, 0, v29
	v_fmac_f32_e32 v82, v61, v81
	v_mfma_f32_32x32x16_bf16 v[0:15], v[44:47], v[104:107], v[0:15]
	v_max_i32_e32 v81, 0, v30
	v_fmac_f32_e32 v82, v62, v81
	v_max_i32_e32 v81, 0, v31
	v_cmp_gt_i32_e32 vcc, v143, v203
	v_fmac_f32_e32 v82, v63, v81
	s_and_b64 vcc, s[54:55], vcc
	v_cndmask_b32_e32 v210, v82, v197, vcc
	s_branch .Lixj42

.Lixj42:
	s_waitcnt lgkmcnt(0)
	ds_read_b128 v[96:99], v131 offset:0x3600
	ds_read_b128 v[88:91], v131 offset:0x3620
	ds_read_b128 v[80:83], v131 offset:0x3640
	ds_read_b128 v[104:107], v131 offset:0x3660
	s_cmp_gt_u32 s94, 35
	s_cselect_b64 s[66:67], -1, 0
	s_cmp_lt_u32 s94, 36
	s_cbranch_scc1 .LBB0_1839
	v_mfma_f32_32x32x16_bf16 v[16:31], v[32:35], v[108:111], 0
	v_cndmask_b32_e64 v109, 0, 1, s[0:1]
	v_cmp_ne_u32_e64 s[54:55], 1, v109
	s_andn2_b64 vcc, exec, s[0:1]
	v_max_i32_e32 v109, 0, v0
	v_fma_f32 v110, v48, v109, 0
	v_max_i32_e32 v109, 0, v1
	v_fmac_f32_e32 v110, v49, v109
	v_max_i32_e32 v109, 0, v2
	v_fmac_f32_e32 v110, v50, v109
	v_max_i32_e32 v109, 0, v3
	v_fmac_f32_e32 v110, v51, v109
	v_max_i32_e32 v109, 0, v4
	v_fmac_f32_e32 v110, v52, v109
	v_mfma_f32_32x32x16_bf16 v[16:31], v[36:39], v[100:103], v[16:31]
	v_max_i32_e32 v109, 0, v5
	v_fmac_f32_e32 v110, v53, v109
	v_max_i32_e32 v109, 0, v6
	v_fmac_f32_e32 v110, v54, v109
	v_max_i32_e32 v109, 0, v7
	v_fmac_f32_e32 v110, v55, v109
	v_max_i32_e32 v109, 0, v8
	v_fmac_f32_e32 v110, v56, v109
	v_max_i32_e32 v109, 0, v9
	v_fmac_f32_e32 v110, v57, v109
	v_mfma_f32_32x32x16_bf16 v[16:31], v[40:43], v[92:95], v[16:31]
	v_max_i32_e32 v109, 0, v10
	v_fmac_f32_e32 v110, v58, v109
	v_max_i32_e32 v109, 0, v11
	v_fmac_f32_e32 v110, v59, v109
	v_max_i32_e32 v109, 0, v12
	v_fmac_f32_e32 v110, v60, v109
	v_max_i32_e32 v109, 0, v13
	v_fmac_f32_e32 v110, v61, v109
	v_mfma_f32_32x32x16_bf16 v[16:31], v[44:47], v[84:87], v[16:31]
	v_max_i32_e32 v109, 0, v14
	s_cmp_eq_u32 s60, 18
	v_fmac_f32_e32 v110, v62, v109
	v_max_i32_e32 v109, 0, v15
	s_cselect_b64 s[0:1], -1, 0
	v_cmp_gt_i32_e32 vcc, v144, v203
	v_fmac_f32_e32 v110, v63, v109
	s_and_b64 vcc, s[0:1], vcc
	v_cndmask_b32_e32 v211, v110, v197, vcc
	s_branch .LBB0_1841

.LBB0_1843:
	s_waitcnt lgkmcnt(0)
	ds_read_b128 v[100:103], v131 offset:0x4800
	ds_read_b128 v[92:95], v131 offset:0x4820
	ds_read_b128 v[84:87], v131 offset:0x4840
	ds_read_b128 v[108:111], v131 offset:0x4860
	s_cmp_gt_u32 s94, 37
	s_cselect_b64 s[68:69], -1, 0
	s_cmp_lt_u32 s94, 38
	s_cbranch_scc1 .LBB0_1845
	v_mfma_f32_32x32x16_bf16 v[0:15], v[32:35], v[96:99], 0
	v_cndmask_b32_e64 v97, 0, 1, s[66:67]
	v_cmp_ne_u32_e64 s[54:55], 1, v97
	s_andn2_b64 vcc, exec, s[66:67]
	v_max_i32_e32 v97, 0, v16
	v_fma_f32 v98, v48, v97, 0
	v_max_i32_e32 v97, 0, v17
	v_fmac_f32_e32 v98, v49, v97
	v_max_i32_e32 v97, 0, v18
	v_fmac_f32_e32 v98, v50, v97
	v_max_i32_e32 v97, 0, v19
	v_fmac_f32_e32 v98, v51, v97
	v_max_i32_e32 v97, 0, v20
	v_fmac_f32_e32 v98, v52, v97
	v_mfma_f32_32x32x16_bf16 v[0:15], v[36:39], v[88:91], v[0:15]
	v_max_i32_e32 v97, 0, v21
	v_fmac_f32_e32 v98, v53, v97
	v_max_i32_e32 v97, 0, v22
	v_fmac_f32_e32 v98, v54, v97
	v_max_i32_e32 v97, 0, v23
	v_fmac_f32_e32 v98, v55, v97
	v_max_i32_e32 v97, 0, v24
	v_fmac_f32_e32 v98, v56, v97
	v_max_i32_e32 v97, 0, v25
	v_fmac_f32_e32 v98, v57, v97
	v_mfma_f32_32x32x16_bf16 v[0:15], v[40:43], v[80:83], v[0:15]
	v_max_i32_e32 v97, 0, v26
	v_fmac_f32_e32 v98, v58, v97
	v_max_i32_e32 v97, 0, v27
	v_fmac_f32_e32 v98, v59, v97
	v_max_i32_e32 v97, 0, v28
	v_fmac_f32_e32 v98, v60, v97
	v_max_i32_e32 v97, 0, v29
	v_fmac_f32_e32 v98, v61, v97
	v_mfma_f32_32x32x16_bf16 v[0:15], v[44:47], v[104:107], v[0:15]
	v_max_i32_e32 v97, 0, v30
	s_cmp_eq_u32 s60, 19
	v_fmac_f32_e32 v98, v62, v97
	v_max_i32_e32 v97, 0, v31
	s_cselect_b64 s[0:1], -1, 0
	v_cmp_gt_i32_e32 vcc, v145, v203
	v_fmac_f32_e32 v98, v63, v97
	s_and_b64 vcc, s[0:1], vcc
	v_cndmask_b32_e32 v212, v98, v197, vcc
	s_branch .LBB0_1847

.LBB0_1849:
	s_waitcnt lgkmcnt(0)
	ds_read_b128 v[96:99], v131 offset:0x5a00
	ds_read_b128 v[88:91], v131 offset:0x5a20
	ds_read_b128 v[80:83], v131 offset:0x5a40
	ds_read_b128 v[104:107], v131 offset:0x5a60
	s_cmp_gt_u32 s94, 39
	s_cselect_b64 s[66:67], -1, 0
	s_cmp_lt_u32 s94, 40
	s_cbranch_scc1 .LBB0_1851
	v_mfma_f32_32x32x16_bf16 v[16:31], v[32:35], v[100:103], 0
	v_cndmask_b32_e64 v101, 0, 1, s[68:69]
	v_cmp_ne_u32_e64 s[54:55], 1, v101
	s_andn2_b64 vcc, exec, s[68:69]
	v_max_i32_e32 v101, 0, v0
	v_fma_f32 v102, v48, v101, 0
	v_max_i32_e32 v101, 0, v1
	v_fmac_f32_e32 v102, v49, v101
	v_max_i32_e32 v101, 0, v2
	v_fmac_f32_e32 v102, v50, v101
	v_max_i32_e32 v101, 0, v3
	v_fmac_f32_e32 v102, v51, v101
	v_max_i32_e32 v101, 0, v4
	v_fmac_f32_e32 v102, v52, v101
	v_mfma_f32_32x32x16_bf16 v[16:31], v[36:39], v[92:95], v[16:31]
	v_max_i32_e32 v101, 0, v5
	v_fmac_f32_e32 v102, v53, v101
	v_max_i32_e32 v101, 0, v6
	v_fmac_f32_e32 v102, v54, v101
	v_max_i32_e32 v101, 0, v7
	v_fmac_f32_e32 v102, v55, v101
	v_max_i32_e32 v101, 0, v8
	v_fmac_f32_e32 v102, v56, v101
	v_max_i32_e32 v101, 0, v9
	v_fmac_f32_e32 v102, v57, v101
	v_mfma_f32_32x32x16_bf16 v[16:31], v[40:43], v[84:87], v[16:31]
	v_max_i32_e32 v101, 0, v10
	v_fmac_f32_e32 v102, v58, v101
	v_max_i32_e32 v101, 0, v11
	v_fmac_f32_e32 v102, v59, v101
	v_max_i32_e32 v101, 0, v12
	v_fmac_f32_e32 v102, v60, v101
	v_max_i32_e32 v101, 0, v13
	v_fmac_f32_e32 v102, v61, v101
	v_mfma_f32_32x32x16_bf16 v[16:31], v[44:47], v[108:111], v[16:31]
	v_max_i32_e32 v101, 0, v14
	s_cmp_eq_u32 s60, 20
	v_fmac_f32_e32 v102, v62, v101
	v_max_i32_e32 v101, 0, v15
	s_cselect_b64 s[0:1], -1, 0
	v_cmp_gt_i32_e32 vcc, v146, v203
	v_fmac_f32_e32 v102, v63, v101
	s_and_b64 vcc, s[0:1], vcc
	v_cndmask_b32_e32 v213, v102, v197, vcc
	s_branch .LBB0_1853

.LBB0_1855:
	s_waitcnt lgkmcnt(0)
	ds_read_b128 v[100:103], v131 offset:0x6c00
	ds_read_b128 v[92:95], v131 offset:0x6c20
	ds_read_b128 v[84:87], v131 offset:0x6c40
	ds_read_b128 v[108:111], v131 offset:0x6c60
	s_cmp_gt_u32 s94, 41
	s_cselect_b64 s[68:69], -1, 0
	s_cmp_lt_u32 s94, 42
	s_cbranch_scc1 .LBB0_1857
	v_mfma_f32_32x32x16_bf16 v[0:15], v[32:35], v[96:99], 0
	v_cndmask_b32_e64 v97, 0, 1, s[66:67]
	v_cmp_ne_u32_e64 s[54:55], 1, v97
	s_andn2_b64 vcc, exec, s[66:67]
	v_max_i32_e32 v97, 0, v16
	v_fma_f32 v98, v48, v97, 0
	v_max_i32_e32 v97, 0, v17
	v_fmac_f32_e32 v98, v49, v97
	v_max_i32_e32 v97, 0, v18
	v_fmac_f32_e32 v98, v50, v97
	v_max_i32_e32 v97, 0, v19
	v_fmac_f32_e32 v98, v51, v97
	v_max_i32_e32 v97, 0, v20
	v_fmac_f32_e32 v98, v52, v97
	v_mfma_f32_32x32x16_bf16 v[0:15], v[36:39], v[88:91], v[0:15]
	v_max_i32_e32 v97, 0, v21
	v_fmac_f32_e32 v98, v53, v97
	v_max_i32_e32 v97, 0, v22
	v_fmac_f32_e32 v98, v54, v97
	v_max_i32_e32 v97, 0, v23
	v_fmac_f32_e32 v98, v55, v97
	v_max_i32_e32 v97, 0, v24
	v_fmac_f32_e32 v98, v56, v97
	v_max_i32_e32 v97, 0, v25
	v_fmac_f32_e32 v98, v57, v97
	v_mfma_f32_32x32x16_bf16 v[0:15], v[40:43], v[80:83], v[0:15]
	v_max_i32_e32 v97, 0, v26
	v_fmac_f32_e32 v98, v58, v97
	v_max_i32_e32 v97, 0, v27
	v_fmac_f32_e32 v98, v59, v97
	v_max_i32_e32 v97, 0, v28
	v_fmac_f32_e32 v98, v60, v97
	v_max_i32_e32 v97, 0, v29
	v_fmac_f32_e32 v98, v61, v97
	v_mfma_f32_32x32x16_bf16 v[0:15], v[44:47], v[104:107], v[0:15]
	v_max_i32_e32 v97, 0, v30
	s_cmp_eq_u32 s60, 21
	v_fmac_f32_e32 v98, v62, v97
	v_max_i32_e32 v97, 0, v31
	s_cselect_b64 s[0:1], -1, 0
	v_cmp_gt_i32_e32 vcc, v147, v203
	v_fmac_f32_e32 v98, v63, v97
	s_and_b64 vcc, s[0:1], vcc
	v_cndmask_b32_e32 v214, v98, v197, vcc
	s_branch .LBB0_1859

.LBB0_1861:
	s_waitcnt lgkmcnt(0)
	ds_read_b128 v[96:99], v131 offset:0x7e00
	ds_read_b128 v[88:91], v131 offset:0x7e20
	ds_read_b128 v[80:83], v131 offset:0x7e40
	ds_read_b128 v[104:107], v131 offset:0x7e60
	s_cmp_gt_u32 s94, 43
	s_cselect_b64 s[66:67], -1, 0
	s_cmp_lt_u32 s94, 44
	s_cbranch_scc1 .LBB0_1863
	v_mfma_f32_32x32x16_bf16 v[16:31], v[32:35], v[100:103], 0
	v_cndmask_b32_e64 v101, 0, 1, s[68:69]
	v_cmp_ne_u32_e64 s[54:55], 1, v101
	s_andn2_b64 vcc, exec, s[68:69]
	v_max_i32_e32 v101, 0, v0
	v_fma_f32 v102, v48, v101, 0
	v_max_i32_e32 v101, 0, v1
	v_fmac_f32_e32 v102, v49, v101
	v_max_i32_e32 v101, 0, v2
	v_fmac_f32_e32 v102, v50, v101
	v_max_i32_e32 v101, 0, v3
	v_fmac_f32_e32 v102, v51, v101
	v_max_i32_e32 v101, 0, v4
	v_fmac_f32_e32 v102, v52, v101
	v_mfma_f32_32x32x16_bf16 v[16:31], v[36:39], v[92:95], v[16:31]
	v_max_i32_e32 v101, 0, v5
	v_fmac_f32_e32 v102, v53, v101
	v_max_i32_e32 v101, 0, v6
	v_fmac_f32_e32 v102, v54, v101
	v_max_i32_e32 v101, 0, v7
	v_fmac_f32_e32 v102, v55, v101
	v_max_i32_e32 v101, 0, v8
	v_fmac_f32_e32 v102, v56, v101
	v_max_i32_e32 v101, 0, v9
	v_fmac_f32_e32 v102, v57, v101
	v_mfma_f32_32x32x16_bf16 v[16:31], v[40:43], v[84:87], v[16:31]
	v_max_i32_e32 v101, 0, v10
	v_fmac_f32_e32 v102, v58, v101
	v_max_i32_e32 v101, 0, v11
	v_fmac_f32_e32 v102, v59, v101
	v_max_i32_e32 v101, 0, v12
	v_fmac_f32_e32 v102, v60, v101
	v_max_i32_e32 v101, 0, v13
	v_fmac_f32_e32 v102, v61, v101
	v_mfma_f32_32x32x16_bf16 v[16:31], v[44:47], v[108:111], v[16:31]
	v_max_i32_e32 v101, 0, v14
	s_cmp_eq_u32 s60, 22
	v_fmac_f32_e32 v102, v62, v101
	v_max_i32_e32 v101, 0, v15
	s_cselect_b64 s[0:1], -1, 0
	v_cmp_gt_i32_e32 vcc, v148, v203
	v_fmac_f32_e32 v102, v63, v101
	s_and_b64 vcc, s[0:1], vcc
	v_cndmask_b32_e32 v216, v102, v197, vcc
	s_branch .LBB0_1865

.LBB0_1867:
	s_waitcnt lgkmcnt(0)
	s_cmp_lt_u32 s94, 46
	s_cbranch_scc1 .LBB0_1869
	v_mfma_f32_32x32x16_bf16 v[0:15], v[32:35], v[96:99], 0
	v_cndmask_b32_e64 v97, 0, 1, s[66:67]
	v_cmp_ne_u32_e64 s[54:55], 1, v97
	s_andn2_b64 vcc, exec, s[66:67]
	v_max_i32_e32 v97, 0, v16
	v_fma_f32 v98, v48, v97, 0
	v_max_i32_e32 v97, 0, v17
	v_fmac_f32_e32 v98, v49, v97
	v_max_i32_e32 v97, 0, v18
	v_fmac_f32_e32 v98, v50, v97
	v_max_i32_e32 v97, 0, v19
	v_fmac_f32_e32 v98, v51, v97
	v_max_i32_e32 v97, 0, v20
	v_fmac_f32_e32 v98, v52, v97
	v_mfma_f32_32x32x16_bf16 v[0:15], v[36:39], v[88:91], v[0:15]
	v_max_i32_e32 v97, 0, v21
	v_fmac_f32_e32 v98, v53, v97
	v_max_i32_e32 v97, 0, v22
	v_fmac_f32_e32 v98, v54, v97
	v_max_i32_e32 v97, 0, v23
	v_fmac_f32_e32 v98, v55, v97
	v_max_i32_e32 v97, 0, v24
	v_fmac_f32_e32 v98, v56, v97
	v_max_i32_e32 v97, 0, v25
	v_fmac_f32_e32 v98, v57, v97
	v_mfma_f32_32x32x16_bf16 v[0:15], v[40:43], v[80:83], v[0:15]
	v_max_i32_e32 v97, 0, v26
	v_fmac_f32_e32 v98, v58, v97
	v_max_i32_e32 v97, 0, v27
	v_fmac_f32_e32 v98, v59, v97
	v_max_i32_e32 v97, 0, v28
	v_fmac_f32_e32 v98, v60, v97
	v_max_i32_e32 v97, 0, v29
	v_fmac_f32_e32 v98, v61, v97
	v_mfma_f32_32x32x16_bf16 v[0:15], v[44:47], v[104:107], v[0:15]
	v_max_i32_e32 v97, 0, v30
	s_cmp_eq_u32 s60, 23
	v_fmac_f32_e32 v98, v62, v97
	v_max_i32_e32 v97, 0, v31
	s_cselect_b64 s[0:1], -1, 0
	v_cmp_gt_i32_e32 vcc, v149, v203
	v_fmac_f32_e32 v98, v63, v97
	s_and_b64 vcc, s[0:1], vcc
	v_cndmask_b32_e32 v217, v98, v197, vcc
	s_branch .LBB0_1871

.LBB0_1879:
	ds_read_b128 v[16:19], v134 offset:0
	ds_read_b128 v[80:83], v134 offset:32
	ds_read_b128 v[84:87], v134 offset:64
	ds_read_b128 v[92:95], v134 offset:0x60
	v_max_i32_e32 v88, 0, v0
	s_waitcnt lgkmcnt(0)
	v_max_i32_e32 v89, 0, v1
	v_mfma_f32_32x32x16_bf16 v[16:31], v[32:35], v[16:19], 0
	v_fma_f32 v218, v48, v88, 0
	v_max_i32_e32 v90, 0, v2
	v_fmac_f32_e32 v218, v49, v89
	v_max_i32_e32 v91, 0, v3
	v_fmac_f32_e32 v218, v50, v90
	v_max_i32_e32 v96, 0, v4
	v_fmac_f32_e32 v218, v51, v91
	v_mfma_f32_32x32x16_bf16 v[16:31], v[36:39], v[80:83], v[16:31]
	v_max_i32_e32 v97, 0, v5
	v_fmac_f32_e32 v218, v52, v96
	v_max_i32_e32 v98, 0, v6
	v_fmac_f32_e32 v218, v53, v97
	v_max_i32_e32 v99, 0, v7
	v_fmac_f32_e32 v218, v54, v98
	v_max_i32_e32 v100, 0, v8
	v_mfma_f32_32x32x16_bf16 v[16:31], v[40:43], v[84:87], v[16:31]
	v_fmac_f32_e32 v218, v55, v99
	v_max_i32_e32 v101, 0, v9
	v_fmac_f32_e32 v218, v56, v100
	v_max_i32_e32 v102, 0, v10
	v_fmac_f32_e32 v218, v57, v101
	v_max_i32_e32 v103, 0, v11
	v_fmac_f32_e32 v218, v58, v102
	v_fmac_f32_e32 v218, v59, v103
	v_max_i32_e32 v84, 0, v12
	ds_read_b128 v[80:83], v134 offset:0x1200
	v_fmac_f32_e32 v218, v60, v84
	v_max_i32_e32 v84, 0, v13
	ds_read_b128 v[88:91], v134 offset:0x1220
	v_fmac_f32_e32 v218, v61, v84
	v_max_i32_e32 v84, 0, v14
	ds_read_b128 v[96:99], v134 offset:0x1240
	v_fmac_f32_e32 v218, v62, v84
	v_max_i32_e32 v84, 0, v15
	ds_read_b128 v[104:107], v134 offset:0x1260
	v_mfma_f32_32x32x16_bf16 v[16:31], v[44:47], v[92:95], v[16:31]
	v_fmac_f32_e32 v218, v63, v84
	s_waitcnt lgkmcnt(0)
	ds_read_b128 v[108:111], v134 offset:0x2400
	ds_read_b128 v[100:103], v134 offset:0x2420
	ds_read_b128 v[92:95], v134 offset:0x2440
	ds_read_b128 v[84:87], v134 offset:0x2460
	s_cmp_eq_u32 s60, 25
	s_cselect_b64 s[54:55], -1, 0
	s_cmp_lg_u32 s60, 25
	s_cselect_b64 s[0:1], -1, 0
	s_and_b64 vcc, exec, s[54:55]
	s_cbranch_vccnz .LBB0_1881
	v_mfma_f32_32x32x16_bf16 v[0:15], v[32:35], v[80:83], 0
	v_max_i32_e32 v81, 0, v16
	v_fma_f32 v82, v48, v81, 0
	v_max_i32_e32 v81, 0, v17
	v_fmac_f32_e32 v82, v49, v81
	v_max_i32_e32 v81, 0, v18
	v_fmac_f32_e32 v82, v50, v81
	v_max_i32_e32 v81, 0, v19
	v_fmac_f32_e32 v82, v51, v81
	v_max_i32_e32 v81, 0, v20
	v_fmac_f32_e32 v82, v52, v81
	v_mfma_f32_32x32x16_bf16 v[0:15], v[36:39], v[88:91], v[0:15]
	v_max_i32_e32 v81, 0, v21
	v_fmac_f32_e32 v82, v53, v81
	v_max_i32_e32 v81, 0, v22
	v_fmac_f32_e32 v82, v54, v81
	v_max_i32_e32 v81, 0, v23
	v_fmac_f32_e32 v82, v55, v81
	v_max_i32_e32 v81, 0, v24
	v_fmac_f32_e32 v82, v56, v81
	v_max_i32_e32 v81, 0, v25
	v_fmac_f32_e32 v82, v57, v81
	v_mfma_f32_32x32x16_bf16 v[0:15], v[40:43], v[96:99], v[0:15]
	v_max_i32_e32 v81, 0, v26
	v_fmac_f32_e32 v82, v58, v81
	v_max_i32_e32 v81, 0, v27
	v_fmac_f32_e32 v82, v59, v81
	v_max_i32_e32 v81, 0, v28
	v_fmac_f32_e32 v82, v60, v81
	v_max_i32_e32 v81, 0, v29
	v_fmac_f32_e32 v82, v61, v81
	v_mfma_f32_32x32x16_bf16 v[0:15], v[44:47], v[104:107], v[0:15]
	v_max_i32_e32 v81, 0, v30
	v_fmac_f32_e32 v82, v62, v81
	v_max_i32_e32 v81, 0, v31
	v_cmp_gt_i32_e32 vcc, v151, v203
	v_fmac_f32_e32 v82, v63, v81
	s_and_b64 vcc, s[54:55], vcc
	v_cndmask_b32_e32 v219, v82, v197, vcc
	s_branch .Lixj35

.Lixj35:
	s_waitcnt lgkmcnt(0)
	ds_read_b128 v[96:99], v134 offset:0x3600
	ds_read_b128 v[88:91], v134 offset:0x3620
	ds_read_b128 v[80:83], v134 offset:0x3640
	ds_read_b128 v[104:107], v134 offset:0x3660
	s_cmp_gt_u32 s94, 51
	s_cselect_b64 s[66:67], -1, 0
	s_cmp_lt_u32 s94, 52
	s_cbranch_scc1 .LBB0_1883
	v_mfma_f32_32x32x16_bf16 v[16:31], v[32:35], v[108:111], 0
	v_cndmask_b32_e64 v109, 0, 1, s[0:1]
	v_cmp_ne_u32_e64 s[54:55], 1, v109
	s_andn2_b64 vcc, exec, s[0:1]
	v_max_i32_e32 v109, 0, v0
	v_fma_f32 v110, v48, v109, 0
	v_max_i32_e32 v109, 0, v1
	v_fmac_f32_e32 v110, v49, v109
	v_max_i32_e32 v109, 0, v2
	v_fmac_f32_e32 v110, v50, v109
	v_max_i32_e32 v109, 0, v3
	v_fmac_f32_e32 v110, v51, v109
	v_max_i32_e32 v109, 0, v4
	v_fmac_f32_e32 v110, v52, v109
	v_mfma_f32_32x32x16_bf16 v[16:31], v[36:39], v[100:103], v[16:31]
	v_max_i32_e32 v109, 0, v5
	v_fmac_f32_e32 v110, v53, v109
	v_max_i32_e32 v109, 0, v6
	v_fmac_f32_e32 v110, v54, v109
	v_max_i32_e32 v109, 0, v7
	v_fmac_f32_e32 v110, v55, v109
	v_max_i32_e32 v109, 0, v8
	v_fmac_f32_e32 v110, v56, v109
	v_max_i32_e32 v109, 0, v9
	v_fmac_f32_e32 v110, v57, v109
	v_mfma_f32_32x32x16_bf16 v[16:31], v[40:43], v[92:95], v[16:31]
	v_max_i32_e32 v109, 0, v10
	v_fmac_f32_e32 v110, v58, v109
	v_max_i32_e32 v109, 0, v11
	v_fmac_f32_e32 v110, v59, v109
	v_max_i32_e32 v109, 0, v12
	v_fmac_f32_e32 v110, v60, v109
	v_max_i32_e32 v109, 0, v13
	v_fmac_f32_e32 v110, v61, v109
	v_mfma_f32_32x32x16_bf16 v[16:31], v[44:47], v[84:87], v[16:31]
	v_max_i32_e32 v109, 0, v14
	s_cmp_eq_u32 s60, 26
	v_fmac_f32_e32 v110, v62, v109
	v_max_i32_e32 v109, 0, v15
	s_cselect_b64 s[0:1], -1, 0
	v_cmp_gt_i32_e32 vcc, v152, v203
	v_fmac_f32_e32 v110, v63, v109
	s_and_b64 vcc, s[0:1], vcc
	v_cndmask_b32_e32 v220, v110, v197, vcc
	s_branch .LBB0_1885

.LBB0_1887:
	s_waitcnt lgkmcnt(0)
	ds_read_b128 v[100:103], v134 offset:0x4800
	ds_read_b128 v[92:95], v134 offset:0x4820
	ds_read_b128 v[84:87], v134 offset:0x4840
	ds_read_b128 v[108:111], v134 offset:0x4860
	s_cmp_gt_u32 s94, 53
	s_cselect_b64 s[68:69], -1, 0
	s_cmp_lt_u32 s94, 54
	s_cbranch_scc1 .LBB0_1889
	v_mfma_f32_32x32x16_bf16 v[0:15], v[32:35], v[96:99], 0
	v_cndmask_b32_e64 v97, 0, 1, s[66:67]
	v_cmp_ne_u32_e64 s[54:55], 1, v97
	s_andn2_b64 vcc, exec, s[66:67]
	v_max_i32_e32 v97, 0, v16
	v_fma_f32 v98, v48, v97, 0
	v_max_i32_e32 v97, 0, v17
	v_fmac_f32_e32 v98, v49, v97
	v_max_i32_e32 v97, 0, v18
	v_fmac_f32_e32 v98, v50, v97
	v_max_i32_e32 v97, 0, v19
	v_fmac_f32_e32 v98, v51, v97
	v_max_i32_e32 v97, 0, v20
	v_fmac_f32_e32 v98, v52, v97
	v_mfma_f32_32x32x16_bf16 v[0:15], v[36:39], v[88:91], v[0:15]
	v_max_i32_e32 v97, 0, v21
	v_fmac_f32_e32 v98, v53, v97
	v_max_i32_e32 v97, 0, v22
	v_fmac_f32_e32 v98, v54, v97
	v_max_i32_e32 v97, 0, v23
	v_fmac_f32_e32 v98, v55, v97
	v_max_i32_e32 v97, 0, v24
	v_fmac_f32_e32 v98, v56, v97
	v_max_i32_e32 v97, 0, v25
	v_fmac_f32_e32 v98, v57, v97
	v_mfma_f32_32x32x16_bf16 v[0:15], v[40:43], v[80:83], v[0:15]
	v_max_i32_e32 v97, 0, v26
	v_fmac_f32_e32 v98, v58, v97
	v_max_i32_e32 v97, 0, v27
	v_fmac_f32_e32 v98, v59, v97
	v_max_i32_e32 v97, 0, v28
	v_fmac_f32_e32 v98, v60, v97
	v_max_i32_e32 v97, 0, v29
	v_fmac_f32_e32 v98, v61, v97
	v_mfma_f32_32x32x16_bf16 v[0:15], v[44:47], v[104:107], v[0:15]
	v_max_i32_e32 v97, 0, v30
	s_cmp_eq_u32 s60, 27
	v_fmac_f32_e32 v98, v62, v97
	v_max_i32_e32 v97, 0, v31
	s_cselect_b64 s[0:1], -1, 0
	v_cmp_gt_i32_e32 vcc, v153, v203
	v_fmac_f32_e32 v98, v63, v97
	s_and_b64 vcc, s[0:1], vcc
	v_cndmask_b32_e32 v221, v98, v197, vcc
	s_branch .LBB0_1891

.LBB0_1893:
	s_waitcnt lgkmcnt(0)
	ds_read_b128 v[96:99], v134 offset:0x5a00
	ds_read_b128 v[88:91], v134 offset:0x5a20
	ds_read_b128 v[80:83], v134 offset:0x5a40
	ds_read_b128 v[104:107], v134 offset:0x5a60
	s_cmp_gt_u32 s94, 55
	s_cselect_b64 s[66:67], -1, 0
	s_cmp_lt_u32 s94, 56
	s_cbranch_scc1 .LBB0_1895
	v_mfma_f32_32x32x16_bf16 v[16:31], v[32:35], v[100:103], 0
	v_cndmask_b32_e64 v101, 0, 1, s[68:69]
	v_cmp_ne_u32_e64 s[54:55], 1, v101
	s_andn2_b64 vcc, exec, s[68:69]
	v_max_i32_e32 v101, 0, v0
	v_fma_f32 v102, v48, v101, 0
	v_max_i32_e32 v101, 0, v1
	v_fmac_f32_e32 v102, v49, v101
	v_max_i32_e32 v101, 0, v2
	v_fmac_f32_e32 v102, v50, v101
	v_max_i32_e32 v101, 0, v3
	v_fmac_f32_e32 v102, v51, v101
	v_max_i32_e32 v101, 0, v4
	v_fmac_f32_e32 v102, v52, v101
	v_mfma_f32_32x32x16_bf16 v[16:31], v[36:39], v[92:95], v[16:31]
	v_max_i32_e32 v101, 0, v5
	v_fmac_f32_e32 v102, v53, v101
	v_max_i32_e32 v101, 0, v6
	v_fmac_f32_e32 v102, v54, v101
	v_max_i32_e32 v101, 0, v7
	v_fmac_f32_e32 v102, v55, v101
	v_max_i32_e32 v101, 0, v8
	v_fmac_f32_e32 v102, v56, v101
	v_max_i32_e32 v101, 0, v9
	v_fmac_f32_e32 v102, v57, v101
	v_mfma_f32_32x32x16_bf16 v[16:31], v[40:43], v[84:87], v[16:31]
	v_max_i32_e32 v101, 0, v10
	v_fmac_f32_e32 v102, v58, v101
	v_max_i32_e32 v101, 0, v11
	v_fmac_f32_e32 v102, v59, v101
	v_max_i32_e32 v101, 0, v12
	v_fmac_f32_e32 v102, v60, v101
	v_max_i32_e32 v101, 0, v13
	v_fmac_f32_e32 v102, v61, v101
	v_mfma_f32_32x32x16_bf16 v[16:31], v[44:47], v[108:111], v[16:31]
	v_max_i32_e32 v101, 0, v14
	s_cmp_eq_u32 s60, 28
	v_fmac_f32_e32 v102, v62, v101
	v_max_i32_e32 v101, 0, v15
	s_cselect_b64 s[0:1], -1, 0
	v_cmp_gt_i32_e32 vcc, v154, v203
	v_fmac_f32_e32 v102, v63, v101
	s_and_b64 vcc, s[0:1], vcc
	v_cndmask_b32_e32 v222, v102, v197, vcc
	s_branch .LBB0_1897

.LBB0_1899:
	s_waitcnt lgkmcnt(0)
	ds_read_b128 v[100:103], v134 offset:0x6c00
	ds_read_b128 v[92:95], v134 offset:0x6c20
	ds_read_b128 v[84:87], v134 offset:0x6c40
	ds_read_b128 v[108:111], v134 offset:0x6c60
	s_cmp_gt_u32 s94, 57
	s_cselect_b64 s[68:69], -1, 0
	s_cmp_lt_u32 s94, 58
	s_cbranch_scc1 .LBB0_1901
	v_mfma_f32_32x32x16_bf16 v[0:15], v[32:35], v[96:99], 0
	v_cndmask_b32_e64 v97, 0, 1, s[66:67]
	v_cmp_ne_u32_e64 s[54:55], 1, v97
	s_andn2_b64 vcc, exec, s[66:67]
	v_max_i32_e32 v97, 0, v16
	v_fma_f32 v98, v48, v97, 0
	v_max_i32_e32 v97, 0, v17
	v_fmac_f32_e32 v98, v49, v97
	v_max_i32_e32 v97, 0, v18
	v_fmac_f32_e32 v98, v50, v97
	v_max_i32_e32 v97, 0, v19
	v_fmac_f32_e32 v98, v51, v97
	v_max_i32_e32 v97, 0, v20
	v_fmac_f32_e32 v98, v52, v97
	v_mfma_f32_32x32x16_bf16 v[0:15], v[36:39], v[88:91], v[0:15]
	v_max_i32_e32 v97, 0, v21
	v_fmac_f32_e32 v98, v53, v97
	v_max_i32_e32 v97, 0, v22
	v_fmac_f32_e32 v98, v54, v97
	v_max_i32_e32 v97, 0, v23
	v_fmac_f32_e32 v98, v55, v97
	v_max_i32_e32 v97, 0, v24
	v_fmac_f32_e32 v98, v56, v97
	v_max_i32_e32 v97, 0, v25
	v_fmac_f32_e32 v98, v57, v97
	v_mfma_f32_32x32x16_bf16 v[0:15], v[40:43], v[80:83], v[0:15]
	v_max_i32_e32 v97, 0, v26
	v_fmac_f32_e32 v98, v58, v97
	v_max_i32_e32 v97, 0, v27
	v_fmac_f32_e32 v98, v59, v97
	v_max_i32_e32 v97, 0, v28
	v_fmac_f32_e32 v98, v60, v97
	v_max_i32_e32 v97, 0, v29
	v_fmac_f32_e32 v98, v61, v97
	v_mfma_f32_32x32x16_bf16 v[0:15], v[44:47], v[104:107], v[0:15]
	v_max_i32_e32 v97, 0, v30
	s_cmp_eq_u32 s60, 29
	v_fmac_f32_e32 v98, v62, v97
	v_max_i32_e32 v97, 0, v31
	s_cselect_b64 s[0:1], -1, 0
	v_cmp_gt_i32_e32 vcc, v155, v203
	v_fmac_f32_e32 v98, v63, v97
	s_and_b64 vcc, s[0:1], vcc
	v_cndmask_b32_e32 v223, v98, v197, vcc
	s_branch .LBB0_1903

.LBB0_1905:
	s_waitcnt lgkmcnt(0)
	ds_read_b128 v[96:99], v134 offset:0x7e00
	ds_read_b128 v[88:91], v134 offset:0x7e20
	ds_read_b128 v[80:83], v134 offset:0x7e40
	ds_read_b128 v[104:107], v134 offset:0x7e60
	s_cmp_gt_u32 s94, 59
	s_cselect_b64 s[66:67], -1, 0
	s_cmp_lt_u32 s94, 60
	s_cbranch_scc1 .LBB0_1907
	v_mfma_f32_32x32x16_bf16 v[16:31], v[32:35], v[100:103], 0
	v_cndmask_b32_e64 v101, 0, 1, s[68:69]
	v_cmp_ne_u32_e64 s[54:55], 1, v101
	s_andn2_b64 vcc, exec, s[68:69]
	v_max_i32_e32 v101, 0, v0
	v_fma_f32 v102, v48, v101, 0
	v_max_i32_e32 v101, 0, v1
	v_fmac_f32_e32 v102, v49, v101
	v_max_i32_e32 v101, 0, v2
	v_fmac_f32_e32 v102, v50, v101
	v_max_i32_e32 v101, 0, v3
	v_fmac_f32_e32 v102, v51, v101
	v_max_i32_e32 v101, 0, v4
	v_fmac_f32_e32 v102, v52, v101
	v_mfma_f32_32x32x16_bf16 v[16:31], v[36:39], v[92:95], v[16:31]
	v_max_i32_e32 v101, 0, v5
	v_fmac_f32_e32 v102, v53, v101
	v_max_i32_e32 v101, 0, v6
	v_fmac_f32_e32 v102, v54, v101
	v_max_i32_e32 v101, 0, v7
	v_fmac_f32_e32 v102, v55, v101
	v_max_i32_e32 v101, 0, v8
	v_fmac_f32_e32 v102, v56, v101
	v_max_i32_e32 v101, 0, v9
	v_fmac_f32_e32 v102, v57, v101
	v_mfma_f32_32x32x16_bf16 v[16:31], v[40:43], v[84:87], v[16:31]
	v_max_i32_e32 v101, 0, v10
	v_fmac_f32_e32 v102, v58, v101
	v_max_i32_e32 v101, 0, v11
	v_fmac_f32_e32 v102, v59, v101
	v_max_i32_e32 v101, 0, v12
	v_fmac_f32_e32 v102, v60, v101
	v_max_i32_e32 v101, 0, v13
	v_fmac_f32_e32 v102, v61, v101
	v_mfma_f32_32x32x16_bf16 v[16:31], v[44:47], v[108:111], v[16:31]
	v_max_i32_e32 v101, 0, v14
	s_cmp_eq_u32 s60, 30
	v_fmac_f32_e32 v102, v62, v101
	v_max_i32_e32 v101, 0, v15
	s_cselect_b64 s[0:1], -1, 0
	v_cmp_gt_i32_e32 vcc, v156, v203
	v_fmac_f32_e32 v102, v63, v101
	s_and_b64 vcc, s[0:1], vcc
	v_cndmask_b32_e32 v224, v102, v197, vcc
	s_branch .LBB0_1909

.LBB0_1911:
	s_waitcnt lgkmcnt(0)
	s_cmp_lt_u32 s94, 62
	s_cbranch_scc1 .LBB0_1913
	v_mfma_f32_32x32x16_bf16 v[0:15], v[32:35], v[96:99], 0
	v_cndmask_b32_e64 v97, 0, 1, s[66:67]
	v_cmp_ne_u32_e64 s[54:55], 1, v97
	s_andn2_b64 vcc, exec, s[66:67]
	v_max_i32_e32 v97, 0, v16
	v_fma_f32 v98, v48, v97, 0
	v_max_i32_e32 v97, 0, v17
	v_fmac_f32_e32 v98, v49, v97
	v_max_i32_e32 v97, 0, v18
	v_fmac_f32_e32 v98, v50, v97
	v_max_i32_e32 v97, 0, v19
	v_fmac_f32_e32 v98, v51, v97
	v_max_i32_e32 v97, 0, v20
	v_fmac_f32_e32 v98, v52, v97
	v_mfma_f32_32x32x16_bf16 v[0:15], v[36:39], v[88:91], v[0:15]
	v_max_i32_e32 v97, 0, v21
	v_fmac_f32_e32 v98, v53, v97
	v_max_i32_e32 v97, 0, v22
	v_fmac_f32_e32 v98, v54, v97
	v_max_i32_e32 v97, 0, v23
	v_fmac_f32_e32 v98, v55, v97
	v_max_i32_e32 v97, 0, v24
	v_fmac_f32_e32 v98, v56, v97
	v_max_i32_e32 v97, 0, v25
	v_fmac_f32_e32 v98, v57, v97
	v_mfma_f32_32x32x16_bf16 v[0:15], v[40:43], v[80:83], v[0:15]
	v_max_i32_e32 v97, 0, v26
	v_fmac_f32_e32 v98, v58, v97
	v_max_i32_e32 v97, 0, v27
	v_fmac_f32_e32 v98, v59, v97
	v_max_i32_e32 v97, 0, v28
	v_fmac_f32_e32 v98, v60, v97
	v_max_i32_e32 v97, 0, v29
	v_fmac_f32_e32 v98, v61, v97
	v_mfma_f32_32x32x16_bf16 v[0:15], v[44:47], v[104:107], v[0:15]
	v_max_i32_e32 v97, 0, v30
	s_cmp_eq_u32 s60, 31
	v_fmac_f32_e32 v98, v62, v97
	v_max_i32_e32 v97, 0, v31
	s_cselect_b64 s[0:1], -1, 0
	v_cmp_gt_i32_e32 vcc, v157, v203
	v_fmac_f32_e32 v98, v63, v97
	s_and_b64 vcc, s[0:1], vcc
	v_cndmask_b32_e32 v225, v98, v197, vcc
	s_branch .LBB0_1915

.LBB0_1923:
	ds_read_b128 v[16:19], v131 offset:0
	ds_read_b128 v[80:83], v131 offset:32
	ds_read_b128 v[84:87], v131 offset:64
	ds_read_b128 v[92:95], v131 offset:0x60
	v_max_i32_e32 v88, 0, v0
	s_waitcnt lgkmcnt(0)
	v_max_i32_e32 v89, 0, v1
	v_mfma_f32_32x32x16_bf16 v[16:31], v[32:35], v[16:19], 0
	v_fma_f32 v226, v48, v88, 0
	v_max_i32_e32 v90, 0, v2
	v_fmac_f32_e32 v226, v49, v89
	v_max_i32_e32 v91, 0, v3
	v_fmac_f32_e32 v226, v50, v90
	v_max_i32_e32 v96, 0, v4
	v_fmac_f32_e32 v226, v51, v91
	v_mfma_f32_32x32x16_bf16 v[16:31], v[36:39], v[80:83], v[16:31]
	v_max_i32_e32 v97, 0, v5
	v_fmac_f32_e32 v226, v52, v96
	v_max_i32_e32 v98, 0, v6
	v_fmac_f32_e32 v226, v53, v97
	v_max_i32_e32 v99, 0, v7
	v_fmac_f32_e32 v226, v54, v98
	v_max_i32_e32 v100, 0, v8
	v_mfma_f32_32x32x16_bf16 v[16:31], v[40:43], v[84:87], v[16:31]
	v_fmac_f32_e32 v226, v55, v99
	v_max_i32_e32 v101, 0, v9
	v_fmac_f32_e32 v226, v56, v100
	v_max_i32_e32 v102, 0, v10
	v_fmac_f32_e32 v226, v57, v101
	v_max_i32_e32 v103, 0, v11
	v_fmac_f32_e32 v226, v58, v102
	v_fmac_f32_e32 v226, v59, v103
	v_max_i32_e32 v84, 0, v12
	ds_read_b128 v[80:83], v131 offset:0x1200
	v_fmac_f32_e32 v226, v60, v84
	v_max_i32_e32 v84, 0, v13
	ds_read_b128 v[88:91], v131 offset:0x1220
	v_fmac_f32_e32 v226, v61, v84
	v_max_i32_e32 v84, 0, v14
	ds_read_b128 v[96:99], v131 offset:0x1240
	v_fmac_f32_e32 v226, v62, v84
	v_max_i32_e32 v84, 0, v15
	ds_read_b128 v[104:107], v131 offset:0x1260
	v_mfma_f32_32x32x16_bf16 v[16:31], v[44:47], v[92:95], v[16:31]
	v_fmac_f32_e32 v226, v63, v84
	s_waitcnt lgkmcnt(0)
	ds_read_b128 v[108:111], v131 offset:0x2400
	ds_read_b128 v[100:103], v131 offset:0x2420
	ds_read_b128 v[92:95], v131 offset:0x2440
	ds_read_b128 v[84:87], v131 offset:0x2460
	s_cmp_eq_u32 s60, 33
	s_cselect_b64 s[54:55], -1, 0
	s_cmp_lg_u32 s60, 33
	s_cselect_b64 s[0:1], -1, 0
	s_and_b64 vcc, exec, s[54:55]
	s_cbranch_vccnz .LBB0_1925
	v_mfma_f32_32x32x16_bf16 v[0:15], v[32:35], v[80:83], 0
	v_max_i32_e32 v81, 0, v16
	v_fma_f32 v82, v48, v81, 0
	v_max_i32_e32 v81, 0, v17
	v_fmac_f32_e32 v82, v49, v81
	v_max_i32_e32 v81, 0, v18
	v_fmac_f32_e32 v82, v50, v81
	v_max_i32_e32 v81, 0, v19
	v_fmac_f32_e32 v82, v51, v81
	v_max_i32_e32 v81, 0, v20
	v_fmac_f32_e32 v82, v52, v81
	v_mfma_f32_32x32x16_bf16 v[0:15], v[36:39], v[88:91], v[0:15]
	v_max_i32_e32 v81, 0, v21
	v_fmac_f32_e32 v82, v53, v81
	v_max_i32_e32 v81, 0, v22
	v_fmac_f32_e32 v82, v54, v81
	v_max_i32_e32 v81, 0, v23
	v_fmac_f32_e32 v82, v55, v81
	v_max_i32_e32 v81, 0, v24
	v_fmac_f32_e32 v82, v56, v81
	v_max_i32_e32 v81, 0, v25
	v_fmac_f32_e32 v82, v57, v81
	v_mfma_f32_32x32x16_bf16 v[0:15], v[40:43], v[96:99], v[0:15]
	v_max_i32_e32 v81, 0, v26
	v_fmac_f32_e32 v82, v58, v81
	v_max_i32_e32 v81, 0, v27
	v_fmac_f32_e32 v82, v59, v81
	v_max_i32_e32 v81, 0, v28
	v_fmac_f32_e32 v82, v60, v81
	v_max_i32_e32 v81, 0, v29
	v_fmac_f32_e32 v82, v61, v81
	v_mfma_f32_32x32x16_bf16 v[0:15], v[44:47], v[104:107], v[0:15]
	v_max_i32_e32 v81, 0, v30
	v_fmac_f32_e32 v82, v62, v81
	v_max_i32_e32 v81, 0, v31
	v_cmp_gt_i32_e32 vcc, v159, v203
	v_fmac_f32_e32 v82, v63, v81
	s_and_b64 vcc, s[54:55], vcc
	v_cndmask_b32_e32 v227, v82, v197, vcc
	s_branch .Lixj28

.Lixj28:
	s_waitcnt lgkmcnt(0)
	ds_read_b128 v[96:99], v131 offset:0x3600
	ds_read_b128 v[88:91], v131 offset:0x3620
	ds_read_b128 v[80:83], v131 offset:0x3640
	ds_read_b128 v[104:107], v131 offset:0x3660
	s_cmpk_gt_u32 s94, 0x43
	s_cselect_b64 s[66:67], -1, 0
	s_cmpk_lt_u32 s94, 0x44
	s_cbranch_scc1 .LBB0_1927
	v_mfma_f32_32x32x16_bf16 v[16:31], v[32:35], v[108:111], 0
	v_cndmask_b32_e64 v109, 0, 1, s[0:1]
	v_cmp_ne_u32_e64 s[54:55], 1, v109
	s_andn2_b64 vcc, exec, s[0:1]
	v_max_i32_e32 v109, 0, v0
	v_fma_f32 v110, v48, v109, 0
	v_max_i32_e32 v109, 0, v1
	v_fmac_f32_e32 v110, v49, v109
	v_max_i32_e32 v109, 0, v2
	v_fmac_f32_e32 v110, v50, v109
	v_max_i32_e32 v109, 0, v3
	v_fmac_f32_e32 v110, v51, v109
	v_max_i32_e32 v109, 0, v4
	v_fmac_f32_e32 v110, v52, v109
	v_mfma_f32_32x32x16_bf16 v[16:31], v[36:39], v[100:103], v[16:31]
	v_max_i32_e32 v109, 0, v5
	v_fmac_f32_e32 v110, v53, v109
	v_max_i32_e32 v109, 0, v6
	v_fmac_f32_e32 v110, v54, v109
	v_max_i32_e32 v109, 0, v7
	v_fmac_f32_e32 v110, v55, v109
	v_max_i32_e32 v109, 0, v8
	v_fmac_f32_e32 v110, v56, v109
	v_max_i32_e32 v109, 0, v9
	v_fmac_f32_e32 v110, v57, v109
	v_mfma_f32_32x32x16_bf16 v[16:31], v[40:43], v[92:95], v[16:31]
	v_max_i32_e32 v109, 0, v10
	v_fmac_f32_e32 v110, v58, v109
	v_max_i32_e32 v109, 0, v11
	v_fmac_f32_e32 v110, v59, v109
	v_max_i32_e32 v109, 0, v12
	v_fmac_f32_e32 v110, v60, v109
	v_max_i32_e32 v109, 0, v13
	v_fmac_f32_e32 v110, v61, v109
	v_mfma_f32_32x32x16_bf16 v[16:31], v[44:47], v[84:87], v[16:31]
	v_max_i32_e32 v109, 0, v14
	s_cmp_eq_u32 s60, 34
	v_fmac_f32_e32 v110, v62, v109
	v_max_i32_e32 v109, 0, v15
	s_cselect_b64 s[0:1], -1, 0
	v_cmp_gt_i32_e32 vcc, v160, v203
	v_fmac_f32_e32 v110, v63, v109
	s_and_b64 vcc, s[0:1], vcc
	v_cndmask_b32_e32 v228, v110, v197, vcc
	s_branch .LBB0_1929

.LBB0_1931:
	s_waitcnt lgkmcnt(0)
	ds_read_b128 v[100:103], v131 offset:0x4800
	ds_read_b128 v[92:95], v131 offset:0x4820
	ds_read_b128 v[84:87], v131 offset:0x4840
	ds_read_b128 v[108:111], v131 offset:0x4860
	s_cmpk_gt_u32 s94, 0x45
	s_cselect_b64 s[68:69], -1, 0
	s_cmpk_lt_u32 s94, 0x46
	s_cbranch_scc1 .LBB0_1933
	v_mfma_f32_32x32x16_bf16 v[0:15], v[32:35], v[96:99], 0
	v_cndmask_b32_e64 v97, 0, 1, s[66:67]
	v_cmp_ne_u32_e64 s[54:55], 1, v97
	s_andn2_b64 vcc, exec, s[66:67]
	v_max_i32_e32 v97, 0, v16
	v_fma_f32 v98, v48, v97, 0
	v_max_i32_e32 v97, 0, v17
	v_fmac_f32_e32 v98, v49, v97
	v_max_i32_e32 v97, 0, v18
	v_fmac_f32_e32 v98, v50, v97
	v_max_i32_e32 v97, 0, v19
	v_fmac_f32_e32 v98, v51, v97
	v_max_i32_e32 v97, 0, v20
	v_fmac_f32_e32 v98, v52, v97
	v_mfma_f32_32x32x16_bf16 v[0:15], v[36:39], v[88:91], v[0:15]
	v_max_i32_e32 v97, 0, v21
	v_fmac_f32_e32 v98, v53, v97
	v_max_i32_e32 v97, 0, v22
	v_fmac_f32_e32 v98, v54, v97
	v_max_i32_e32 v97, 0, v23
	v_fmac_f32_e32 v98, v55, v97
	v_max_i32_e32 v97, 0, v24
	v_fmac_f32_e32 v98, v56, v97
	v_max_i32_e32 v97, 0, v25
	v_fmac_f32_e32 v98, v57, v97
	v_mfma_f32_32x32x16_bf16 v[0:15], v[40:43], v[80:83], v[0:15]
	v_max_i32_e32 v97, 0, v26
	v_fmac_f32_e32 v98, v58, v97
	v_max_i32_e32 v97, 0, v27
	v_fmac_f32_e32 v98, v59, v97
	v_max_i32_e32 v97, 0, v28
	v_fmac_f32_e32 v98, v60, v97
	v_max_i32_e32 v97, 0, v29
	v_fmac_f32_e32 v98, v61, v97
	v_mfma_f32_32x32x16_bf16 v[0:15], v[44:47], v[104:107], v[0:15]
	v_max_i32_e32 v97, 0, v30
	s_cmp_eq_u32 s60, 35
	v_fmac_f32_e32 v98, v62, v97
	v_max_i32_e32 v97, 0, v31
	s_cselect_b64 s[0:1], -1, 0
	v_cmp_gt_i32_e32 vcc, v161, v203
	v_fmac_f32_e32 v98, v63, v97
	s_and_b64 vcc, s[0:1], vcc
	v_cndmask_b32_e32 v229, v98, v197, vcc
	s_branch .LBB0_1935

.LBB0_1937:
	s_waitcnt lgkmcnt(0)
	ds_read_b128 v[96:99], v131 offset:0x5a00
	ds_read_b128 v[88:91], v131 offset:0x5a20
	ds_read_b128 v[80:83], v131 offset:0x5a40
	ds_read_b128 v[104:107], v131 offset:0x5a60
	s_cmpk_gt_u32 s94, 0x47
	s_cselect_b64 s[66:67], -1, 0
	s_cmpk_lt_u32 s94, 0x48
	s_cbranch_scc1 .LBB0_1939
	v_mfma_f32_32x32x16_bf16 v[16:31], v[32:35], v[100:103], 0
	v_cndmask_b32_e64 v101, 0, 1, s[68:69]
	v_cmp_ne_u32_e64 s[54:55], 1, v101
	s_andn2_b64 vcc, exec, s[68:69]
	v_max_i32_e32 v101, 0, v0
	v_fma_f32 v102, v48, v101, 0
	v_max_i32_e32 v101, 0, v1
	v_fmac_f32_e32 v102, v49, v101
	v_max_i32_e32 v101, 0, v2
	v_fmac_f32_e32 v102, v50, v101
	v_max_i32_e32 v101, 0, v3
	v_fmac_f32_e32 v102, v51, v101
	v_max_i32_e32 v101, 0, v4
	v_fmac_f32_e32 v102, v52, v101
	v_mfma_f32_32x32x16_bf16 v[16:31], v[36:39], v[92:95], v[16:31]
	v_max_i32_e32 v101, 0, v5
	v_fmac_f32_e32 v102, v53, v101
	v_max_i32_e32 v101, 0, v6
	v_fmac_f32_e32 v102, v54, v101
	v_max_i32_e32 v101, 0, v7
	v_fmac_f32_e32 v102, v55, v101
	v_max_i32_e32 v101, 0, v8
	v_fmac_f32_e32 v102, v56, v101
	v_max_i32_e32 v101, 0, v9
	v_fmac_f32_e32 v102, v57, v101
	v_mfma_f32_32x32x16_bf16 v[16:31], v[40:43], v[84:87], v[16:31]
	v_max_i32_e32 v101, 0, v10
	v_fmac_f32_e32 v102, v58, v101
	v_max_i32_e32 v101, 0, v11
	v_fmac_f32_e32 v102, v59, v101
	v_max_i32_e32 v101, 0, v12
	v_fmac_f32_e32 v102, v60, v101
	v_max_i32_e32 v101, 0, v13
	v_fmac_f32_e32 v102, v61, v101
	v_mfma_f32_32x32x16_bf16 v[16:31], v[44:47], v[108:111], v[16:31]
	v_max_i32_e32 v101, 0, v14
	s_cmp_eq_u32 s60, 36
	v_fmac_f32_e32 v102, v62, v101
	v_max_i32_e32 v101, 0, v15
	s_cselect_b64 s[0:1], -1, 0
	v_cmp_gt_i32_e32 vcc, v162, v203
	v_fmac_f32_e32 v102, v63, v101
	s_and_b64 vcc, s[0:1], vcc
	v_cndmask_b32_e32 v230, v102, v197, vcc
	s_branch .LBB0_1941

.LBB0_1943:
	s_waitcnt lgkmcnt(0)
	ds_read_b128 v[100:103], v131 offset:0x6c00
	ds_read_b128 v[92:95], v131 offset:0x6c20
	ds_read_b128 v[84:87], v131 offset:0x6c40
	ds_read_b128 v[108:111], v131 offset:0x6c60
	s_cmpk_gt_u32 s94, 0x49
	s_cselect_b64 s[68:69], -1, 0
	s_cmpk_lt_u32 s94, 0x4a
	s_cbranch_scc1 .LBB0_1945
	v_mfma_f32_32x32x16_bf16 v[0:15], v[32:35], v[96:99], 0
	v_cndmask_b32_e64 v97, 0, 1, s[66:67]
	v_cmp_ne_u32_e64 s[54:55], 1, v97
	s_andn2_b64 vcc, exec, s[66:67]
	v_max_i32_e32 v97, 0, v16
	v_fma_f32 v98, v48, v97, 0
	v_max_i32_e32 v97, 0, v17
	v_fmac_f32_e32 v98, v49, v97
	v_max_i32_e32 v97, 0, v18
	v_fmac_f32_e32 v98, v50, v97
	v_max_i32_e32 v97, 0, v19
	v_fmac_f32_e32 v98, v51, v97
	v_max_i32_e32 v97, 0, v20
	v_fmac_f32_e32 v98, v52, v97
	v_mfma_f32_32x32x16_bf16 v[0:15], v[36:39], v[88:91], v[0:15]
	v_max_i32_e32 v97, 0, v21
	v_fmac_f32_e32 v98, v53, v97
	v_max_i32_e32 v97, 0, v22
	v_fmac_f32_e32 v98, v54, v97
	v_max_i32_e32 v97, 0, v23
	v_fmac_f32_e32 v98, v55, v97
	v_max_i32_e32 v97, 0, v24
	v_fmac_f32_e32 v98, v56, v97
	v_max_i32_e32 v97, 0, v25
	v_fmac_f32_e32 v98, v57, v97
	v_mfma_f32_32x32x16_bf16 v[0:15], v[40:43], v[80:83], v[0:15]
	v_max_i32_e32 v97, 0, v26
	v_fmac_f32_e32 v98, v58, v97
	v_max_i32_e32 v97, 0, v27
	v_fmac_f32_e32 v98, v59, v97
	v_max_i32_e32 v97, 0, v28
	v_fmac_f32_e32 v98, v60, v97
	v_max_i32_e32 v97, 0, v29
	v_fmac_f32_e32 v98, v61, v97
	v_mfma_f32_32x32x16_bf16 v[0:15], v[44:47], v[104:107], v[0:15]
	v_max_i32_e32 v97, 0, v30
	s_cmp_eq_u32 s60, 37
	v_fmac_f32_e32 v98, v62, v97
	v_max_i32_e32 v97, 0, v31
	s_cselect_b64 s[0:1], -1, 0
	v_cmp_gt_i32_e32 vcc, v163, v203
	v_fmac_f32_e32 v98, v63, v97
	s_and_b64 vcc, s[0:1], vcc
	v_cndmask_b32_e32 v231, v98, v197, vcc
	s_branch .LBB0_1947

.LBB0_1949:
	s_waitcnt lgkmcnt(0)
	ds_read_b128 v[96:99], v131 offset:0x7e00
	ds_read_b128 v[88:91], v131 offset:0x7e20
	ds_read_b128 v[80:83], v131 offset:0x7e40
	ds_read_b128 v[104:107], v131 offset:0x7e60
	s_cmpk_gt_u32 s94, 0x4b
	s_cselect_b64 s[66:67], -1, 0
	s_cmpk_lt_u32 s94, 0x4c
	s_cbranch_scc1 .LBB0_1951
	v_mfma_f32_32x32x16_bf16 v[16:31], v[32:35], v[100:103], 0
	v_cndmask_b32_e64 v101, 0, 1, s[68:69]
	v_cmp_ne_u32_e64 s[54:55], 1, v101
	s_andn2_b64 vcc, exec, s[68:69]
	v_max_i32_e32 v101, 0, v0
	v_fma_f32 v102, v48, v101, 0
	v_max_i32_e32 v101, 0, v1
	v_fmac_f32_e32 v102, v49, v101
	v_max_i32_e32 v101, 0, v2
	v_fmac_f32_e32 v102, v50, v101
	v_max_i32_e32 v101, 0, v3
	v_fmac_f32_e32 v102, v51, v101
	v_max_i32_e32 v101, 0, v4
	v_fmac_f32_e32 v102, v52, v101
	v_mfma_f32_32x32x16_bf16 v[16:31], v[36:39], v[92:95], v[16:31]
	v_max_i32_e32 v101, 0, v5
	v_fmac_f32_e32 v102, v53, v101
	v_max_i32_e32 v101, 0, v6
	v_fmac_f32_e32 v102, v54, v101
	v_max_i32_e32 v101, 0, v7
	v_fmac_f32_e32 v102, v55, v101
	v_max_i32_e32 v101, 0, v8
	v_fmac_f32_e32 v102, v56, v101
	v_max_i32_e32 v101, 0, v9
	v_fmac_f32_e32 v102, v57, v101
	v_mfma_f32_32x32x16_bf16 v[16:31], v[40:43], v[84:87], v[16:31]
	v_max_i32_e32 v101, 0, v10
	v_fmac_f32_e32 v102, v58, v101
	v_max_i32_e32 v101, 0, v11
	v_fmac_f32_e32 v102, v59, v101
	v_max_i32_e32 v101, 0, v12
	v_fmac_f32_e32 v102, v60, v101
	v_max_i32_e32 v101, 0, v13
	v_fmac_f32_e32 v102, v61, v101
	v_mfma_f32_32x32x16_bf16 v[16:31], v[44:47], v[108:111], v[16:31]
	v_max_i32_e32 v101, 0, v14
	s_cmp_eq_u32 s60, 38
	v_fmac_f32_e32 v102, v62, v101
	v_max_i32_e32 v101, 0, v15
	s_cselect_b64 s[0:1], -1, 0
	v_cmp_gt_i32_e32 vcc, v164, v203
	v_fmac_f32_e32 v102, v63, v101
	s_and_b64 vcc, s[0:1], vcc
	v_cndmask_b32_e32 v232, v102, v197, vcc
	s_branch .LBB0_1953

.LBB0_1955:
	s_waitcnt lgkmcnt(0)
	s_cmpk_lt_u32 s94, 0x4e
	s_cbranch_scc1 .LBB0_1957
	v_mfma_f32_32x32x16_bf16 v[0:15], v[32:35], v[96:99], 0
	v_cndmask_b32_e64 v97, 0, 1, s[66:67]
	v_cmp_ne_u32_e64 s[54:55], 1, v97
	s_andn2_b64 vcc, exec, s[66:67]
	v_max_i32_e32 v97, 0, v16
	v_fma_f32 v98, v48, v97, 0
	v_max_i32_e32 v97, 0, v17
	v_fmac_f32_e32 v98, v49, v97
	v_max_i32_e32 v97, 0, v18
	v_fmac_f32_e32 v98, v50, v97
	v_max_i32_e32 v97, 0, v19
	v_fmac_f32_e32 v98, v51, v97
	v_max_i32_e32 v97, 0, v20
	v_fmac_f32_e32 v98, v52, v97
	v_mfma_f32_32x32x16_bf16 v[0:15], v[36:39], v[88:91], v[0:15]
	v_max_i32_e32 v97, 0, v21
	v_fmac_f32_e32 v98, v53, v97
	v_max_i32_e32 v97, 0, v22
	v_fmac_f32_e32 v98, v54, v97
	v_max_i32_e32 v97, 0, v23
	v_fmac_f32_e32 v98, v55, v97
	v_max_i32_e32 v97, 0, v24
	v_fmac_f32_e32 v98, v56, v97
	v_max_i32_e32 v97, 0, v25
	v_fmac_f32_e32 v98, v57, v97
	v_mfma_f32_32x32x16_bf16 v[0:15], v[40:43], v[80:83], v[0:15]
	v_max_i32_e32 v97, 0, v26
	v_fmac_f32_e32 v98, v58, v97
	v_max_i32_e32 v97, 0, v27
	v_fmac_f32_e32 v98, v59, v97
	v_max_i32_e32 v97, 0, v28
	v_fmac_f32_e32 v98, v60, v97
	v_max_i32_e32 v97, 0, v29
	v_fmac_f32_e32 v98, v61, v97
	v_mfma_f32_32x32x16_bf16 v[0:15], v[44:47], v[104:107], v[0:15]
	v_max_i32_e32 v97, 0, v30
	s_cmp_eq_u32 s60, 39
	v_fmac_f32_e32 v98, v62, v97
	v_max_i32_e32 v97, 0, v31
	s_cselect_b64 s[0:1], -1, 0
	v_cmp_gt_i32_e32 vcc, v165, v203
	v_fmac_f32_e32 v98, v63, v97
	s_and_b64 vcc, s[0:1], vcc
	v_cndmask_b32_e32 v233, v98, v197, vcc
	s_branch .LBB0_1959

.LBB0_1967:
	ds_read_b128 v[16:19], v134 offset:0
	ds_read_b128 v[80:83], v134 offset:32
	ds_read_b128 v[84:87], v134 offset:64
	ds_read_b128 v[92:95], v134 offset:0x60
	v_max_i32_e32 v88, 0, v0
	s_waitcnt lgkmcnt(0)
	v_max_i32_e32 v89, 0, v1
	v_mfma_f32_32x32x16_bf16 v[16:31], v[32:35], v[16:19], 0
	v_fma_f32 v234, v48, v88, 0
	v_max_i32_e32 v90, 0, v2
	v_fmac_f32_e32 v234, v49, v89
	v_max_i32_e32 v91, 0, v3
	v_fmac_f32_e32 v234, v50, v90
	v_max_i32_e32 v96, 0, v4
	v_fmac_f32_e32 v234, v51, v91
	v_mfma_f32_32x32x16_bf16 v[16:31], v[36:39], v[80:83], v[16:31]
	v_max_i32_e32 v97, 0, v5
	v_fmac_f32_e32 v234, v52, v96
	v_max_i32_e32 v98, 0, v6
	v_fmac_f32_e32 v234, v53, v97
	v_max_i32_e32 v99, 0, v7
	v_fmac_f32_e32 v234, v54, v98
	v_max_i32_e32 v100, 0, v8
	v_mfma_f32_32x32x16_bf16 v[16:31], v[40:43], v[84:87], v[16:31]
	v_fmac_f32_e32 v234, v55, v99
	v_max_i32_e32 v101, 0, v9
	v_fmac_f32_e32 v234, v56, v100
	v_max_i32_e32 v102, 0, v10
	v_fmac_f32_e32 v234, v57, v101
	v_max_i32_e32 v103, 0, v11
	v_fmac_f32_e32 v234, v58, v102
	v_fmac_f32_e32 v234, v59, v103
	v_max_i32_e32 v84, 0, v12
	ds_read_b128 v[80:83], v134 offset:0x1200
	v_fmac_f32_e32 v234, v60, v84
	v_max_i32_e32 v84, 0, v13
	ds_read_b128 v[88:91], v134 offset:0x1220
	v_fmac_f32_e32 v234, v61, v84
	v_max_i32_e32 v84, 0, v14
	ds_read_b128 v[96:99], v134 offset:0x1240
	v_fmac_f32_e32 v234, v62, v84
	v_max_i32_e32 v84, 0, v15
	ds_read_b128 v[104:107], v134 offset:0x1260
	v_mfma_f32_32x32x16_bf16 v[16:31], v[44:47], v[92:95], v[16:31]
	v_fmac_f32_e32 v234, v63, v84
	s_waitcnt lgkmcnt(0)
	ds_read_b128 v[108:111], v134 offset:0x2400
	ds_read_b128 v[100:103], v134 offset:0x2420
	ds_read_b128 v[92:95], v134 offset:0x2440
	ds_read_b128 v[84:87], v134 offset:0x2460
	s_cmp_eq_u32 s60, 41
	s_cselect_b64 s[54:55], -1, 0
	s_cmp_lg_u32 s60, 41
	s_cselect_b64 s[0:1], -1, 0
	s_and_b64 vcc, exec, s[54:55]
	s_cbranch_vccnz .LBB0_1969
	v_mfma_f32_32x32x16_bf16 v[0:15], v[32:35], v[80:83], 0
	v_max_i32_e32 v81, 0, v16
	v_fma_f32 v82, v48, v81, 0
	v_max_i32_e32 v81, 0, v17
	v_fmac_f32_e32 v82, v49, v81
	v_max_i32_e32 v81, 0, v18
	v_fmac_f32_e32 v82, v50, v81
	v_max_i32_e32 v81, 0, v19
	v_fmac_f32_e32 v82, v51, v81
	v_max_i32_e32 v81, 0, v20
	v_fmac_f32_e32 v82, v52, v81
	v_mfma_f32_32x32x16_bf16 v[0:15], v[36:39], v[88:91], v[0:15]
	v_max_i32_e32 v81, 0, v21
	v_fmac_f32_e32 v82, v53, v81
	v_max_i32_e32 v81, 0, v22
	v_fmac_f32_e32 v82, v54, v81
	v_max_i32_e32 v81, 0, v23
	v_fmac_f32_e32 v82, v55, v81
	v_max_i32_e32 v81, 0, v24
	v_fmac_f32_e32 v82, v56, v81
	v_max_i32_e32 v81, 0, v25
	v_fmac_f32_e32 v82, v57, v81
	v_mfma_f32_32x32x16_bf16 v[0:15], v[40:43], v[96:99], v[0:15]
	v_max_i32_e32 v81, 0, v26
	v_fmac_f32_e32 v82, v58, v81
	v_max_i32_e32 v81, 0, v27
	v_fmac_f32_e32 v82, v59, v81
	v_max_i32_e32 v81, 0, v28
	v_fmac_f32_e32 v82, v60, v81
	v_max_i32_e32 v81, 0, v29
	v_fmac_f32_e32 v82, v61, v81
	v_mfma_f32_32x32x16_bf16 v[0:15], v[44:47], v[104:107], v[0:15]
	v_max_i32_e32 v81, 0, v30
	v_fmac_f32_e32 v82, v62, v81
	v_max_i32_e32 v81, 0, v31
	v_cmp_gt_i32_e32 vcc, v167, v203
	v_fmac_f32_e32 v82, v63, v81
	s_and_b64 vcc, s[54:55], vcc
	v_cndmask_b32_e32 v235, v82, v197, vcc
	s_branch .Lixj21

.Lixj21:
	s_waitcnt lgkmcnt(0)
	ds_read_b128 v[96:99], v134 offset:0x3600
	ds_read_b128 v[88:91], v134 offset:0x3620
	ds_read_b128 v[80:83], v134 offset:0x3640
	ds_read_b128 v[104:107], v134 offset:0x3660
	s_cmpk_gt_u32 s94, 0x53
	s_cselect_b64 s[66:67], -1, 0
	s_cmpk_lt_u32 s94, 0x54
	s_cbranch_scc1 .LBB0_1971
	v_mfma_f32_32x32x16_bf16 v[16:31], v[32:35], v[108:111], 0
	v_cndmask_b32_e64 v109, 0, 1, s[0:1]
	v_cmp_ne_u32_e64 s[54:55], 1, v109
	s_andn2_b64 vcc, exec, s[0:1]
	v_max_i32_e32 v109, 0, v0
	v_fma_f32 v110, v48, v109, 0
	v_max_i32_e32 v109, 0, v1
	v_fmac_f32_e32 v110, v49, v109
	v_max_i32_e32 v109, 0, v2
	v_fmac_f32_e32 v110, v50, v109
	v_max_i32_e32 v109, 0, v3
	v_fmac_f32_e32 v110, v51, v109
	v_max_i32_e32 v109, 0, v4
	v_fmac_f32_e32 v110, v52, v109
	v_mfma_f32_32x32x16_bf16 v[16:31], v[36:39], v[100:103], v[16:31]
	v_max_i32_e32 v109, 0, v5
	v_fmac_f32_e32 v110, v53, v109
	v_max_i32_e32 v109, 0, v6
	v_fmac_f32_e32 v110, v54, v109
	v_max_i32_e32 v109, 0, v7
	v_fmac_f32_e32 v110, v55, v109
	v_max_i32_e32 v109, 0, v8
	v_fmac_f32_e32 v110, v56, v109
	v_max_i32_e32 v109, 0, v9
	v_fmac_f32_e32 v110, v57, v109
	v_mfma_f32_32x32x16_bf16 v[16:31], v[40:43], v[92:95], v[16:31]
	v_max_i32_e32 v109, 0, v10
	v_fmac_f32_e32 v110, v58, v109
	v_max_i32_e32 v109, 0, v11
	v_fmac_f32_e32 v110, v59, v109
	v_max_i32_e32 v109, 0, v12
	v_fmac_f32_e32 v110, v60, v109
	v_max_i32_e32 v109, 0, v13
	v_fmac_f32_e32 v110, v61, v109
	v_mfma_f32_32x32x16_bf16 v[16:31], v[44:47], v[84:87], v[16:31]
	v_max_i32_e32 v109, 0, v14
	s_cmp_eq_u32 s60, 42
	v_fmac_f32_e32 v110, v62, v109
	v_max_i32_e32 v109, 0, v15
	s_cselect_b64 s[0:1], -1, 0
	v_cmp_gt_i32_e32 vcc, v168, v203
	v_fmac_f32_e32 v110, v63, v109
	s_and_b64 vcc, s[0:1], vcc
	v_cndmask_b32_e32 v236, v110, v197, vcc
	s_branch .LBB0_1973

.LBB0_1975:
	s_waitcnt lgkmcnt(0)
	ds_read_b128 v[100:103], v134 offset:0x4800
	ds_read_b128 v[92:95], v134 offset:0x4820
	ds_read_b128 v[84:87], v134 offset:0x4840
	ds_read_b128 v[108:111], v134 offset:0x4860
	s_cmpk_gt_u32 s94, 0x55
	s_cselect_b64 s[68:69], -1, 0
	s_cmpk_lt_u32 s94, 0x56
	s_cbranch_scc1 .LBB0_1977
	v_mfma_f32_32x32x16_bf16 v[0:15], v[32:35], v[96:99], 0
	v_cndmask_b32_e64 v97, 0, 1, s[66:67]
	v_cmp_ne_u32_e64 s[54:55], 1, v97
	s_andn2_b64 vcc, exec, s[66:67]
	v_max_i32_e32 v97, 0, v16
	v_fma_f32 v98, v48, v97, 0
	v_max_i32_e32 v97, 0, v17
	v_fmac_f32_e32 v98, v49, v97
	v_max_i32_e32 v97, 0, v18
	v_fmac_f32_e32 v98, v50, v97
	v_max_i32_e32 v97, 0, v19
	v_fmac_f32_e32 v98, v51, v97
	v_max_i32_e32 v97, 0, v20
	v_fmac_f32_e32 v98, v52, v97
	v_mfma_f32_32x32x16_bf16 v[0:15], v[36:39], v[88:91], v[0:15]
	v_max_i32_e32 v97, 0, v21
	v_fmac_f32_e32 v98, v53, v97
	v_max_i32_e32 v97, 0, v22
	v_fmac_f32_e32 v98, v54, v97
	v_max_i32_e32 v97, 0, v23
	v_fmac_f32_e32 v98, v55, v97
	v_max_i32_e32 v97, 0, v24
	v_fmac_f32_e32 v98, v56, v97
	v_max_i32_e32 v97, 0, v25
	v_fmac_f32_e32 v98, v57, v97
	v_mfma_f32_32x32x16_bf16 v[0:15], v[40:43], v[80:83], v[0:15]
	v_max_i32_e32 v97, 0, v26
	v_fmac_f32_e32 v98, v58, v97
	v_max_i32_e32 v97, 0, v27
	v_fmac_f32_e32 v98, v59, v97
	v_max_i32_e32 v97, 0, v28
	v_fmac_f32_e32 v98, v60, v97
	v_max_i32_e32 v97, 0, v29
	v_fmac_f32_e32 v98, v61, v97
	v_mfma_f32_32x32x16_bf16 v[0:15], v[44:47], v[104:107], v[0:15]
	v_max_i32_e32 v97, 0, v30
	s_cmp_eq_u32 s60, 43
	v_fmac_f32_e32 v98, v62, v97
	v_max_i32_e32 v97, 0, v31
	s_cselect_b64 s[0:1], -1, 0
	v_cmp_gt_i32_e32 vcc, v169, v203
	v_fmac_f32_e32 v98, v63, v97
	s_and_b64 vcc, s[0:1], vcc
	v_cndmask_b32_e32 v237, v98, v197, vcc
	s_branch .LBB0_1979

.LBB0_1981:
	s_waitcnt lgkmcnt(0)
	ds_read_b128 v[96:99], v134 offset:0x5a00
	ds_read_b128 v[88:91], v134 offset:0x5a20
	ds_read_b128 v[80:83], v134 offset:0x5a40
	ds_read_b128 v[104:107], v134 offset:0x5a60
	s_cmpk_gt_u32 s94, 0x57
	s_cselect_b64 s[66:67], -1, 0
	s_cmpk_lt_u32 s94, 0x58
	s_cbranch_scc1 .LBB0_1983
	v_mfma_f32_32x32x16_bf16 v[16:31], v[32:35], v[100:103], 0
	v_cndmask_b32_e64 v101, 0, 1, s[68:69]
	v_cmp_ne_u32_e64 s[54:55], 1, v101
	s_andn2_b64 vcc, exec, s[68:69]
	v_max_i32_e32 v101, 0, v0
	v_fma_f32 v102, v48, v101, 0
	v_max_i32_e32 v101, 0, v1
	v_fmac_f32_e32 v102, v49, v101
	v_max_i32_e32 v101, 0, v2
	v_fmac_f32_e32 v102, v50, v101
	v_max_i32_e32 v101, 0, v3
	v_fmac_f32_e32 v102, v51, v101
	v_max_i32_e32 v101, 0, v4
	v_fmac_f32_e32 v102, v52, v101
	v_mfma_f32_32x32x16_bf16 v[16:31], v[36:39], v[92:95], v[16:31]
	v_max_i32_e32 v101, 0, v5
	v_fmac_f32_e32 v102, v53, v101
	v_max_i32_e32 v101, 0, v6
	v_fmac_f32_e32 v102, v54, v101
	v_max_i32_e32 v101, 0, v7
	v_fmac_f32_e32 v102, v55, v101
	v_max_i32_e32 v101, 0, v8
	v_fmac_f32_e32 v102, v56, v101
	v_max_i32_e32 v101, 0, v9
	v_fmac_f32_e32 v102, v57, v101
	v_mfma_f32_32x32x16_bf16 v[16:31], v[40:43], v[84:87], v[16:31]
	v_max_i32_e32 v101, 0, v10
	v_fmac_f32_e32 v102, v58, v101
	v_max_i32_e32 v101, 0, v11
	v_fmac_f32_e32 v102, v59, v101
	v_max_i32_e32 v101, 0, v12
	v_fmac_f32_e32 v102, v60, v101
	v_max_i32_e32 v101, 0, v13
	v_fmac_f32_e32 v102, v61, v101
	v_mfma_f32_32x32x16_bf16 v[16:31], v[44:47], v[108:111], v[16:31]
	v_max_i32_e32 v101, 0, v14
	s_cmp_eq_u32 s60, 44
	v_fmac_f32_e32 v102, v62, v101
	v_max_i32_e32 v101, 0, v15
	s_cselect_b64 s[0:1], -1, 0
	v_cmp_gt_i32_e32 vcc, v170, v203
	v_fmac_f32_e32 v102, v63, v101
	s_and_b64 vcc, s[0:1], vcc
	v_cndmask_b32_e32 v238, v102, v197, vcc
	s_branch .LBB0_1985

.LBB0_1987:
	s_waitcnt lgkmcnt(0)
	ds_read_b128 v[100:103], v134 offset:0x6c00
	ds_read_b128 v[92:95], v134 offset:0x6c20
	ds_read_b128 v[84:87], v134 offset:0x6c40
	ds_read_b128 v[108:111], v134 offset:0x6c60
	s_cmpk_gt_u32 s94, 0x59
	s_cselect_b64 s[68:69], -1, 0
	s_cmpk_lt_u32 s94, 0x5a
	s_cbranch_scc1 .LBB0_1989
	v_mfma_f32_32x32x16_bf16 v[0:15], v[32:35], v[96:99], 0
	v_cndmask_b32_e64 v97, 0, 1, s[66:67]
	v_cmp_ne_u32_e64 s[54:55], 1, v97
	s_andn2_b64 vcc, exec, s[66:67]
	v_max_i32_e32 v97, 0, v16
	v_fma_f32 v98, v48, v97, 0
	v_max_i32_e32 v97, 0, v17
	v_fmac_f32_e32 v98, v49, v97
	v_max_i32_e32 v97, 0, v18
	v_fmac_f32_e32 v98, v50, v97
	v_max_i32_e32 v97, 0, v19
	v_fmac_f32_e32 v98, v51, v97
	v_max_i32_e32 v97, 0, v20
	v_fmac_f32_e32 v98, v52, v97
	v_mfma_f32_32x32x16_bf16 v[0:15], v[36:39], v[88:91], v[0:15]
	v_max_i32_e32 v97, 0, v21
	v_fmac_f32_e32 v98, v53, v97
	v_max_i32_e32 v97, 0, v22
	v_fmac_f32_e32 v98, v54, v97
	v_max_i32_e32 v97, 0, v23
	v_fmac_f32_e32 v98, v55, v97
	v_max_i32_e32 v97, 0, v24
	v_fmac_f32_e32 v98, v56, v97
	v_max_i32_e32 v97, 0, v25
	v_fmac_f32_e32 v98, v57, v97
	v_mfma_f32_32x32x16_bf16 v[0:15], v[40:43], v[80:83], v[0:15]
	v_max_i32_e32 v97, 0, v26
	v_fmac_f32_e32 v98, v58, v97
	v_max_i32_e32 v97, 0, v27
	v_fmac_f32_e32 v98, v59, v97
	v_max_i32_e32 v97, 0, v28
	v_fmac_f32_e32 v98, v60, v97
	v_max_i32_e32 v97, 0, v29
	v_fmac_f32_e32 v98, v61, v97
	v_mfma_f32_32x32x16_bf16 v[0:15], v[44:47], v[104:107], v[0:15]
	v_max_i32_e32 v97, 0, v30
	s_cmp_eq_u32 s60, 45
	v_fmac_f32_e32 v98, v62, v97
	v_max_i32_e32 v97, 0, v31
	s_cselect_b64 s[0:1], -1, 0
	v_cmp_gt_i32_e32 vcc, v171, v203
	v_fmac_f32_e32 v98, v63, v97
	s_and_b64 vcc, s[0:1], vcc
	v_cndmask_b32_e32 v239, v98, v197, vcc
	s_branch .LBB0_1991

.LBB0_1993:
	s_waitcnt lgkmcnt(0)
	ds_read_b128 v[96:99], v134 offset:0x7e00
	ds_read_b128 v[88:91], v134 offset:0x7e20
	ds_read_b128 v[80:83], v134 offset:0x7e40
	ds_read_b128 v[104:107], v134 offset:0x7e60
	s_cmpk_gt_u32 s94, 0x5b
	s_cselect_b64 s[66:67], -1, 0
	s_cmpk_lt_u32 s94, 0x5c
	s_cbranch_scc1 .LBB0_1995
	v_mfma_f32_32x32x16_bf16 v[16:31], v[32:35], v[100:103], 0
	v_cndmask_b32_e64 v101, 0, 1, s[68:69]
	v_cmp_ne_u32_e64 s[54:55], 1, v101
	s_andn2_b64 vcc, exec, s[68:69]
	v_max_i32_e32 v101, 0, v0
	v_fma_f32 v102, v48, v101, 0
	v_max_i32_e32 v101, 0, v1
	v_fmac_f32_e32 v102, v49, v101
	v_max_i32_e32 v101, 0, v2
	v_fmac_f32_e32 v102, v50, v101
	v_max_i32_e32 v101, 0, v3
	v_fmac_f32_e32 v102, v51, v101
	v_max_i32_e32 v101, 0, v4
	v_fmac_f32_e32 v102, v52, v101
	v_mfma_f32_32x32x16_bf16 v[16:31], v[36:39], v[92:95], v[16:31]
	v_max_i32_e32 v101, 0, v5
	v_fmac_f32_e32 v102, v53, v101
	v_max_i32_e32 v101, 0, v6
	v_fmac_f32_e32 v102, v54, v101
	v_max_i32_e32 v101, 0, v7
	v_fmac_f32_e32 v102, v55, v101
	v_max_i32_e32 v101, 0, v8
	v_fmac_f32_e32 v102, v56, v101
	v_max_i32_e32 v101, 0, v9
	v_fmac_f32_e32 v102, v57, v101
	v_mfma_f32_32x32x16_bf16 v[16:31], v[40:43], v[84:87], v[16:31]
	v_max_i32_e32 v101, 0, v10
	v_fmac_f32_e32 v102, v58, v101
	v_max_i32_e32 v101, 0, v11
	v_fmac_f32_e32 v102, v59, v101
	v_max_i32_e32 v101, 0, v12
	v_fmac_f32_e32 v102, v60, v101
	v_max_i32_e32 v101, 0, v13
	v_fmac_f32_e32 v102, v61, v101
	v_mfma_f32_32x32x16_bf16 v[16:31], v[44:47], v[108:111], v[16:31]
	v_max_i32_e32 v101, 0, v14
	s_cmp_eq_u32 s60, 46
	v_fmac_f32_e32 v102, v62, v101
	v_max_i32_e32 v101, 0, v15
	s_cselect_b64 s[0:1], -1, 0
	v_cmp_gt_i32_e32 vcc, v172, v203
	v_fmac_f32_e32 v102, v63, v101
	s_and_b64 vcc, s[0:1], vcc
	v_cndmask_b32_e32 v240, v102, v197, vcc
	s_branch .LBB0_1997

.LBB0_1999:
	s_waitcnt lgkmcnt(0)
	s_cmpk_lt_u32 s94, 0x5e
	s_cbranch_scc1 .LBB0_2001
	v_mfma_f32_32x32x16_bf16 v[0:15], v[32:35], v[96:99], 0
	v_cndmask_b32_e64 v97, 0, 1, s[66:67]
	v_cmp_ne_u32_e64 s[54:55], 1, v97
	s_andn2_b64 vcc, exec, s[66:67]
	v_max_i32_e32 v97, 0, v16
	v_fma_f32 v98, v48, v97, 0
	v_max_i32_e32 v97, 0, v17
	v_fmac_f32_e32 v98, v49, v97
	v_max_i32_e32 v97, 0, v18
	v_fmac_f32_e32 v98, v50, v97
	v_max_i32_e32 v97, 0, v19
	v_fmac_f32_e32 v98, v51, v97
	v_max_i32_e32 v97, 0, v20
	v_fmac_f32_e32 v98, v52, v97
	v_mfma_f32_32x32x16_bf16 v[0:15], v[36:39], v[88:91], v[0:15]
	v_max_i32_e32 v97, 0, v21
	v_fmac_f32_e32 v98, v53, v97
	v_max_i32_e32 v97, 0, v22
	v_fmac_f32_e32 v98, v54, v97
	v_max_i32_e32 v97, 0, v23
	v_fmac_f32_e32 v98, v55, v97
	v_max_i32_e32 v97, 0, v24
	v_fmac_f32_e32 v98, v56, v97
	v_max_i32_e32 v97, 0, v25
	v_fmac_f32_e32 v98, v57, v97
	v_mfma_f32_32x32x16_bf16 v[0:15], v[40:43], v[80:83], v[0:15]
	v_max_i32_e32 v97, 0, v26
	v_fmac_f32_e32 v98, v58, v97
	v_max_i32_e32 v97, 0, v27
	v_fmac_f32_e32 v98, v59, v97
	v_max_i32_e32 v97, 0, v28
	v_fmac_f32_e32 v98, v60, v97
	v_max_i32_e32 v97, 0, v29
	v_fmac_f32_e32 v98, v61, v97
	v_mfma_f32_32x32x16_bf16 v[0:15], v[44:47], v[104:107], v[0:15]
	v_max_i32_e32 v97, 0, v30
	s_cmp_eq_u32 s60, 47
	v_fmac_f32_e32 v98, v62, v97
	v_max_i32_e32 v97, 0, v31
	s_cselect_b64 s[0:1], -1, 0
	v_cmp_gt_i32_e32 vcc, v173, v203
	v_fmac_f32_e32 v98, v63, v97
	s_and_b64 vcc, s[0:1], vcc
	v_cndmask_b32_e32 v241, v98, v197, vcc
	s_branch .LBB0_2003

.LBB0_2011:
	ds_read_b128 v[16:19], v131 offset:0
	ds_read_b128 v[80:83], v131 offset:32
	ds_read_b128 v[84:87], v131 offset:64
	ds_read_b128 v[92:95], v131 offset:0x60
	v_max_i32_e32 v88, 0, v0
	s_waitcnt lgkmcnt(0)
	v_max_i32_e32 v89, 0, v1
	v_mfma_f32_32x32x16_bf16 v[16:31], v[32:35], v[16:19], 0
	v_fma_f32 v242, v48, v88, 0
	v_max_i32_e32 v90, 0, v2
	v_fmac_f32_e32 v242, v49, v89
	v_max_i32_e32 v91, 0, v3
	v_fmac_f32_e32 v242, v50, v90
	v_max_i32_e32 v96, 0, v4
	v_fmac_f32_e32 v242, v51, v91
	v_mfma_f32_32x32x16_bf16 v[16:31], v[36:39], v[80:83], v[16:31]
	v_max_i32_e32 v97, 0, v5
	v_fmac_f32_e32 v242, v52, v96
	v_max_i32_e32 v98, 0, v6
	v_fmac_f32_e32 v242, v53, v97
	v_max_i32_e32 v99, 0, v7
	v_fmac_f32_e32 v242, v54, v98
	v_max_i32_e32 v100, 0, v8
	v_mfma_f32_32x32x16_bf16 v[16:31], v[40:43], v[84:87], v[16:31]
	v_fmac_f32_e32 v242, v55, v99
	v_max_i32_e32 v101, 0, v9
	v_fmac_f32_e32 v242, v56, v100
	v_max_i32_e32 v102, 0, v10
	v_fmac_f32_e32 v242, v57, v101
	v_max_i32_e32 v103, 0, v11
	v_fmac_f32_e32 v242, v58, v102
	v_fmac_f32_e32 v242, v59, v103
	v_max_i32_e32 v84, 0, v12
	ds_read_b128 v[80:83], v131 offset:0x1200
	v_fmac_f32_e32 v242, v60, v84
	v_max_i32_e32 v84, 0, v13
	ds_read_b128 v[88:91], v131 offset:0x1220
	v_fmac_f32_e32 v242, v61, v84
	v_max_i32_e32 v84, 0, v14
	ds_read_b128 v[96:99], v131 offset:0x1240
	v_fmac_f32_e32 v242, v62, v84
	v_max_i32_e32 v84, 0, v15
	ds_read_b128 v[104:107], v131 offset:0x1260
	v_mfma_f32_32x32x16_bf16 v[16:31], v[44:47], v[92:95], v[16:31]
	v_fmac_f32_e32 v242, v63, v84
	s_waitcnt lgkmcnt(0)
	ds_read_b128 v[108:111], v131 offset:0x2400
	ds_read_b128 v[100:103], v131 offset:0x2420
	ds_read_b128 v[92:95], v131 offset:0x2440
	ds_read_b128 v[84:87], v131 offset:0x2460
	s_cmp_eq_u32 s60, 49
	s_cselect_b64 s[54:55], -1, 0
	s_cmp_lg_u32 s60, 49
	s_cselect_b64 s[0:1], -1, 0
	s_and_b64 vcc, exec, s[54:55]
	s_cbranch_vccnz .LBB0_2013
	v_mfma_f32_32x32x16_bf16 v[0:15], v[32:35], v[80:83], 0
	v_max_i32_e32 v81, 0, v16
	v_fma_f32 v82, v48, v81, 0
	v_max_i32_e32 v81, 0, v17
	v_fmac_f32_e32 v82, v49, v81
	v_max_i32_e32 v81, 0, v18
	v_fmac_f32_e32 v82, v50, v81
	v_max_i32_e32 v81, 0, v19
	v_fmac_f32_e32 v82, v51, v81
	v_max_i32_e32 v81, 0, v20
	v_fmac_f32_e32 v82, v52, v81
	v_mfma_f32_32x32x16_bf16 v[0:15], v[36:39], v[88:91], v[0:15]
	v_max_i32_e32 v81, 0, v21
	v_fmac_f32_e32 v82, v53, v81
	v_max_i32_e32 v81, 0, v22
	v_fmac_f32_e32 v82, v54, v81
	v_max_i32_e32 v81, 0, v23
	v_fmac_f32_e32 v82, v55, v81
	v_max_i32_e32 v81, 0, v24
	v_fmac_f32_e32 v82, v56, v81
	v_max_i32_e32 v81, 0, v25
	v_fmac_f32_e32 v82, v57, v81
	v_mfma_f32_32x32x16_bf16 v[0:15], v[40:43], v[96:99], v[0:15]
	v_max_i32_e32 v81, 0, v26
	v_fmac_f32_e32 v82, v58, v81
	v_max_i32_e32 v81, 0, v27
	v_fmac_f32_e32 v82, v59, v81
	v_max_i32_e32 v81, 0, v28
	v_fmac_f32_e32 v82, v60, v81
	v_max_i32_e32 v81, 0, v29
	v_fmac_f32_e32 v82, v61, v81
	v_mfma_f32_32x32x16_bf16 v[0:15], v[44:47], v[104:107], v[0:15]
	v_max_i32_e32 v81, 0, v30
	v_fmac_f32_e32 v82, v62, v81
	v_max_i32_e32 v81, 0, v31
	v_cmp_gt_i32_e32 vcc, v175, v203
	v_fmac_f32_e32 v82, v63, v81
	s_and_b64 vcc, s[54:55], vcc
	v_cndmask_b32_e32 v243, v82, v197, vcc
	s_branch .Lixj14

.Lixj14:
	s_waitcnt lgkmcnt(0)
	ds_read_b128 v[96:99], v131 offset:0x3600
	ds_read_b128 v[88:91], v131 offset:0x3620
	ds_read_b128 v[80:83], v131 offset:0x3640
	ds_read_b128 v[104:107], v131 offset:0x3660
	s_cmpk_gt_u32 s94, 0x63
	s_cselect_b64 s[62:63], -1, 0
	s_cmpk_lt_u32 s94, 0x64
	s_cbranch_scc1 .LBB0_2015
	v_mfma_f32_32x32x16_bf16 v[16:31], v[32:35], v[108:111], 0
	v_cndmask_b32_e64 v109, 0, 1, s[0:1]
	v_cmp_ne_u32_e64 s[54:55], 1, v109
	s_andn2_b64 vcc, exec, s[0:1]
	v_max_i32_e32 v109, 0, v0
	v_fma_f32 v110, v48, v109, 0
	v_max_i32_e32 v109, 0, v1
	v_fmac_f32_e32 v110, v49, v109
	v_max_i32_e32 v109, 0, v2
	v_fmac_f32_e32 v110, v50, v109
	v_max_i32_e32 v109, 0, v3
	v_fmac_f32_e32 v110, v51, v109
	v_max_i32_e32 v109, 0, v4
	v_fmac_f32_e32 v110, v52, v109
	v_mfma_f32_32x32x16_bf16 v[16:31], v[36:39], v[100:103], v[16:31]
	v_max_i32_e32 v109, 0, v5
	v_fmac_f32_e32 v110, v53, v109
	v_max_i32_e32 v109, 0, v6
	v_fmac_f32_e32 v110, v54, v109
	v_max_i32_e32 v109, 0, v7
	v_fmac_f32_e32 v110, v55, v109
	v_max_i32_e32 v109, 0, v8
	v_fmac_f32_e32 v110, v56, v109
	v_max_i32_e32 v109, 0, v9
	v_fmac_f32_e32 v110, v57, v109
	v_mfma_f32_32x32x16_bf16 v[16:31], v[40:43], v[92:95], v[16:31]
	v_max_i32_e32 v109, 0, v10
	v_fmac_f32_e32 v110, v58, v109
	v_max_i32_e32 v109, 0, v11
	v_fmac_f32_e32 v110, v59, v109
	v_max_i32_e32 v109, 0, v12
	v_fmac_f32_e32 v110, v60, v109
	v_max_i32_e32 v109, 0, v13
	v_fmac_f32_e32 v110, v61, v109
	v_mfma_f32_32x32x16_bf16 v[16:31], v[44:47], v[84:87], v[16:31]
	v_max_i32_e32 v109, 0, v14
	s_cmp_eq_u32 s60, 50
	v_fmac_f32_e32 v110, v62, v109
	v_max_i32_e32 v109, 0, v15
	s_cselect_b64 s[0:1], -1, 0
	v_cmp_gt_i32_e32 vcc, v176, v203
	v_fmac_f32_e32 v110, v63, v109
	s_and_b64 vcc, s[0:1], vcc
	v_cndmask_b32_e32 v244, v110, v197, vcc
	s_branch .LBB0_2017

.LBB0_2019:
	s_waitcnt lgkmcnt(0)
	ds_read_b128 v[100:103], v131 offset:0x4800
	ds_read_b128 v[92:95], v131 offset:0x4820
	ds_read_b128 v[84:87], v131 offset:0x4840
	ds_read_b128 v[108:111], v131 offset:0x4860
	s_cmpk_gt_u32 s94, 0x65
	s_cselect_b64 s[66:67], -1, 0
	s_cmpk_lt_u32 s94, 0x66
	s_cbranch_scc1 .LBB0_2021
	v_mfma_f32_32x32x16_bf16 v[0:15], v[32:35], v[96:99], 0
	v_cndmask_b32_e64 v97, 0, 1, s[62:63]
	v_cmp_ne_u32_e64 s[54:55], 1, v97
	s_andn2_b64 vcc, exec, s[62:63]
	v_max_i32_e32 v97, 0, v16
	v_fma_f32 v98, v48, v97, 0
	v_max_i32_e32 v97, 0, v17
	v_fmac_f32_e32 v98, v49, v97
	v_max_i32_e32 v97, 0, v18
	v_fmac_f32_e32 v98, v50, v97
	v_max_i32_e32 v97, 0, v19
	v_fmac_f32_e32 v98, v51, v97
	v_max_i32_e32 v97, 0, v20
	v_fmac_f32_e32 v98, v52, v97
	v_mfma_f32_32x32x16_bf16 v[0:15], v[36:39], v[88:91], v[0:15]
	v_max_i32_e32 v97, 0, v21
	v_fmac_f32_e32 v98, v53, v97
	v_max_i32_e32 v97, 0, v22
	v_fmac_f32_e32 v98, v54, v97
	v_max_i32_e32 v97, 0, v23
	v_fmac_f32_e32 v98, v55, v97
	v_max_i32_e32 v97, 0, v24
	v_fmac_f32_e32 v98, v56, v97
	v_max_i32_e32 v97, 0, v25
	v_fmac_f32_e32 v98, v57, v97
	v_mfma_f32_32x32x16_bf16 v[0:15], v[40:43], v[80:83], v[0:15]
	v_max_i32_e32 v97, 0, v26
	v_fmac_f32_e32 v98, v58, v97
	v_max_i32_e32 v97, 0, v27
	v_fmac_f32_e32 v98, v59, v97
	v_max_i32_e32 v97, 0, v28
	v_fmac_f32_e32 v98, v60, v97
	v_max_i32_e32 v97, 0, v29
	v_fmac_f32_e32 v98, v61, v97
	v_mfma_f32_32x32x16_bf16 v[0:15], v[44:47], v[104:107], v[0:15]
	v_max_i32_e32 v97, 0, v30
	s_cmp_eq_u32 s60, 51
	v_fmac_f32_e32 v98, v62, v97
	v_max_i32_e32 v97, 0, v31
	s_cselect_b64 s[0:1], -1, 0
	v_cmp_gt_i32_e32 vcc, v177, v203
	v_fmac_f32_e32 v98, v63, v97
	s_and_b64 vcc, s[0:1], vcc
	v_cndmask_b32_e32 v245, v98, v197, vcc
	s_branch .LBB0_2023

.LBB0_2025:
	s_waitcnt lgkmcnt(0)
	ds_read_b128 v[96:99], v131 offset:0x5a00
	ds_read_b128 v[88:91], v131 offset:0x5a20
	ds_read_b128 v[80:83], v131 offset:0x5a40
	ds_read_b128 v[104:107], v131 offset:0x5a60
	s_cmpk_gt_u32 s94, 0x67
	s_cselect_b64 s[62:63], -1, 0
	s_cmpk_lt_u32 s94, 0x68
	s_cbranch_scc1 .LBB0_2027
	v_mfma_f32_32x32x16_bf16 v[16:31], v[32:35], v[100:103], 0
	v_cndmask_b32_e64 v101, 0, 1, s[66:67]
	v_cmp_ne_u32_e64 s[54:55], 1, v101
	s_andn2_b64 vcc, exec, s[66:67]
	v_max_i32_e32 v101, 0, v0
	v_fma_f32 v102, v48, v101, 0
	v_max_i32_e32 v101, 0, v1
	v_fmac_f32_e32 v102, v49, v101
	v_max_i32_e32 v101, 0, v2
	v_fmac_f32_e32 v102, v50, v101
	v_max_i32_e32 v101, 0, v3
	v_fmac_f32_e32 v102, v51, v101
	v_max_i32_e32 v101, 0, v4
	v_fmac_f32_e32 v102, v52, v101
	v_mfma_f32_32x32x16_bf16 v[16:31], v[36:39], v[92:95], v[16:31]
	v_max_i32_e32 v101, 0, v5
	v_fmac_f32_e32 v102, v53, v101
	v_max_i32_e32 v101, 0, v6
	v_fmac_f32_e32 v102, v54, v101
	v_max_i32_e32 v101, 0, v7
	v_fmac_f32_e32 v102, v55, v101
	v_max_i32_e32 v101, 0, v8
	v_fmac_f32_e32 v102, v56, v101
	v_max_i32_e32 v101, 0, v9
	v_fmac_f32_e32 v102, v57, v101
	v_mfma_f32_32x32x16_bf16 v[16:31], v[40:43], v[84:87], v[16:31]
	v_max_i32_e32 v101, 0, v10
	v_fmac_f32_e32 v102, v58, v101
	v_max_i32_e32 v101, 0, v11
	v_fmac_f32_e32 v102, v59, v101
	v_max_i32_e32 v101, 0, v12
	v_fmac_f32_e32 v102, v60, v101
	v_max_i32_e32 v101, 0, v13
	v_fmac_f32_e32 v102, v61, v101
	v_mfma_f32_32x32x16_bf16 v[16:31], v[44:47], v[108:111], v[16:31]
	v_max_i32_e32 v101, 0, v14
	s_cmp_eq_u32 s60, 52
	v_fmac_f32_e32 v102, v62, v101
	v_max_i32_e32 v101, 0, v15
	s_cselect_b64 s[0:1], -1, 0
	v_cmp_gt_i32_e32 vcc, v178, v203
	v_fmac_f32_e32 v102, v63, v101
	s_and_b64 vcc, s[0:1], vcc
	v_cndmask_b32_e32 v246, v102, v197, vcc
	s_branch .LBB0_2029

.LBB0_2031:
	s_waitcnt lgkmcnt(0)
	ds_read_b128 v[100:103], v131 offset:0x6c00
	ds_read_b128 v[92:95], v131 offset:0x6c20
	ds_read_b128 v[84:87], v131 offset:0x6c40
	ds_read_b128 v[108:111], v131 offset:0x6c60
	s_cmpk_gt_u32 s94, 0x69
	s_cselect_b64 s[66:67], -1, 0
	s_cmpk_lt_u32 s94, 0x6a
	s_cbranch_scc1 .LBB0_2033
	v_mfma_f32_32x32x16_bf16 v[0:15], v[32:35], v[96:99], 0
	v_cndmask_b32_e64 v97, 0, 1, s[62:63]
	v_cmp_ne_u32_e64 s[54:55], 1, v97
	s_andn2_b64 vcc, exec, s[62:63]
	v_max_i32_e32 v97, 0, v16
	v_fma_f32 v98, v48, v97, 0
	v_max_i32_e32 v97, 0, v17
	v_fmac_f32_e32 v98, v49, v97
	v_max_i32_e32 v97, 0, v18
	v_fmac_f32_e32 v98, v50, v97
	v_max_i32_e32 v97, 0, v19
	v_fmac_f32_e32 v98, v51, v97
	v_max_i32_e32 v97, 0, v20
	v_fmac_f32_e32 v98, v52, v97
	v_mfma_f32_32x32x16_bf16 v[0:15], v[36:39], v[88:91], v[0:15]
	v_max_i32_e32 v97, 0, v21
	v_fmac_f32_e32 v98, v53, v97
	v_max_i32_e32 v97, 0, v22
	v_fmac_f32_e32 v98, v54, v97
	v_max_i32_e32 v97, 0, v23
	v_fmac_f32_e32 v98, v55, v97
	v_max_i32_e32 v97, 0, v24
	v_fmac_f32_e32 v98, v56, v97
	v_max_i32_e32 v97, 0, v25
	v_fmac_f32_e32 v98, v57, v97
	v_mfma_f32_32x32x16_bf16 v[0:15], v[40:43], v[80:83], v[0:15]
	v_max_i32_e32 v97, 0, v26
	v_fmac_f32_e32 v98, v58, v97
	v_max_i32_e32 v97, 0, v27
	v_fmac_f32_e32 v98, v59, v97
	v_max_i32_e32 v97, 0, v28
	v_fmac_f32_e32 v98, v60, v97
	v_max_i32_e32 v97, 0, v29
	v_fmac_f32_e32 v98, v61, v97
	v_mfma_f32_32x32x16_bf16 v[0:15], v[44:47], v[104:107], v[0:15]
	v_max_i32_e32 v97, 0, v30
	s_cmp_eq_u32 s60, 53
	v_fmac_f32_e32 v98, v62, v97
	v_max_i32_e32 v97, 0, v31
	s_cselect_b64 s[0:1], -1, 0
	v_cmp_gt_i32_e32 vcc, v179, v203
	v_fmac_f32_e32 v98, v63, v97
	s_and_b64 vcc, s[0:1], vcc
	v_cndmask_b32_e32 v247, v98, v197, vcc
	s_branch .LBB0_2035

.LBB0_2037:
	s_waitcnt lgkmcnt(0)
	ds_read_b128 v[96:99], v131 offset:0x7e00
	ds_read_b128 v[88:91], v131 offset:0x7e20
	ds_read_b128 v[80:83], v131 offset:0x7e40
	ds_read_b128 v[104:107], v131 offset:0x7e60
	s_cmpk_gt_u32 s94, 0x6b
	s_cselect_b64 s[62:63], -1, 0
	s_cmpk_lt_u32 s94, 0x6c
	s_cbranch_scc1 .LBB0_2039
	v_mfma_f32_32x32x16_bf16 v[16:31], v[32:35], v[100:103], 0
	v_cndmask_b32_e64 v101, 0, 1, s[66:67]
	v_cmp_ne_u32_e64 s[54:55], 1, v101
	s_andn2_b64 vcc, exec, s[66:67]
	v_max_i32_e32 v101, 0, v0
	v_fma_f32 v102, v48, v101, 0
	v_max_i32_e32 v101, 0, v1
	v_fmac_f32_e32 v102, v49, v101
	v_max_i32_e32 v101, 0, v2
	v_fmac_f32_e32 v102, v50, v101
	v_max_i32_e32 v101, 0, v3
	v_fmac_f32_e32 v102, v51, v101
	v_max_i32_e32 v101, 0, v4
	v_fmac_f32_e32 v102, v52, v101
	v_mfma_f32_32x32x16_bf16 v[16:31], v[36:39], v[92:95], v[16:31]
	v_max_i32_e32 v101, 0, v5
	v_fmac_f32_e32 v102, v53, v101
	v_max_i32_e32 v101, 0, v6
	v_fmac_f32_e32 v102, v54, v101
	v_max_i32_e32 v101, 0, v7
	v_fmac_f32_e32 v102, v55, v101
	v_max_i32_e32 v101, 0, v8
	v_fmac_f32_e32 v102, v56, v101
	v_max_i32_e32 v101, 0, v9
	v_fmac_f32_e32 v102, v57, v101
	v_mfma_f32_32x32x16_bf16 v[16:31], v[40:43], v[84:87], v[16:31]
	v_max_i32_e32 v101, 0, v10
	v_fmac_f32_e32 v102, v58, v101
	v_max_i32_e32 v101, 0, v11
	v_fmac_f32_e32 v102, v59, v101
	v_max_i32_e32 v101, 0, v12
	v_fmac_f32_e32 v102, v60, v101
	v_max_i32_e32 v101, 0, v13
	v_fmac_f32_e32 v102, v61, v101
	v_mfma_f32_32x32x16_bf16 v[16:31], v[44:47], v[108:111], v[16:31]
	v_max_i32_e32 v101, 0, v14
	s_cmp_eq_u32 s60, 54
	v_fmac_f32_e32 v102, v62, v101
	v_max_i32_e32 v101, 0, v15
	s_cselect_b64 s[0:1], -1, 0
	v_cmp_gt_i32_e32 vcc, v180, v203
	v_fmac_f32_e32 v102, v63, v101
	s_and_b64 vcc, s[0:1], vcc
	v_cndmask_b32_e32 v248, v102, v197, vcc
	s_branch .LBB0_2041

.LBB0_2043:
	s_waitcnt lgkmcnt(0)
	s_cmpk_lt_u32 s94, 0x6e
	s_cbranch_scc1 .LBB0_2045
	v_mfma_f32_32x32x16_bf16 v[0:15], v[32:35], v[96:99], 0
	v_cndmask_b32_e64 v97, 0, 1, s[62:63]
	v_cmp_ne_u32_e64 s[54:55], 1, v97
	s_andn2_b64 vcc, exec, s[62:63]
	v_max_i32_e32 v97, 0, v16
	v_fma_f32 v98, v48, v97, 0
	v_max_i32_e32 v97, 0, v17
	v_fmac_f32_e32 v98, v49, v97
	v_max_i32_e32 v97, 0, v18
	v_fmac_f32_e32 v98, v50, v97
	v_max_i32_e32 v97, 0, v19
	v_fmac_f32_e32 v98, v51, v97
	v_max_i32_e32 v97, 0, v20
	v_fmac_f32_e32 v98, v52, v97
	v_mfma_f32_32x32x16_bf16 v[0:15], v[36:39], v[88:91], v[0:15]
	v_max_i32_e32 v97, 0, v21
	v_fmac_f32_e32 v98, v53, v97
	v_max_i32_e32 v97, 0, v22
	v_fmac_f32_e32 v98, v54, v97
	v_max_i32_e32 v97, 0, v23
	v_fmac_f32_e32 v98, v55, v97
	v_max_i32_e32 v97, 0, v24
	v_fmac_f32_e32 v98, v56, v97
	v_max_i32_e32 v97, 0, v25
	v_fmac_f32_e32 v98, v57, v97
	v_mfma_f32_32x32x16_bf16 v[0:15], v[40:43], v[80:83], v[0:15]
	v_max_i32_e32 v97, 0, v26
	v_fmac_f32_e32 v98, v58, v97
	v_max_i32_e32 v97, 0, v27
	v_fmac_f32_e32 v98, v59, v97
	v_max_i32_e32 v97, 0, v28
	v_fmac_f32_e32 v98, v60, v97
	v_max_i32_e32 v97, 0, v29
	v_fmac_f32_e32 v98, v61, v97
	v_mfma_f32_32x32x16_bf16 v[0:15], v[44:47], v[104:107], v[0:15]
	v_max_i32_e32 v97, 0, v30
	s_cmp_eq_u32 s60, 55
	v_fmac_f32_e32 v98, v62, v97
	v_max_i32_e32 v97, 0, v31
	s_cselect_b64 s[0:1], -1, 0
	v_cmp_gt_i32_e32 vcc, v181, v203
	v_fmac_f32_e32 v98, v63, v97
	s_and_b64 vcc, s[0:1], vcc
	v_cndmask_b32_e32 v249, v98, v197, vcc
	s_branch .LBB0_2047

.LBB0_2053:
	ds_read_b128 v[16:19], v134 offset:0
	ds_read_b128 v[80:83], v134 offset:32
	ds_read_b128 v[84:87], v134 offset:64
	ds_read_b128 v[92:95], v134 offset:0x60
	v_max_i32_e32 v88, 0, v0
	s_waitcnt lgkmcnt(0)
	v_max_i32_e32 v89, 0, v1
	v_mfma_f32_32x32x16_bf16 v[16:31], v[32:35], v[16:19], 0
	v_fma_f32 v250, v48, v88, 0
	v_max_i32_e32 v90, 0, v2
	v_fmac_f32_e32 v250, v49, v89
	v_max_i32_e32 v91, 0, v3
	v_fmac_f32_e32 v250, v50, v90
	v_max_i32_e32 v96, 0, v4
	v_fmac_f32_e32 v250, v51, v91
	v_mfma_f32_32x32x16_bf16 v[16:31], v[36:39], v[80:83], v[16:31]
	v_max_i32_e32 v97, 0, v5
	v_fmac_f32_e32 v250, v52, v96
	v_max_i32_e32 v98, 0, v6
	v_fmac_f32_e32 v250, v53, v97
	v_max_i32_e32 v99, 0, v7
	v_fmac_f32_e32 v250, v54, v98
	v_max_i32_e32 v100, 0, v8
	v_mfma_f32_32x32x16_bf16 v[16:31], v[40:43], v[84:87], v[16:31]
	v_fmac_f32_e32 v250, v55, v99
	v_max_i32_e32 v101, 0, v9
	v_fmac_f32_e32 v250, v56, v100
	v_max_i32_e32 v102, 0, v10
	v_fmac_f32_e32 v250, v57, v101
	v_max_i32_e32 v103, 0, v11
	v_fmac_f32_e32 v250, v58, v102
	v_fmac_f32_e32 v250, v59, v103
	v_max_i32_e32 v84, 0, v12
	ds_read_b128 v[80:83], v134 offset:0x1200
	v_fmac_f32_e32 v250, v60, v84
	v_max_i32_e32 v84, 0, v13
	ds_read_b128 v[88:91], v134 offset:0x1220
	v_fmac_f32_e32 v250, v61, v84
	v_max_i32_e32 v84, 0, v14
	ds_read_b128 v[96:99], v134 offset:0x1240
	v_fmac_f32_e32 v250, v62, v84
	v_max_i32_e32 v84, 0, v15
	ds_read_b128 v[104:107], v134 offset:0x1260
	v_mfma_f32_32x32x16_bf16 v[16:31], v[44:47], v[92:95], v[16:31]
	v_fmac_f32_e32 v250, v63, v84
	s_waitcnt lgkmcnt(0)
	ds_read_b128 v[108:111], v134 offset:0x2400
	ds_read_b128 v[100:103], v134 offset:0x2420
	ds_read_b128 v[92:95], v134 offset:0x2440
	ds_read_b128 v[84:87], v134 offset:0x2460
	s_cmp_eq_u32 s60, 57
	s_cselect_b64 s[54:55], -1, 0
	s_cmp_lg_u32 s60, 57
	s_cselect_b64 s[0:1], -1, 0
	s_and_b64 vcc, exec, s[54:55]
	s_cbranch_vccnz .LBB0_2055
	v_mfma_f32_32x32x16_bf16 v[0:15], v[32:35], v[80:83], 0
	v_max_i32_e32 v81, 0, v16
	v_fma_f32 v82, v48, v81, 0
	v_max_i32_e32 v81, 0, v17
	v_fmac_f32_e32 v82, v49, v81
	v_max_i32_e32 v81, 0, v18
	v_fmac_f32_e32 v82, v50, v81
	v_max_i32_e32 v81, 0, v19
	v_fmac_f32_e32 v82, v51, v81
	v_max_i32_e32 v81, 0, v20
	v_fmac_f32_e32 v82, v52, v81
	v_mfma_f32_32x32x16_bf16 v[0:15], v[36:39], v[88:91], v[0:15]
	v_max_i32_e32 v81, 0, v21
	v_fmac_f32_e32 v82, v53, v81
	v_max_i32_e32 v81, 0, v22
	v_fmac_f32_e32 v82, v54, v81
	v_max_i32_e32 v81, 0, v23
	v_fmac_f32_e32 v82, v55, v81
	v_max_i32_e32 v81, 0, v24
	v_fmac_f32_e32 v82, v56, v81
	v_max_i32_e32 v81, 0, v25
	v_fmac_f32_e32 v82, v57, v81
	v_mfma_f32_32x32x16_bf16 v[0:15], v[40:43], v[96:99], v[0:15]
	v_max_i32_e32 v81, 0, v26
	v_fmac_f32_e32 v82, v58, v81
	v_max_i32_e32 v81, 0, v27
	v_fmac_f32_e32 v82, v59, v81
	v_max_i32_e32 v81, 0, v28
	v_fmac_f32_e32 v82, v60, v81
	v_max_i32_e32 v81, 0, v29
	v_fmac_f32_e32 v82, v61, v81
	v_mfma_f32_32x32x16_bf16 v[0:15], v[44:47], v[104:107], v[0:15]
	v_max_i32_e32 v81, 0, v30
	v_fmac_f32_e32 v82, v62, v81
	v_max_i32_e32 v81, 0, v31
	v_cmp_gt_i32_e32 vcc, v183, v203
	v_fmac_f32_e32 v82, v63, v81
	s_and_b64 vcc, s[54:55], vcc
	v_cndmask_b32_e32 v251, v82, v197, vcc
	s_branch .Lixj7

.Lixj7:
	s_waitcnt lgkmcnt(0)
	ds_read_b128 v[96:99], v134 offset:0x3600
	ds_read_b128 v[88:91], v134 offset:0x3620
	ds_read_b128 v[80:83], v134 offset:0x3640
	ds_read_b128 v[104:107], v134 offset:0x3660
	s_cmpk_gt_u32 s94, 0x73
	s_cselect_b64 s[62:63], -1, 0
	s_cmpk_lt_u32 s94, 0x74
	s_cbranch_scc1 .LBB0_2057
	v_mfma_f32_32x32x16_bf16 v[16:31], v[32:35], v[108:111], 0
	v_cndmask_b32_e64 v109, 0, 1, s[0:1]
	v_cmp_ne_u32_e64 s[54:55], 1, v109
	s_andn2_b64 vcc, exec, s[0:1]
	v_max_i32_e32 v109, 0, v0
	v_fma_f32 v110, v48, v109, 0
	v_max_i32_e32 v109, 0, v1
	v_fmac_f32_e32 v110, v49, v109
	v_max_i32_e32 v109, 0, v2
	v_fmac_f32_e32 v110, v50, v109
	v_max_i32_e32 v109, 0, v3
	v_fmac_f32_e32 v110, v51, v109
	v_max_i32_e32 v109, 0, v4
	v_fmac_f32_e32 v110, v52, v109
	v_mfma_f32_32x32x16_bf16 v[16:31], v[36:39], v[100:103], v[16:31]
	v_max_i32_e32 v109, 0, v5
	v_fmac_f32_e32 v110, v53, v109
	v_max_i32_e32 v109, 0, v6
	v_fmac_f32_e32 v110, v54, v109
	v_max_i32_e32 v109, 0, v7
	v_fmac_f32_e32 v110, v55, v109
	v_max_i32_e32 v109, 0, v8
	v_fmac_f32_e32 v110, v56, v109
	v_max_i32_e32 v109, 0, v9
	v_fmac_f32_e32 v110, v57, v109
	v_mfma_f32_32x32x16_bf16 v[16:31], v[40:43], v[92:95], v[16:31]
	v_max_i32_e32 v109, 0, v10
	v_fmac_f32_e32 v110, v58, v109
	v_max_i32_e32 v109, 0, v11
	v_fmac_f32_e32 v110, v59, v109
	v_max_i32_e32 v109, 0, v12
	v_fmac_f32_e32 v110, v60, v109
	v_max_i32_e32 v109, 0, v13
	v_fmac_f32_e32 v110, v61, v109
	v_mfma_f32_32x32x16_bf16 v[16:31], v[44:47], v[84:87], v[16:31]
	v_max_i32_e32 v109, 0, v14
	s_cmp_eq_u32 s60, 58
	v_fmac_f32_e32 v110, v62, v109
	v_max_i32_e32 v109, 0, v15
	s_cselect_b64 s[0:1], -1, 0
	v_cmp_gt_i32_e32 vcc, v184, v203
	v_fmac_f32_e32 v110, v63, v109
	s_and_b64 vcc, s[0:1], vcc
	v_cndmask_b32_e32 v252, v110, v197, vcc
	s_branch .LBB0_2059

.LBB0_2061:
	s_waitcnt lgkmcnt(0)
	ds_read_b128 v[100:103], v134 offset:0x4800
	ds_read_b128 v[92:95], v134 offset:0x4820
	ds_read_b128 v[84:87], v134 offset:0x4840
	ds_read_b128 v[108:111], v134 offset:0x4860
	s_cmpk_gt_u32 s94, 0x75
	s_cselect_b64 s[64:65], -1, 0
	s_cmpk_lt_u32 s94, 0x76
	s_cbranch_scc1 .LBB0_2063
	v_mfma_f32_32x32x16_bf16 v[0:15], v[32:35], v[96:99], 0
	v_cndmask_b32_e64 v97, 0, 1, s[62:63]
	v_cmp_ne_u32_e64 s[54:55], 1, v97
	s_andn2_b64 vcc, exec, s[62:63]
	v_max_i32_e32 v97, 0, v16
	v_fma_f32 v98, v48, v97, 0
	v_max_i32_e32 v97, 0, v17
	v_fmac_f32_e32 v98, v49, v97
	v_max_i32_e32 v97, 0, v18
	v_fmac_f32_e32 v98, v50, v97
	v_max_i32_e32 v97, 0, v19
	v_fmac_f32_e32 v98, v51, v97
	v_max_i32_e32 v97, 0, v20
	v_fmac_f32_e32 v98, v52, v97
	v_mfma_f32_32x32x16_bf16 v[0:15], v[36:39], v[88:91], v[0:15]
	v_max_i32_e32 v97, 0, v21
	v_fmac_f32_e32 v98, v53, v97
	v_max_i32_e32 v97, 0, v22
	v_fmac_f32_e32 v98, v54, v97
	v_max_i32_e32 v97, 0, v23
	v_fmac_f32_e32 v98, v55, v97
	v_max_i32_e32 v97, 0, v24
	v_fmac_f32_e32 v98, v56, v97
	v_max_i32_e32 v97, 0, v25
	v_fmac_f32_e32 v98, v57, v97
	v_mfma_f32_32x32x16_bf16 v[0:15], v[40:43], v[80:83], v[0:15]
	v_max_i32_e32 v97, 0, v26
	v_fmac_f32_e32 v98, v58, v97
	v_max_i32_e32 v97, 0, v27
	v_fmac_f32_e32 v98, v59, v97
	v_max_i32_e32 v97, 0, v28
	v_fmac_f32_e32 v98, v60, v97
	v_max_i32_e32 v97, 0, v29
	v_fmac_f32_e32 v98, v61, v97
	v_mfma_f32_32x32x16_bf16 v[0:15], v[44:47], v[104:107], v[0:15]
	v_max_i32_e32 v97, 0, v30
	s_cmp_eq_u32 s60, 59
	v_fmac_f32_e32 v98, v62, v97
	v_max_i32_e32 v97, 0, v31
	s_cselect_b64 s[0:1], -1, 0
	v_cmp_gt_i32_e32 vcc, v185, v203
	v_fmac_f32_e32 v98, v63, v97
	s_and_b64 vcc, s[0:1], vcc
	v_cndmask_b32_e32 v253, v98, v197, vcc
	s_branch .LBB0_2065

.LBB0_2067:
	s_waitcnt lgkmcnt(0)
	ds_read_b128 v[96:99], v134 offset:0x5a00
	ds_read_b128 v[88:91], v134 offset:0x5a20
	ds_read_b128 v[80:83], v134 offset:0x5a40
	ds_read_b128 v[104:107], v134 offset:0x5a60
	s_cmpk_gt_u32 s94, 0x77
	s_cselect_b64 s[62:63], -1, 0
	s_cmpk_lt_u32 s94, 0x78
	s_cbranch_scc1 .LBB0_2069
	v_mfma_f32_32x32x16_bf16 v[16:31], v[32:35], v[100:103], 0
	v_cndmask_b32_e64 v101, 0, 1, s[64:65]
	v_cmp_ne_u32_e64 s[54:55], 1, v101
	s_andn2_b64 vcc, exec, s[64:65]
	v_max_i32_e32 v101, 0, v0
	v_fma_f32 v102, v48, v101, 0
	v_max_i32_e32 v101, 0, v1
	v_fmac_f32_e32 v102, v49, v101
	v_max_i32_e32 v101, 0, v2
	v_fmac_f32_e32 v102, v50, v101
	v_max_i32_e32 v101, 0, v3
	v_fmac_f32_e32 v102, v51, v101
	v_max_i32_e32 v101, 0, v4
	v_fmac_f32_e32 v102, v52, v101
	v_mfma_f32_32x32x16_bf16 v[16:31], v[36:39], v[92:95], v[16:31]
	v_max_i32_e32 v101, 0, v5
	v_fmac_f32_e32 v102, v53, v101
	v_max_i32_e32 v101, 0, v6
	v_fmac_f32_e32 v102, v54, v101
	v_max_i32_e32 v101, 0, v7
	v_fmac_f32_e32 v102, v55, v101
	v_max_i32_e32 v101, 0, v8
	v_fmac_f32_e32 v102, v56, v101
	v_max_i32_e32 v101, 0, v9
	v_fmac_f32_e32 v102, v57, v101
	v_mfma_f32_32x32x16_bf16 v[16:31], v[40:43], v[84:87], v[16:31]
	v_max_i32_e32 v101, 0, v10
	v_fmac_f32_e32 v102, v58, v101
	v_max_i32_e32 v101, 0, v11
	v_fmac_f32_e32 v102, v59, v101
	v_max_i32_e32 v101, 0, v12
	v_fmac_f32_e32 v102, v60, v101
	v_max_i32_e32 v101, 0, v13
	v_fmac_f32_e32 v102, v61, v101
	v_mfma_f32_32x32x16_bf16 v[16:31], v[44:47], v[108:111], v[16:31]
	v_max_i32_e32 v101, 0, v14
	s_cmp_eq_u32 s60, 60
	v_fmac_f32_e32 v102, v62, v101
	v_max_i32_e32 v101, 0, v15
	s_cselect_b64 s[0:1], -1, 0
	v_cmp_gt_i32_e32 vcc, v186, v203
	v_fmac_f32_e32 v102, v63, v101
	s_and_b64 vcc, s[0:1], vcc
	v_cndmask_b32_e32 v215, v102, v197, vcc
	s_branch .LBB0_2071

.LBB0_2073:
	s_waitcnt lgkmcnt(0)
	ds_read_b128 v[100:103], v134 offset:0x6c00
	ds_read_b128 v[92:95], v134 offset:0x6c20
	ds_read_b128 v[84:87], v134 offset:0x6c40
	ds_read_b128 v[108:111], v134 offset:0x6c60
	s_cmpk_gt_u32 s94, 0x79
	s_cselect_b64 s[64:65], -1, 0
	s_cmpk_lt_u32 s94, 0x7a
	s_cbranch_scc1 .LBB0_2075
	v_mfma_f32_32x32x16_bf16 v[0:15], v[32:35], v[96:99], 0
	v_cndmask_b32_e64 v97, 0, 1, s[62:63]
	v_cmp_ne_u32_e64 s[54:55], 1, v97
	s_andn2_b64 vcc, exec, s[62:63]
	v_max_i32_e32 v97, 0, v16
	v_fma_f32 v98, v48, v97, 0
	v_max_i32_e32 v97, 0, v17
	v_fmac_f32_e32 v98, v49, v97
	v_max_i32_e32 v97, 0, v18
	v_fmac_f32_e32 v98, v50, v97
	v_max_i32_e32 v97, 0, v19
	v_fmac_f32_e32 v98, v51, v97
	v_max_i32_e32 v97, 0, v20
	v_fmac_f32_e32 v98, v52, v97
	v_mfma_f32_32x32x16_bf16 v[0:15], v[36:39], v[88:91], v[0:15]
	v_max_i32_e32 v97, 0, v21
	v_fmac_f32_e32 v98, v53, v97
	v_max_i32_e32 v97, 0, v22
	v_fmac_f32_e32 v98, v54, v97
	v_max_i32_e32 v97, 0, v23
	v_fmac_f32_e32 v98, v55, v97
	v_max_i32_e32 v97, 0, v24
	v_fmac_f32_e32 v98, v56, v97
	v_max_i32_e32 v97, 0, v25
	v_fmac_f32_e32 v98, v57, v97
	v_mfma_f32_32x32x16_bf16 v[0:15], v[40:43], v[80:83], v[0:15]
	v_max_i32_e32 v97, 0, v26
	v_fmac_f32_e32 v98, v58, v97
	v_max_i32_e32 v97, 0, v27
	v_fmac_f32_e32 v98, v59, v97
	v_max_i32_e32 v97, 0, v28
	v_fmac_f32_e32 v98, v60, v97
	v_max_i32_e32 v97, 0, v29
	v_fmac_f32_e32 v98, v61, v97
	v_mfma_f32_32x32x16_bf16 v[0:15], v[44:47], v[104:107], v[0:15]
	v_max_i32_e32 v97, 0, v30
	s_cmp_eq_u32 s60, 61
	v_fmac_f32_e32 v98, v62, v97
	v_max_i32_e32 v97, 0, v31
	s_cselect_b64 s[0:1], -1, 0
	v_cmp_gt_i32_e32 vcc, v187, v203
	v_fmac_f32_e32 v98, v63, v97
	s_and_b64 vcc, s[0:1], vcc
	v_cndmask_b32_e32 v133, v98, v197, vcc
	s_branch .LBB0_2077

.LBB0_2079:
	s_waitcnt lgkmcnt(0)
	ds_read_b128 v[96:99], v134 offset:0x7e00
	ds_read_b128 v[88:91], v134 offset:0x7e20
	ds_read_b128 v[80:83], v134 offset:0x7e40
	ds_read_b128 v[104:107], v134 offset:0x7e60
	s_cmpk_gt_u32 s94, 0x7b
	s_cselect_b64 s[62:63], -1, 0
	s_cmpk_lt_u32 s94, 0x7c
	s_cbranch_scc1 .LBB0_2081
	v_mfma_f32_32x32x16_bf16 v[16:31], v[32:35], v[100:103], 0
	v_cndmask_b32_e64 v101, 0, 1, s[64:65]
	v_cmp_ne_u32_e64 s[54:55], 1, v101
	s_andn2_b64 vcc, exec, s[64:65]
	v_max_i32_e32 v101, 0, v0
	v_fma_f32 v102, v48, v101, 0
	v_max_i32_e32 v101, 0, v1
	v_fmac_f32_e32 v102, v49, v101
	v_max_i32_e32 v101, 0, v2
	v_fmac_f32_e32 v102, v50, v101
	v_max_i32_e32 v101, 0, v3
	v_fmac_f32_e32 v102, v51, v101
	v_max_i32_e32 v101, 0, v4
	v_fmac_f32_e32 v102, v52, v101
	v_mfma_f32_32x32x16_bf16 v[16:31], v[36:39], v[92:95], v[16:31]
	v_max_i32_e32 v101, 0, v5
	v_fmac_f32_e32 v102, v53, v101
	v_max_i32_e32 v101, 0, v6
	v_fmac_f32_e32 v102, v54, v101
	v_max_i32_e32 v101, 0, v7
	v_fmac_f32_e32 v102, v55, v101
	v_max_i32_e32 v101, 0, v8
	v_fmac_f32_e32 v102, v56, v101
	v_max_i32_e32 v101, 0, v9
	v_fmac_f32_e32 v102, v57, v101
	v_mfma_f32_32x32x16_bf16 v[16:31], v[40:43], v[84:87], v[16:31]
	v_max_i32_e32 v101, 0, v10
	v_fmac_f32_e32 v102, v58, v101
	v_max_i32_e32 v101, 0, v11
	v_fmac_f32_e32 v102, v59, v101
	v_max_i32_e32 v101, 0, v12
	v_fmac_f32_e32 v102, v60, v101
	v_max_i32_e32 v101, 0, v13
	v_fmac_f32_e32 v102, v61, v101
	v_mfma_f32_32x32x16_bf16 v[16:31], v[44:47], v[108:111], v[16:31]
	v_max_i32_e32 v101, 0, v14
	s_cmp_eq_u32 s60, 62
	v_fmac_f32_e32 v102, v62, v101
	v_max_i32_e32 v101, 0, v15
	s_cselect_b64 s[0:1], -1, 0
	v_cmp_gt_i32_e32 vcc, v188, v203
	v_fmac_f32_e32 v102, v63, v101
	s_and_b64 vcc, s[0:1], vcc
	v_cndmask_b32_e32 v84, v102, v197, vcc
	s_branch .LBB0_2083

.LBB0_2085:
	s_waitcnt lgkmcnt(0)
	s_cmpk_lt_u32 s94, 0x7e
	s_cbranch_scc1 .LBB0_2087
	v_mfma_f32_32x32x16_bf16 v[0:15], v[32:35], v[96:99], 0
	v_cndmask_b32_e64 v97, 0, 1, s[62:63]
	v_cmp_ne_u32_e64 s[54:55], 1, v97
	s_andn2_b64 vcc, exec, s[62:63]
	v_max_i32_e32 v97, 0, v16
	v_fma_f32 v98, v48, v97, 0
	v_max_i32_e32 v97, 0, v17
	v_fmac_f32_e32 v98, v49, v97
	v_max_i32_e32 v97, 0, v18
	v_fmac_f32_e32 v98, v50, v97
	v_max_i32_e32 v97, 0, v19
	v_fmac_f32_e32 v98, v51, v97
	v_max_i32_e32 v97, 0, v20
	v_fmac_f32_e32 v98, v52, v97
	v_mfma_f32_32x32x16_bf16 v[0:15], v[36:39], v[88:91], v[0:15]
	v_max_i32_e32 v97, 0, v21
	v_fmac_f32_e32 v98, v53, v97
	v_max_i32_e32 v97, 0, v22
	v_fmac_f32_e32 v98, v54, v97
	v_max_i32_e32 v97, 0, v23
	v_fmac_f32_e32 v98, v55, v97
	v_max_i32_e32 v97, 0, v24
	v_fmac_f32_e32 v98, v56, v97
	v_max_i32_e32 v97, 0, v25
	v_fmac_f32_e32 v98, v57, v97
	v_mfma_f32_32x32x16_bf16 v[0:15], v[40:43], v[80:83], v[0:15]
	v_max_i32_e32 v97, 0, v26
	v_fmac_f32_e32 v98, v58, v97
	v_max_i32_e32 v97, 0, v27
	v_fmac_f32_e32 v98, v59, v97
	v_max_i32_e32 v97, 0, v28
	v_fmac_f32_e32 v98, v60, v97
	v_max_i32_e32 v97, 0, v29
	v_fmac_f32_e32 v98, v61, v97
	v_mfma_f32_32x32x16_bf16 v[0:15], v[44:47], v[104:107], v[0:15]
	v_max_i32_e32 v97, 0, v30
	s_cmp_eq_u32 s60, 63
	v_fmac_f32_e32 v98, v62, v97
	v_max_i32_e32 v97, 0, v31
	s_cselect_b64 s[0:1], -1, 0
	v_cmp_gt_i32_e32 vcc, v189, v203
	v_fmac_f32_e32 v98, v63, v97
	s_and_b64 vcc, s[0:1], vcc
	v_cndmask_b32_e32 v80, v98, v197, vcc
	s_branch .LBB0_2089
